# all six GEMM K-loops: first iteration peeled with C = 0 on the first MFMA of every accumulator; the 128 accumulator-zeroing moves per tile are gone
# speedup vs baseline: 1.0053x; 1.0053x over previous
; #define PG8_STAGE(bufoff, gbase, voff) do { _Pragma("unroll") for (int _i = 0; _i < 2; ++_i) \
;         __builtin_amdgcn_global_load_lds((const unsigned*)((const char*)(gbase) + (voff)[_i]), (PG8_LAS unsigned*)(lds + (bufoff) + ldsw + _i * 8192), 16, 0, 0); } while (0)
; #define PG8_LDA(dst, b, h) do { _Pragma("unroll") for (int m = 0; m < 4; ++m) _Pragma("unroll") for (int k = 0; k < 2; ++k) dst[m][k] = *(const PG8_LAS bf16x8*)(lds + PG8_SA(b, h) + aoff + m * 2048 + k * 1024); } while (0)
; #define PG8_LDB(dst, b, h) do { _Pragma("unroll") for (int n = 0; n < 2; ++n) _Pragma("unroll") for (int k = 0; k < 2; ++k) dst[n][k] = *(const PG8_LAS bf16x8*)(lds + PG8_SB(b, h) + boff + n * 2048 + k * 1024); } while (0)
; #define PG8_MMA(ai, bj, At, Bt) do { __builtin_amdgcn_s_setprio(1); _Pragma("unroll") for (int m = 0; m < 4; ++m) _Pragma("unroll") for (int n = 0; n < 2; ++n) _Pragma("unroll") for (int k = 0; k < 2; ++k) \
;         acc[ai][bj][m][n] = __builtin_amdgcn_mfma_f32_16x16x32_bf16(Bt[n][k], At[m][k], acc[ai][bj][m][n], 0, 0, 0); __builtin_amdgcn_s_setprio(0); } while (0)
; #define PG8_WAIT_V(n) asm volatile("s_waitcnt vmcnt(" #n ")" ::: "memory")
; #define PG8_BAR __builtin_amdgcn_s_barrier()
; template <class Epi, class Sched, bool ALIGN_EPI = false, bool SP2 = false>
; __device__ __forceinline__ void gemm_phase(PG8_LAS unsigned char* lds, const Gemm g, const Sched& S, const Epi& E) {
;     ...
;         for (int t = 0; t < nt; t += 2) {
;             const bool last = (t == nt - 2);
;             const char* a1 = cA + (size_t)(t + 1) * kstep;
;             const char* a2 = last ? nA : cA + (size_t)(t + 2) * kstep; const char* b2 = last ? nB : cB + (size_t)(t + 2) * kstep;
;             const char* a3 = a2 + kstep; const char* b3 = b2 + kstep;
;             if (last && has_next) S.a_ready(nxt);
;             if constexpr (SP2) {
;             PG8_LDB(B0, 0, 0); PG8_LDB(B1, 0, 1); PG8_SCHED; PG8_LDA(At, 0, 0); PG8_STAGE(PG8_SA(1, 1), a1 + hstep, voffA);
;             PG8_WAIT_V(8); PG8_WAIT_L(0); PG8_BAR; PG8_MMA(0, 0, At, B0); PG8_MMA(0, 1, At, B1); PG8_BAR; PG8_SCHED;
;             PG8_LDA(At, 0, 1); PG8_STAGE(PG8_SB(0, 0), b2, voffB); PG8_STAGE(PG8_SB(0, 1), b2 + hstep, voffB); PG8_STAGE(PG8_SA(0, 0), a2, voffA);
;             PG8_WAIT_V(8); PG8_WAIT_L(0); PG8_BAR; PG8_MMA(1, 0, At, B0); PG8_MMA(1, 1, At, B1); PG8_BAR; PG8_SCHED;
.LBB0_35:
	s_ashr_i32 s45, s44, 31
	s_lshl_b64 s[46:47], s[44:45], 22
	s_add_u32 s94, s92, s46
	s_addc_u32 s95, s93, s47
	s_and_b64 s[46:47], s[42:43], exec
	s_cselect_b32 s45, s95, s19
	s_cselect_b32 s73, s94, s18
	s_ashr_i32 s37, s36, 31
	s_lshl_b64 s[46:47], s[36:37], 22
	v_readlane_b32 s58, v254, 47
	v_readlane_b32 s59, v254, 48
	s_add_u32 s96, s58, s46
	s_addc_u32 s97, s59, s47
	s_and_b64 s[46:47], s[42:43], exec
	s_cselect_b32 s37, s97, s63
	s_cselect_b32 s84, s96, s62
	s_add_u32 s58, s18, 0x200080
	s_addc_u32 s59, s19, 0
	s_add_u32 s78, s62, 0x100
	s_addc_u32 s79, s63, 0
	s_mov_b32 s46, -2
	s_waitcnt lgkmcnt(0)
	s_waitcnt vmcnt(0)
	s_add_u32 s18, s58, 0xffe00080
	s_addc_u32 s19, s59, -1
	s_add_i32 s47, 0, 0x10000
	s_cmpk_eq_i32 s46, 0x7c
	s_cselect_b32 s63, s45, s19
	s_cselect_b32 s62, s73, s18
	v_add_u32_e32 v160, s47, v143
	s_cselect_b32 s19, s37, s79
	s_cselect_b32 s18, s84, s78
	s_add_i32 s80, 0, 0x14000
	ds_read_b128 v[156:159], v160
	ds_read_b128 v[164:167], v160 offset:1024
	ds_read_b128 v[168:171], v160 offset:2048
	ds_read_b128 v[172:175], v160 offset:3072
	v_add_u32_e32 v160, s80, v143
	ds_read_b128 v[176:179], v160
	ds_read_b128 v[180:183], v160 offset:1024
	ds_read_b128 v[184:187], v160 offset:2048
	ds_read_b128 v[204:207], v160 offset:3072
	v_lshl_add_u64 v[160:161], s[58:59], 0, v[152:153]
	s_add_i32 m0, s5, 0xc000
	ds_read_b128 v[208:211], v163
	ds_read_b128 v[212:215], v163 offset:1024
	ds_read_b128 v[216:219], v163 offset:2048
	ds_read_b128 v[220:223], v163 offset:3072
	ds_read_b128 v[224:227], v163 offset:4096
	ds_read_b128 v[228:231], v163 offset:5120
	ds_read_b128 v[232:235], v163 offset:6144
	ds_read_b128 v[236:239], v163 offset:7168
	global_load_lds_dwordx4 v[160:161], off
	v_lshl_add_u64 v[160:161], s[58:59], 0, v[154:155]
	s_add_i32 m0, s5, 0xe000
	s_nop 0
	global_load_lds_dwordx4 v[160:161], off
	s_nop 0
	s_waitcnt vmcnt(8)
	s_waitcnt lgkmcnt(0)
	s_setprio 1
	s_barrier
	v_mfma_f32_16x16x32_bf16 v[126:129], v[156:159], v[208:211], 0
	v_mfma_f32_16x16x32_bf16 v[122:125], v[168:171], v[208:211], 0
	v_mfma_f32_16x16x32_bf16 v[110:113], v[156:159], v[216:219], 0
	v_mfma_f32_16x16x32_bf16 v[106:109], v[168:171], v[216:219], 0
	v_mfma_f32_16x16x32_bf16 v[94:97], v[156:159], v[224:227], 0
	v_mfma_f32_16x16x32_bf16 v[90:93], v[168:171], v[224:227], 0
	v_mfma_f32_16x16x32_bf16 v[78:81], v[156:159], v[232:235], 0
	v_mfma_f32_16x16x32_bf16 v[74:77], v[168:171], v[232:235], 0
	s_setprio 0
	s_setprio 1
	v_mfma_f32_16x16x32_bf16 v[126:129], v[164:167], v[212:215], v[126:129]
	v_mfma_f32_16x16x32_bf16 v[122:125], v[172:175], v[212:215], v[122:125]
	v_mfma_f32_16x16x32_bf16 v[110:113], v[164:167], v[220:223], v[110:113]
	v_mfma_f32_16x16x32_bf16 v[106:109], v[172:175], v[220:223], v[106:109]
	v_mfma_f32_16x16x32_bf16 v[94:97], v[164:167], v[228:231], v[94:97]
	v_mfma_f32_16x16x32_bf16 v[90:93], v[172:175], v[228:231], v[90:93]
	v_mfma_f32_16x16x32_bf16 v[78:81], v[164:167], v[236:239], v[78:81]
	v_mfma_f32_16x16x32_bf16 v[74:77], v[172:175], v[236:239], v[74:77]
	s_setprio 0
	s_setprio 1
	v_mfma_f32_16x16x32_bf16 v[118:121], v[176:179], v[208:211], 0
	v_mfma_f32_16x16x32_bf16 v[114:117], v[184:187], v[208:211], 0
	v_mfma_f32_16x16x32_bf16 v[102:105], v[176:179], v[216:219], 0
	v_mfma_f32_16x16x32_bf16 v[98:101], v[184:187], v[216:219], 0
	v_mfma_f32_16x16x32_bf16 v[86:89], v[176:179], v[224:227], 0
	v_mfma_f32_16x16x32_bf16 v[82:85], v[184:187], v[224:227], 0
	v_mfma_f32_16x16x32_bf16 v[70:73], v[176:179], v[232:235], 0
	v_mfma_f32_16x16x32_bf16 v[66:69], v[184:187], v[232:235], 0
	s_setprio 0
	s_setprio 1
	v_mfma_f32_16x16x32_bf16 v[118:121], v[180:183], v[212:215], v[118:121]
	v_mfma_f32_16x16x32_bf16 v[114:117], v[204:207], v[212:215], v[114:117]
	v_mfma_f32_16x16x32_bf16 v[102:105], v[180:183], v[220:223], v[102:105]
	v_mfma_f32_16x16x32_bf16 v[98:101], v[204:207], v[220:223], v[98:101]
	v_mfma_f32_16x16x32_bf16 v[86:89], v[180:183], v[228:231], v[86:89]
	v_mfma_f32_16x16x32_bf16 v[82:85], v[204:207], v[228:231], v[82:85]
	v_mfma_f32_16x16x32_bf16 v[70:73], v[180:183], v[236:239], v[70:73]
	v_mfma_f32_16x16x32_bf16 v[66:69], v[204:207], v[236:239], v[66:69]
	s_setprio 0
	s_barrier
	s_add_i32 s47, s47, s4
	v_lshl_add_u64 v[160:161], s[18:19], 0, v[148:149]
	s_mov_b32 m0, s47
	ds_read_b128 v[208:211], v163 offset:16384
	ds_read_b128 v[212:215], v163 offset:17408
	ds_read_b128 v[216:219], v163 offset:18432
	ds_read_b128 v[220:223], v163 offset:19456
	ds_read_b128 v[224:227], v163 offset:20480
	ds_read_b128 v[228:231], v163 offset:21504
	ds_read_b128 v[232:235], v163 offset:22528
	ds_read_b128 v[236:239], v163 offset:23552
	global_load_lds_dwordx4 v[160:161], off
	s_add_i32 m0, s47, 0x2000
	s_add_u32 s76, s18, 0x200000
	v_lshl_add_u64 v[240:241], s[18:19], 0, v[144:145]
	s_addc_u32 s77, s19, 0
	s_add_i32 s47, s80, s4
	global_load_lds_dwordx4 v[240:241], off
	v_lshl_add_u64 v[242:243], s[76:77], 0, v[148:149]
	s_mov_b32 m0, s47
	v_lshl_add_u64 v[244:245], s[62:63], 0, v[146:147]
	global_load_lds_dwordx4 v[242:243], off
	v_lshl_add_u64 v[242:243], s[76:77], 0, v[144:145]
	s_add_i32 m0, s47, 0x2000
	s_nop 0
	global_load_lds_dwordx4 v[242:243], off
	v_lshl_add_u64 v[242:243], s[62:63], 0, v[150:151]
	s_mov_b32 m0, s5
	s_nop 0
	global_load_lds_dwordx4 v[242:243], off
	s_mov_b32 m0, s30
	s_nop 0
	global_load_lds_dwordx4 v[244:245], off
	s_waitcnt vmcnt(8)
	s_waitcnt lgkmcnt(0)
	s_setprio 1
	s_barrier
; #define PG8_STAGE(bufoff, gbase, voff) do { _Pragma("unroll") for (int _i = 0; _i < 2; ++_i) \
;         __builtin_amdgcn_global_load_lds((const unsigned*)((const char*)(gbase) + (voff)[_i]), (PG8_LAS unsigned*)(lds + (bufoff) + ldsw + _i * 8192), 16, 0, 0); } while (0)
; #define PG8_LDA(dst, b, h) do { _Pragma("unroll") for (int m = 0; m < 4; ++m) _Pragma("unroll") for (int k = 0; k < 2; ++k) dst[m][k] = *(const PG8_LAS bf16x8*)(lds + PG8_SA(b, h) + aoff + m * 2048 + k * 1024); } while (0)
; #define PG8_LDB(dst, b, h) do { _Pragma("unroll") for (int n = 0; n < 2; ++n) _Pragma("unroll") for (int k = 0; k < 2; ++k) dst[n][k] = *(const PG8_LAS bf16x8*)(lds + PG8_SB(b, h) + boff + n * 2048 + k * 1024); } while (0)
; #define PG8_MMA(ai, bj, At, Bt) do { __builtin_amdgcn_s_setprio(1); _Pragma("unroll") for (int m = 0; m < 4; ++m) _Pragma("unroll") for (int n = 0; n < 2; ++n) _Pragma("unroll") for (int k = 0; k < 2; ++k) \
;         acc[ai][bj][m][n] = __builtin_amdgcn_mfma_f32_16x16x32_bf16(Bt[n][k], At[m][k], acc[ai][bj][m][n], 0, 0, 0); __builtin_amdgcn_s_setprio(0); } while (0)
; #define PG8_WAIT_V(n) asm volatile("s_waitcnt vmcnt(" #n ")" ::: "memory")
; #define PG8_WAIT_L(n) asm volatile("s_waitcnt lgkmcnt(" #n ")" ::: "memory")
; #define PG8_BAR __builtin_amdgcn_s_barrier()
; #define PG8_SCHED __builtin_amdgcn_sched_barrier(0)
; template <class Epi, class Sched, bool ALIGN_EPI = false, bool SP2 = false>
; __device__ __forceinline__ void gemm_phase(PG8_LAS unsigned char* lds, const Gemm g, const Sched& S, const Epi& E) {
;     ...
;             PG8_WAIT_V(8); PG8_WAIT_L(0); PG8_BAR; PG8_MMA(1, 0, At, B0); PG8_MMA(1, 1, At, B1); PG8_BAR; PG8_SCHED;
;             PG8_LDB(B0, 1, 0); PG8_LDB(B1, 1, 1); PG8_SCHED; PG8_LDA(At, 1, 0); PG8_STAGE(PG8_SA(0, 1), a2 + hstep, voffA);
;             PG8_WAIT_V(8); PG8_WAIT_L(0); PG8_BAR; PG8_MMA(0, 0, At, B0); PG8_MMA(0, 1, At, B1); PG8_BAR; PG8_SCHED;
	v_mfma_f32_16x16x32_bf16 v[62:65], v[156:159], v[208:211], 0
	v_mfma_f32_16x16x32_bf16 v[58:61], v[168:171], v[208:211], 0
	v_mfma_f32_16x16x32_bf16 v[46:49], v[156:159], v[216:219], 0
	v_mfma_f32_16x16x32_bf16 v[42:45], v[168:171], v[216:219], 0
	v_mfma_f32_16x16x32_bf16 v[30:33], v[156:159], v[224:227], 0
	v_mfma_f32_16x16x32_bf16 v[26:29], v[168:171], v[224:227], 0
	v_mfma_f32_16x16x32_bf16 v[14:17], v[156:159], v[232:235], 0
	v_mfma_f32_16x16x32_bf16 v[10:13], v[168:171], v[232:235], 0
	v_mfma_f32_16x16x32_bf16 v[62:65], v[164:167], v[212:215], v[62:65]
	v_mfma_f32_16x16x32_bf16 v[58:61], v[172:175], v[212:215], v[58:61]
	v_mfma_f32_16x16x32_bf16 v[46:49], v[164:167], v[220:223], v[46:49]
	v_mfma_f32_16x16x32_bf16 v[42:45], v[172:175], v[220:223], v[42:45]
	v_mfma_f32_16x16x32_bf16 v[30:33], v[164:167], v[228:231], v[30:33]
	v_mfma_f32_16x16x32_bf16 v[26:29], v[172:175], v[228:231], v[26:29]
	v_mfma_f32_16x16x32_bf16 v[14:17], v[164:167], v[236:239], v[14:17]
	v_mfma_f32_16x16x32_bf16 v[10:13], v[172:175], v[236:239], v[10:13]
	v_mfma_f32_16x16x32_bf16 v[54:57], v[176:179], v[208:211], 0
	v_mfma_f32_16x16x32_bf16 v[50:53], v[184:187], v[208:211], 0
	v_mfma_f32_16x16x32_bf16 v[38:41], v[176:179], v[216:219], 0
	v_mfma_f32_16x16x32_bf16 v[34:37], v[184:187], v[216:219], 0
	v_mfma_f32_16x16x32_bf16 v[22:25], v[176:179], v[224:227], 0
	v_mfma_f32_16x16x32_bf16 v[18:21], v[184:187], v[224:227], 0
	v_mfma_f32_16x16x32_bf16 v[6:9], v[176:179], v[232:235], 0
	v_mfma_f32_16x16x32_bf16 v[2:5], v[184:187], v[232:235], 0
	v_mfma_f32_16x16x32_bf16 v[54:57], v[180:183], v[212:215], v[54:57]
	v_mfma_f32_16x16x32_bf16 v[50:53], v[204:207], v[212:215], v[50:53]
	v_mfma_f32_16x16x32_bf16 v[38:41], v[180:183], v[220:223], v[38:41]
	v_mfma_f32_16x16x32_bf16 v[34:37], v[204:207], v[220:223], v[34:37]
	v_mfma_f32_16x16x32_bf16 v[22:25], v[180:183], v[228:231], v[22:25]
	v_mfma_f32_16x16x32_bf16 v[18:21], v[204:207], v[228:231], v[18:21]
	v_mfma_f32_16x16x32_bf16 v[6:9], v[180:183], v[236:239], v[6:9]
	v_mfma_f32_16x16x32_bf16 v[2:5], v[204:207], v[236:239], v[2:5]
	s_setprio 0
	s_barrier
	s_add_i32 s47, 0, 0x18000
	s_add_i32 s76, 0, 0x1c000
	v_add_u32_e32 v172, s47, v143
	v_add_u32_e32 v203, s76, v143
	ds_read_b128 v[156:159], v172
	ds_read_b128 v[164:167], v172 offset:1024
	ds_read_b128 v[168:171], v172 offset:2048
	ds_read_b128 v[172:175], v172 offset:3072
	ds_read_b128 v[176:179], v203
	ds_read_b128 v[180:183], v203 offset:1024
	ds_read_b128 v[184:187], v203 offset:2048
	ds_read_b128 v[204:207], v203 offset:3072
	s_add_u32 s62, s62, 0x200000
	s_addc_u32 s63, s63, 0
	s_mov_b32 m0, s57
	v_lshl_add_u64 v[246:247], s[62:63], 0, v[150:151]
	ds_read_b128 v[208:211], v163 offset:32768
	ds_read_b128 v[212:215], v163 offset:33792
	ds_read_b128 v[216:219], v163 offset:34816
	ds_read_b128 v[220:223], v163 offset:35840
	ds_read_b128 v[224:227], v163 offset:36864
	ds_read_b128 v[228:231], v163 offset:37888
	ds_read_b128 v[232:235], v163 offset:38912
	ds_read_b128 v[236:239], v163 offset:39936
	global_load_lds_dwordx4 v[246:247], off
	v_lshl_add_u64 v[246:247], s[62:63], 0, v[146:147]
	s_mov_b32 m0, s67
	s_nop 0
	global_load_lds_dwordx4 v[246:247], off
	s_waitcnt vmcnt(8)
	s_waitcnt lgkmcnt(0)
	s_setprio 1
	s_barrier
	v_mfma_f32_16x16x32_bf16 v[126:129], v[156:159], v[208:211], v[126:129]
	v_mfma_f32_16x16x32_bf16 v[122:125], v[168:171], v[208:211], v[122:125]
	v_mfma_f32_16x16x32_bf16 v[110:113], v[156:159], v[216:219], v[110:113]
	v_mfma_f32_16x16x32_bf16 v[106:109], v[168:171], v[216:219], v[106:109]
	v_mfma_f32_16x16x32_bf16 v[94:97], v[156:159], v[224:227], v[94:97]
	v_mfma_f32_16x16x32_bf16 v[90:93], v[168:171], v[224:227], v[90:93]
	v_mfma_f32_16x16x32_bf16 v[78:81], v[156:159], v[232:235], v[78:81]
	v_mfma_f32_16x16x32_bf16 v[74:77], v[168:171], v[232:235], v[74:77]
	s_setprio 0
	s_setprio 1
	v_mfma_f32_16x16x32_bf16 v[126:129], v[164:167], v[212:215], v[126:129]
	v_mfma_f32_16x16x32_bf16 v[122:125], v[172:175], v[212:215], v[122:125]
	v_mfma_f32_16x16x32_bf16 v[110:113], v[164:167], v[220:223], v[110:113]
	v_mfma_f32_16x16x32_bf16 v[106:109], v[172:175], v[220:223], v[106:109]
	v_mfma_f32_16x16x32_bf16 v[94:97], v[164:167], v[228:231], v[94:97]
	v_mfma_f32_16x16x32_bf16 v[90:93], v[172:175], v[228:231], v[90:93]
	v_mfma_f32_16x16x32_bf16 v[78:81], v[164:167], v[236:239], v[78:81]
	v_mfma_f32_16x16x32_bf16 v[74:77], v[172:175], v[236:239], v[74:77]
	s_setprio 0
	s_setprio 1
	v_mfma_f32_16x16x32_bf16 v[118:121], v[176:179], v[208:211], v[118:121]
	v_mfma_f32_16x16x32_bf16 v[114:117], v[184:187], v[208:211], v[114:117]
	v_mfma_f32_16x16x32_bf16 v[102:105], v[176:179], v[216:219], v[102:105]
	v_mfma_f32_16x16x32_bf16 v[98:101], v[184:187], v[216:219], v[98:101]
	v_mfma_f32_16x16x32_bf16 v[86:89], v[176:179], v[224:227], v[86:89]
	v_mfma_f32_16x16x32_bf16 v[82:85], v[184:187], v[224:227], v[82:85]
	v_mfma_f32_16x16x32_bf16 v[70:73], v[176:179], v[232:235], v[70:73]
	v_mfma_f32_16x16x32_bf16 v[66:69], v[184:187], v[232:235], v[66:69]
	s_setprio 0
	s_setprio 1
	v_mfma_f32_16x16x32_bf16 v[118:121], v[180:183], v[212:215], v[118:121]
	v_mfma_f32_16x16x32_bf16 v[114:117], v[204:207], v[212:215], v[114:117]
	v_mfma_f32_16x16x32_bf16 v[102:105], v[180:183], v[220:223], v[102:105]
	v_mfma_f32_16x16x32_bf16 v[98:101], v[204:207], v[220:223], v[98:101]
	v_mfma_f32_16x16x32_bf16 v[86:89], v[180:183], v[228:231], v[86:89]
	v_mfma_f32_16x16x32_bf16 v[82:85], v[204:207], v[228:231], v[82:85]
	v_mfma_f32_16x16x32_bf16 v[70:73], v[180:183], v[236:239], v[70:73]
	v_mfma_f32_16x16x32_bf16 v[66:69], v[204:207], v[236:239], v[66:69]
	s_setprio 0
	s_barrier
; #define PG8_STAGE(bufoff, gbase, voff) do { _Pragma("unroll") for (int _i = 0; _i < 2; ++_i) \
;         __builtin_amdgcn_global_load_lds((const unsigned*)((const char*)(gbase) + (voff)[_i]), (PG8_LAS unsigned*)(lds + (bufoff) + ldsw + _i * 8192), 16, 0, 0); } while (0)
; #define PG8_LDA(dst, b, h) do { _Pragma("unroll") for (int m = 0; m < 4; ++m) _Pragma("unroll") for (int k = 0; k < 2; ++k) dst[m][k] = *(const PG8_LAS bf16x8*)(lds + PG8_SA(b, h) + aoff + m * 2048 + k * 1024); } while (0)
; #define PG8_MMA(ai, bj, At, Bt) do { __builtin_amdgcn_s_setprio(1); _Pragma("unroll") for (int m = 0; m < 4; ++m) _Pragma("unroll") for (int n = 0; n < 2; ++n) _Pragma("unroll") for (int k = 0; k < 2; ++k) \
;         acc[ai][bj][m][n] = __builtin_amdgcn_mfma_f32_16x16x32_bf16(Bt[n][k], At[m][k], acc[ai][bj][m][n], 0, 0, 0); __builtin_amdgcn_s_setprio(0); } while (0)
; #define PG8_WAIT_V(n) asm volatile("s_waitcnt vmcnt(" #n ")" ::: "memory")
; #define PG8_WAIT_L(n) asm volatile("s_waitcnt lgkmcnt(" #n ")" ::: "memory")
; #define PG8_BAR __builtin_amdgcn_s_barrier()
; #define PG8_SCHED __builtin_amdgcn_sched_barrier(0)
; template <class Epi, class Sched, bool ALIGN_EPI = false, bool SP2 = false>
; __device__ __forceinline__ void gemm_phase(PG8_LAS unsigned char* lds, const Gemm g, const Sched& S, const Epi& E) {
;     ...
;             PG8_LDA(At, 1, 1); PG8_STAGE(PG8_SB(1, 0), b3, voffB); PG8_STAGE(PG8_SB(1, 1), b3 + hstep, voffB); PG8_STAGE(PG8_SA(1, 0), a3, voffA);
;             PG8_WAIT_V(8); PG8_WAIT_L(0); PG8_BAR; PG8_MMA(1, 0, At, B0); PG8_MMA(1, 1, At, B1); PG8_BAR; PG8_SCHED;
	s_add_i32 s47, s47, s4
	v_lshl_add_u64 v[160:161], v[160:161], 0, s[68:69]
	s_mov_b32 m0, s47
	ds_read_b128 v[208:211], v163 offset:49152
	ds_read_b128 v[212:215], v163 offset:50176
	ds_read_b128 v[216:219], v163 offset:51200
	ds_read_b128 v[220:223], v163 offset:52224
	ds_read_b128 v[224:227], v163 offset:53248
	ds_read_b128 v[228:231], v163 offset:54272
	ds_read_b128 v[232:235], v163 offset:55296
	ds_read_b128 v[236:239], v163 offset:56320
	global_load_lds_dwordx4 v[160:161], off
	s_add_i32 m0, s47, 0x2000
	s_add_u32 s18, s18, 0x200080
	v_lshl_add_u64 v[160:161], v[240:241], 0, s[68:69]
	s_addc_u32 s19, s19, 0
	s_add_i32 s47, s76, s4
	global_load_lds_dwordx4 v[160:161], off
	v_lshl_add_u64 v[160:161], s[18:19], 0, v[148:149]
	s_mov_b32 m0, s47
	s_nop 0
	global_load_lds_dwordx4 v[160:161], off
	v_lshl_add_u64 v[160:161], s[18:19], 0, v[144:145]
	s_add_i32 m0, s47, 0x2000
	s_nop 0
	global_load_lds_dwordx4 v[160:161], off
	v_lshl_add_u64 v[160:161], v[242:243], 0, s[68:69]
	s_mov_b32 m0, s1
	s_nop 0
	global_load_lds_dwordx4 v[160:161], off
	v_lshl_add_u64 v[160:161], v[244:245], 0, s[68:69]
	s_mov_b32 m0, s60
	s_nop 0
	global_load_lds_dwordx4 v[160:161], off
	s_nop 0
	s_waitcnt vmcnt(8)
	s_waitcnt lgkmcnt(0)
	s_setprio 1
	s_barrier
	v_mfma_f32_16x16x32_bf16 v[62:65], v[156:159], v[208:211], v[62:65]
	v_mfma_f32_16x16x32_bf16 v[58:61], v[168:171], v[208:211], v[58:61]
	v_mfma_f32_16x16x32_bf16 v[46:49], v[156:159], v[216:219], v[46:49]
	v_mfma_f32_16x16x32_bf16 v[42:45], v[168:171], v[216:219], v[42:45]
	v_mfma_f32_16x16x32_bf16 v[30:33], v[156:159], v[224:227], v[30:33]
	v_mfma_f32_16x16x32_bf16 v[26:29], v[168:171], v[224:227], v[26:29]
	v_mfma_f32_16x16x32_bf16 v[14:17], v[156:159], v[232:235], v[14:17]
	v_mfma_f32_16x16x32_bf16 v[10:13], v[168:171], v[232:235], v[10:13]
	v_mfma_f32_16x16x32_bf16 v[62:65], v[164:167], v[212:215], v[62:65]
	v_mfma_f32_16x16x32_bf16 v[58:61], v[172:175], v[212:215], v[58:61]
	v_mfma_f32_16x16x32_bf16 v[46:49], v[164:167], v[220:223], v[46:49]
	v_mfma_f32_16x16x32_bf16 v[42:45], v[172:175], v[220:223], v[42:45]
	v_mfma_f32_16x16x32_bf16 v[30:33], v[164:167], v[228:231], v[30:33]
	v_mfma_f32_16x16x32_bf16 v[26:29], v[172:175], v[228:231], v[26:29]
	v_mfma_f32_16x16x32_bf16 v[14:17], v[164:167], v[236:239], v[14:17]
	v_mfma_f32_16x16x32_bf16 v[10:13], v[172:175], v[236:239], v[10:13]
	v_mfma_f32_16x16x32_bf16 v[54:57], v[176:179], v[208:211], v[54:57]
	v_mfma_f32_16x16x32_bf16 v[50:53], v[184:187], v[208:211], v[50:53]
	v_mfma_f32_16x16x32_bf16 v[38:41], v[176:179], v[216:219], v[38:41]
	v_mfma_f32_16x16x32_bf16 v[34:37], v[184:187], v[216:219], v[34:37]
	v_mfma_f32_16x16x32_bf16 v[22:25], v[176:179], v[224:227], v[22:25]
	v_mfma_f32_16x16x32_bf16 v[18:21], v[184:187], v[224:227], v[18:21]
	v_mfma_f32_16x16x32_bf16 v[6:9], v[176:179], v[232:235], v[6:9]
	v_mfma_f32_16x16x32_bf16 v[2:5], v[184:187], v[232:235], v[2:5]
	v_mfma_f32_16x16x32_bf16 v[54:57], v[180:183], v[212:215], v[54:57]
	v_mfma_f32_16x16x32_bf16 v[50:53], v[204:207], v[212:215], v[50:53]
	v_mfma_f32_16x16x32_bf16 v[38:41], v[180:183], v[220:223], v[38:41]
	v_mfma_f32_16x16x32_bf16 v[34:37], v[204:207], v[220:223], v[34:37]
	v_mfma_f32_16x16x32_bf16 v[22:25], v[180:183], v[228:231], v[22:25]
	v_mfma_f32_16x16x32_bf16 v[18:21], v[204:207], v[228:231], v[18:21]
	v_mfma_f32_16x16x32_bf16 v[6:9], v[180:183], v[236:239], v[6:9]
	v_mfma_f32_16x16x32_bf16 v[2:5], v[204:207], v[236:239], v[2:5]
	s_setprio 0
	s_barrier
	s_add_i32 s46, s46, 2
	s_add_u32 s58, s58, 0x100
	s_addc_u32 s59, s59, 0
	s_add_u32 s78, s78, 0x100
	s_addc_u32 s79, s79, 0
	s_cmpk_gt_u32 s46, 0x7d

; #define PG8_STAGE(bufoff, gbase, voff) do { _Pragma("unroll") for (int _i = 0; _i < 2; ++_i) \
;         __builtin_amdgcn_global_load_lds((const unsigned*)((const char*)(gbase) + (voff)[_i]), (PG8_LAS unsigned*)(lds + (bufoff) + ldsw + _i * 8192), 16, 0, 0); } while (0)
; #define PG8_LDA(dst, b, h) do { _Pragma("unroll") for (int m = 0; m < 4; ++m) _Pragma("unroll") for (int k = 0; k < 2; ++k) dst[m][k] = *(const PG8_LAS bf16x8*)(lds + PG8_SA(b, h) + aoff + m * 2048 + k * 1024); } while (0)
; #define PG8_LDB(dst, b, h) do { _Pragma("unroll") for (int n = 0; n < 2; ++n) _Pragma("unroll") for (int k = 0; k < 2; ++k) dst[n][k] = *(const PG8_LAS bf16x8*)(lds + PG8_SB(b, h) + boff + n * 2048 + k * 1024); } while (0)
; #define PG8_WAIT_V(n) asm volatile("s_waitcnt vmcnt(" #n ")" ::: "memory")
; #define PG8_WAIT_L(n) asm volatile("s_waitcnt lgkmcnt(" #n ")" ::: "memory")
; #define PG8_BAR __builtin_amdgcn_s_barrier()
; #define PG8_SCHED __builtin_amdgcn_sched_barrier(0)
; template <class Epi, class Sched, bool ALIGN_EPI = false, bool SP2 = false>
; __device__ __forceinline__ void gemm_phase(PG8_LAS unsigned char* lds, const Gemm g, const Sched& S, const Epi& E) {
;     ...
;         const bool has_next = S.next(ui + 1, nxt);
;         const char* nA = has_next ? (const char*)g.A + (size_t)nxt.pm * tstep : cA; const char* nB = has_next ? (const char*)g.Bt + (size_t)nxt.pn * tstep : cB;
;         for (int t = 0; t < nt; t += 2) {
;             const bool last = (t == nt - 2);
;             const char* a1 = cA + (size_t)(t + 1) * kstep;
;             const char* a2 = last ? nA : cA + (size_t)(t + 2) * kstep; const char* b2 = last ? nB : cB + (size_t)(t + 2) * kstep;
;             const char* a3 = a2 + kstep; const char* b3 = b2 + kstep;
;             if (last && has_next) S.a_ready(nxt);
;             if constexpr (SP2) {
;             PG8_LDB(B0, 0, 0); PG8_LDB(B1, 0, 1); PG8_SCHED; PG8_LDA(At, 0, 0); PG8_STAGE(PG8_SA(1, 1), a1 + hstep, voffA);
;             PG8_WAIT_V(8); PG8_WAIT_L(0); PG8_BAR; PG8_MMA(0, 0, At, B0); PG8_MMA(0, 1, At, B1); PG8_BAR; PG8_SCHED;
;             PG8_LDA(At, 0, 1); PG8_STAGE(PG8_SB(0, 0), b2, voffB); PG8_STAGE(PG8_SB(0, 1), b2 + hstep, voffB); PG8_STAGE(PG8_SA(0, 0), a2, voffA);
;             PG8_WAIT_V(8); PG8_WAIT_L(0); PG8_BAR; PG8_MMA(1, 0, At, B0); PG8_MMA(1, 1, At, B1); PG8_BAR; PG8_SCHED;
.LBB0_75:
	s_ashr_i32 s97, s96, 31
	s_lshl_b64 s[18:19], s[96:97], 20
	s_add_u32 s94, s70, s18
	s_addc_u32 s95, s71, s19
	s_and_b64 s[18:19], s[40:41], exec
	s_cselect_b32 s60, s95, s1
	s_cselect_b32 s73, s94, s0
	s_ashr_i32 s45, s44, 31
	s_lshl_b64 s[18:19], s[44:45], 20
	s_add_u32 s36, s82, s18
	s_addc_u32 s37, s83, s19
	s_and_b64 s[18:19], s[40:41], exec
	s_cselect_b32 s45, s37, s59
	s_cselect_b32 s84, s36, s58
	s_add_u32 s0, s0, 0x80080
	s_addc_u32 s1, s1, 0
	s_add_u32 s78, s58, 0x100
	s_addc_u32 s79, s59, 0
	s_mov_b32 s46, -2
	s_waitcnt vmcnt(0)
	s_add_u32 s18, s0, 0xfff80080
	s_addc_u32 s19, s1, -1
	s_add_i32 s47, 0, 0x10000
	s_cmp_eq_u32 s46, 28
	s_cselect_b32 s59, s60, s19
	s_cselect_b32 s58, s73, s18
	v_add_u32_e32 v158, s47, v143
	s_cselect_b32 s19, s45, s79
	s_cselect_b32 s18, s84, s78
	s_add_i32 s80, 0, 0x14000
	ds_read_b128 v[162:165], v158
	ds_read_b128 v[166:169], v158 offset:1024
	ds_read_b128 v[170:173], v158 offset:2048
	ds_read_b128 v[174:177], v158 offset:3072
	v_add_u32_e32 v158, s80, v143
	ds_read_b128 v[178:181], v158
	ds_read_b128 v[182:185], v158 offset:1024
	ds_read_b128 v[204:207], v158 offset:2048
	ds_read_b128 v[208:211], v158 offset:3072
	v_lshl_add_u64 v[158:159], s[0:1], 0, v[154:155]
	s_add_i32 m0, s62, 0xc000
	ds_read_b128 v[212:215], v161
	ds_read_b128 v[216:219], v161 offset:1024
	ds_read_b128 v[220:223], v161 offset:2048
	ds_read_b128 v[224:227], v161 offset:3072
	ds_read_b128 v[228:231], v161 offset:4096
	ds_read_b128 v[232:235], v161 offset:5120
	ds_read_b128 v[236:239], v161 offset:6144
	ds_read_b128 v[240:243], v161 offset:7168
	global_load_lds_dwordx4 v[158:159], off
	v_lshl_add_u64 v[158:159], s[0:1], 0, v[156:157]
	s_add_i32 m0, s62, 0xe000
	s_nop 0
	global_load_lds_dwordx4 v[158:159], off
	s_nop 0
	s_waitcnt vmcnt(8)
	s_waitcnt lgkmcnt(0)
	s_setprio 1
	s_barrier
	v_mfma_f32_16x16x32_bf16 v[126:129], v[162:165], v[212:215], 0
	v_mfma_f32_16x16x32_bf16 v[122:125], v[170:173], v[212:215], 0
	v_mfma_f32_16x16x32_bf16 v[110:113], v[162:165], v[220:223], 0
	v_mfma_f32_16x16x32_bf16 v[106:109], v[170:173], v[220:223], 0
	v_mfma_f32_16x16x32_bf16 v[94:97], v[162:165], v[228:231], 0
	v_mfma_f32_16x16x32_bf16 v[90:93], v[170:173], v[228:231], 0
	v_mfma_f32_16x16x32_bf16 v[78:81], v[162:165], v[236:239], 0
	v_mfma_f32_16x16x32_bf16 v[74:77], v[170:173], v[236:239], 0
	s_setprio 0
	s_setprio 1
	v_mfma_f32_16x16x32_bf16 v[126:129], v[166:169], v[216:219], v[126:129]
	v_mfma_f32_16x16x32_bf16 v[122:125], v[174:177], v[216:219], v[122:125]
	v_mfma_f32_16x16x32_bf16 v[110:113], v[166:169], v[224:227], v[110:113]
	v_mfma_f32_16x16x32_bf16 v[106:109], v[174:177], v[224:227], v[106:109]
	v_mfma_f32_16x16x32_bf16 v[94:97], v[166:169], v[232:235], v[94:97]
	v_mfma_f32_16x16x32_bf16 v[90:93], v[174:177], v[232:235], v[90:93]
	v_mfma_f32_16x16x32_bf16 v[78:81], v[166:169], v[240:243], v[78:81]
	v_mfma_f32_16x16x32_bf16 v[74:77], v[174:177], v[240:243], v[74:77]
	s_setprio 0
	s_setprio 1
	v_mfma_f32_16x16x32_bf16 v[118:121], v[178:181], v[212:215], 0
	v_mfma_f32_16x16x32_bf16 v[114:117], v[204:207], v[212:215], 0
	v_mfma_f32_16x16x32_bf16 v[102:105], v[178:181], v[220:223], 0
	v_mfma_f32_16x16x32_bf16 v[98:101], v[204:207], v[220:223], 0
	v_mfma_f32_16x16x32_bf16 v[86:89], v[178:181], v[228:231], 0
	v_mfma_f32_16x16x32_bf16 v[82:85], v[204:207], v[228:231], 0
	v_mfma_f32_16x16x32_bf16 v[70:73], v[178:181], v[236:239], 0
	v_mfma_f32_16x16x32_bf16 v[66:69], v[204:207], v[236:239], 0
	s_setprio 0
	s_setprio 1
	v_mfma_f32_16x16x32_bf16 v[118:121], v[182:185], v[216:219], v[118:121]
	v_mfma_f32_16x16x32_bf16 v[114:117], v[208:211], v[216:219], v[114:117]
	v_mfma_f32_16x16x32_bf16 v[102:105], v[182:185], v[224:227], v[102:105]
	v_mfma_f32_16x16x32_bf16 v[98:101], v[208:211], v[224:227], v[98:101]
	v_mfma_f32_16x16x32_bf16 v[86:89], v[182:185], v[232:235], v[86:89]
	v_mfma_f32_16x16x32_bf16 v[82:85], v[208:211], v[232:235], v[82:85]
	v_mfma_f32_16x16x32_bf16 v[70:73], v[182:185], v[240:243], v[70:73]
	v_mfma_f32_16x16x32_bf16 v[66:69], v[208:211], v[240:243], v[66:69]
	s_setprio 0
	s_barrier
	s_add_i32 s47, s47, s54
	v_lshl_add_u64 v[158:159], s[18:19], 0, v[148:149]
	s_mov_b32 m0, s47
	ds_read_b128 v[212:215], v161 offset:16384
	ds_read_b128 v[216:219], v161 offset:17408
	ds_read_b128 v[220:223], v161 offset:18432
	ds_read_b128 v[224:227], v161 offset:19456
	ds_read_b128 v[228:231], v161 offset:20480
	ds_read_b128 v[232:235], v161 offset:21504
	ds_read_b128 v[236:239], v161 offset:22528
	ds_read_b128 v[240:243], v161 offset:23552
	global_load_lds_dwordx4 v[158:159], off
	s_add_i32 m0, s47, 0x2000
	s_add_u32 s76, s18, 0x80000
	v_lshl_add_u64 v[186:187], s[18:19], 0, v[144:145]
	s_addc_u32 s77, s19, 0
	s_add_i32 s47, s80, s54
	global_load_lds_dwordx4 v[186:187], off
	v_lshl_add_u64 v[244:245], s[76:77], 0, v[148:149]
	s_mov_b32 m0, s47
	v_lshl_add_u64 v[246:247], s[58:59], 0, v[146:147]
	global_load_lds_dwordx4 v[244:245], off
	v_lshl_add_u64 v[244:245], s[76:77], 0, v[144:145]
	s_add_i32 m0, s47, 0x2000
	s_nop 0
	global_load_lds_dwordx4 v[244:245], off
	v_lshl_add_u64 v[244:245], s[58:59], 0, v[150:151]
	s_mov_b32 m0, s62
	s_nop 0
	global_load_lds_dwordx4 v[244:245], off
	s_mov_b32 m0, s63
	s_nop 0
	global_load_lds_dwordx4 v[246:247], off
	s_waitcnt vmcnt(8)
	s_waitcnt lgkmcnt(0)
	s_setprio 1
	s_barrier
; #define PG8_STAGE(bufoff, gbase, voff) do { _Pragma("unroll") for (int _i = 0; _i < 2; ++_i) \
;         __builtin_amdgcn_global_load_lds((const unsigned*)((const char*)(gbase) + (voff)[_i]), (PG8_LAS unsigned*)(lds + (bufoff) + ldsw + _i * 8192), 16, 0, 0); } while (0)
; #define PG8_LDA(dst, b, h) do { _Pragma("unroll") for (int m = 0; m < 4; ++m) _Pragma("unroll") for (int k = 0; k < 2; ++k) dst[m][k] = *(const PG8_LAS bf16x8*)(lds + PG8_SA(b, h) + aoff + m * 2048 + k * 1024); } while (0)
; #define PG8_LDB(dst, b, h) do { _Pragma("unroll") for (int n = 0; n < 2; ++n) _Pragma("unroll") for (int k = 0; k < 2; ++k) dst[n][k] = *(const PG8_LAS bf16x8*)(lds + PG8_SB(b, h) + boff + n * 2048 + k * 1024); } while (0)
; #define PG8_MMA(ai, bj, At, Bt) do { __builtin_amdgcn_s_setprio(1); _Pragma("unroll") for (int m = 0; m < 4; ++m) _Pragma("unroll") for (int n = 0; n < 2; ++n) _Pragma("unroll") for (int k = 0; k < 2; ++k) \
;         acc[ai][bj][m][n] = __builtin_amdgcn_mfma_f32_16x16x32_bf16(Bt[n][k], At[m][k], acc[ai][bj][m][n], 0, 0, 0); __builtin_amdgcn_s_setprio(0); } while (0)
; #define PG8_WAIT_V(n) asm volatile("s_waitcnt vmcnt(" #n ")" ::: "memory")
; #define PG8_WAIT_L(n) asm volatile("s_waitcnt lgkmcnt(" #n ")" ::: "memory")
; #define PG8_BAR __builtin_amdgcn_s_barrier()
; #define PG8_SCHED __builtin_amdgcn_sched_barrier(0)
; template <class Epi, class Sched, bool ALIGN_EPI = false, bool SP2 = false>
; __device__ __forceinline__ void gemm_phase(PG8_LAS unsigned char* lds, const Gemm g, const Sched& S, const Epi& E) {
;     ...
;             PG8_WAIT_V(8); PG8_WAIT_L(0); PG8_BAR; PG8_MMA(1, 0, At, B0); PG8_MMA(1, 1, At, B1); PG8_BAR; PG8_SCHED;
;             PG8_LDB(B0, 1, 0); PG8_LDB(B1, 1, 1); PG8_SCHED; PG8_LDA(At, 1, 0); PG8_STAGE(PG8_SA(0, 1), a2 + hstep, voffA);
;             PG8_WAIT_V(8); PG8_WAIT_L(0); PG8_BAR; PG8_MMA(0, 0, At, B0); PG8_MMA(0, 1, At, B1); PG8_BAR; PG8_SCHED;
;             PG8_LDA(At, 1, 1); PG8_STAGE(PG8_SB(1, 0), b3, voffB); PG8_STAGE(PG8_SB(1, 1), b3 + hstep, voffB); PG8_STAGE(PG8_SA(1, 0), a3, voffA);
	v_mfma_f32_16x16x32_bf16 v[62:65], v[162:165], v[212:215], 0
	v_mfma_f32_16x16x32_bf16 v[58:61], v[170:173], v[212:215], 0
	v_mfma_f32_16x16x32_bf16 v[46:49], v[162:165], v[220:223], 0
	v_mfma_f32_16x16x32_bf16 v[42:45], v[170:173], v[220:223], 0
	v_mfma_f32_16x16x32_bf16 v[30:33], v[162:165], v[228:231], 0
	v_mfma_f32_16x16x32_bf16 v[26:29], v[170:173], v[228:231], 0
	v_mfma_f32_16x16x32_bf16 v[14:17], v[162:165], v[236:239], 0
	v_mfma_f32_16x16x32_bf16 v[10:13], v[170:173], v[236:239], 0
	v_mfma_f32_16x16x32_bf16 v[62:65], v[166:169], v[216:219], v[62:65]
	v_mfma_f32_16x16x32_bf16 v[58:61], v[174:177], v[216:219], v[58:61]
	v_mfma_f32_16x16x32_bf16 v[46:49], v[166:169], v[224:227], v[46:49]
	v_mfma_f32_16x16x32_bf16 v[42:45], v[174:177], v[224:227], v[42:45]
	v_mfma_f32_16x16x32_bf16 v[30:33], v[166:169], v[232:235], v[30:33]
	v_mfma_f32_16x16x32_bf16 v[26:29], v[174:177], v[232:235], v[26:29]
	v_mfma_f32_16x16x32_bf16 v[14:17], v[166:169], v[240:243], v[14:17]
	v_mfma_f32_16x16x32_bf16 v[10:13], v[174:177], v[240:243], v[10:13]
	v_mfma_f32_16x16x32_bf16 v[54:57], v[178:181], v[212:215], 0
	v_mfma_f32_16x16x32_bf16 v[50:53], v[204:207], v[212:215], 0
	v_mfma_f32_16x16x32_bf16 v[38:41], v[178:181], v[220:223], 0
	v_mfma_f32_16x16x32_bf16 v[34:37], v[204:207], v[220:223], 0
	v_mfma_f32_16x16x32_bf16 v[22:25], v[178:181], v[228:231], 0
	v_mfma_f32_16x16x32_bf16 v[18:21], v[204:207], v[228:231], 0
	v_mfma_f32_16x16x32_bf16 v[6:9], v[178:181], v[236:239], 0
	v_mfma_f32_16x16x32_bf16 v[2:5], v[204:207], v[236:239], 0
	v_mfma_f32_16x16x32_bf16 v[54:57], v[182:185], v[216:219], v[54:57]
	v_mfma_f32_16x16x32_bf16 v[50:53], v[208:211], v[216:219], v[50:53]
	v_mfma_f32_16x16x32_bf16 v[38:41], v[182:185], v[224:227], v[38:41]
	v_mfma_f32_16x16x32_bf16 v[34:37], v[208:211], v[224:227], v[34:37]
	v_mfma_f32_16x16x32_bf16 v[22:25], v[182:185], v[232:235], v[22:25]
	v_mfma_f32_16x16x32_bf16 v[18:21], v[208:211], v[232:235], v[18:21]
	v_mfma_f32_16x16x32_bf16 v[6:9], v[182:185], v[240:243], v[6:9]
	v_mfma_f32_16x16x32_bf16 v[2:5], v[208:211], v[240:243], v[2:5]
	s_setprio 0
	s_barrier
	s_add_i32 s47, 0, 0x18000
	s_add_i32 s76, 0, 0x1c000
	v_add_u32_e32 v174, s47, v143
	v_add_u32_e32 v203, s76, v143
	ds_read_b128 v[162:165], v174
	ds_read_b128 v[166:169], v174 offset:1024
	ds_read_b128 v[170:173], v174 offset:2048
	ds_read_b128 v[174:177], v174 offset:3072
	ds_read_b128 v[178:181], v203
	ds_read_b128 v[182:185], v203 offset:1024
	ds_read_b128 v[204:207], v203 offset:2048
	ds_read_b128 v[208:211], v203 offset:3072
	s_add_u32 s58, s58, 0x80000
	s_addc_u32 s59, s59, 0
	s_mov_b32 m0, s67
	v_lshl_add_u64 v[248:249], s[58:59], 0, v[150:151]
	ds_read_b128 v[212:215], v161 offset:32768
	ds_read_b128 v[216:219], v161 offset:33792
	ds_read_b128 v[220:223], v161 offset:34816
	ds_read_b128 v[224:227], v161 offset:35840
	ds_read_b128 v[228:231], v161 offset:36864
	ds_read_b128 v[232:235], v161 offset:37888
	ds_read_b128 v[236:239], v161 offset:38912
	ds_read_b128 v[240:243], v161 offset:39936
	global_load_lds_dwordx4 v[248:249], off
	v_lshl_add_u64 v[248:249], s[58:59], 0, v[146:147]
	s_mov_b32 m0, s4
	s_nop 0
	global_load_lds_dwordx4 v[248:249], off
	s_waitcnt vmcnt(8)
	s_waitcnt lgkmcnt(0)
	s_setprio 1
	s_barrier
	v_mfma_f32_16x16x32_bf16 v[126:129], v[162:165], v[212:215], v[126:129]
	v_mfma_f32_16x16x32_bf16 v[122:125], v[170:173], v[212:215], v[122:125]
	v_mfma_f32_16x16x32_bf16 v[110:113], v[162:165], v[220:223], v[110:113]
	v_mfma_f32_16x16x32_bf16 v[106:109], v[170:173], v[220:223], v[106:109]
	v_mfma_f32_16x16x32_bf16 v[94:97], v[162:165], v[228:231], v[94:97]
	v_mfma_f32_16x16x32_bf16 v[90:93], v[170:173], v[228:231], v[90:93]
	v_mfma_f32_16x16x32_bf16 v[78:81], v[162:165], v[236:239], v[78:81]
	v_mfma_f32_16x16x32_bf16 v[74:77], v[170:173], v[236:239], v[74:77]
	s_setprio 0
	s_setprio 1
	v_mfma_f32_16x16x32_bf16 v[126:129], v[166:169], v[216:219], v[126:129]
	v_mfma_f32_16x16x32_bf16 v[122:125], v[174:177], v[216:219], v[122:125]
	v_mfma_f32_16x16x32_bf16 v[110:113], v[166:169], v[224:227], v[110:113]
	v_mfma_f32_16x16x32_bf16 v[106:109], v[174:177], v[224:227], v[106:109]
	v_mfma_f32_16x16x32_bf16 v[94:97], v[166:169], v[232:235], v[94:97]
	v_mfma_f32_16x16x32_bf16 v[90:93], v[174:177], v[232:235], v[90:93]
	v_mfma_f32_16x16x32_bf16 v[78:81], v[166:169], v[240:243], v[78:81]
	v_mfma_f32_16x16x32_bf16 v[74:77], v[174:177], v[240:243], v[74:77]
	s_setprio 0
	s_setprio 1
	v_mfma_f32_16x16x32_bf16 v[118:121], v[178:181], v[212:215], v[118:121]
	v_mfma_f32_16x16x32_bf16 v[114:117], v[204:207], v[212:215], v[114:117]
	v_mfma_f32_16x16x32_bf16 v[102:105], v[178:181], v[220:223], v[102:105]
	v_mfma_f32_16x16x32_bf16 v[98:101], v[204:207], v[220:223], v[98:101]
	v_mfma_f32_16x16x32_bf16 v[86:89], v[178:181], v[228:231], v[86:89]
	v_mfma_f32_16x16x32_bf16 v[82:85], v[204:207], v[228:231], v[82:85]
	v_mfma_f32_16x16x32_bf16 v[70:73], v[178:181], v[236:239], v[70:73]
	v_mfma_f32_16x16x32_bf16 v[66:69], v[204:207], v[236:239], v[66:69]
	s_setprio 0
	s_setprio 1
	v_mfma_f32_16x16x32_bf16 v[118:121], v[182:185], v[216:219], v[118:121]
	v_mfma_f32_16x16x32_bf16 v[114:117], v[208:211], v[216:219], v[114:117]
	v_mfma_f32_16x16x32_bf16 v[102:105], v[182:185], v[224:227], v[102:105]
	v_mfma_f32_16x16x32_bf16 v[98:101], v[208:211], v[224:227], v[98:101]
	v_mfma_f32_16x16x32_bf16 v[86:89], v[182:185], v[232:235], v[86:89]
	v_mfma_f32_16x16x32_bf16 v[82:85], v[208:211], v[232:235], v[82:85]
	v_mfma_f32_16x16x32_bf16 v[70:73], v[182:185], v[240:243], v[70:73]
	v_mfma_f32_16x16x32_bf16 v[66:69], v[208:211], v[240:243], v[66:69]
	s_setprio 0
	s_barrier
; #define PG8_STAGE(bufoff, gbase, voff) do { _Pragma("unroll") for (int _i = 0; _i < 2; ++_i) \
;         __builtin_amdgcn_global_load_lds((const unsigned*)((const char*)(gbase) + (voff)[_i]), (PG8_LAS unsigned*)(lds + (bufoff) + ldsw + _i * 8192), 16, 0, 0); } while (0)
; #define PG8_LDA(dst, b, h) do { _Pragma("unroll") for (int m = 0; m < 4; ++m) _Pragma("unroll") for (int k = 0; k < 2; ++k) dst[m][k] = *(const PG8_LAS bf16x8*)(lds + PG8_SA(b, h) + aoff + m * 2048 + k * 1024); } while (0)
; #define PG8_MMA(ai, bj, At, Bt) do { __builtin_amdgcn_s_setprio(1); _Pragma("unroll") for (int m = 0; m < 4; ++m) _Pragma("unroll") for (int n = 0; n < 2; ++n) _Pragma("unroll") for (int k = 0; k < 2; ++k) \
;         acc[ai][bj][m][n] = __builtin_amdgcn_mfma_f32_16x16x32_bf16(Bt[n][k], At[m][k], acc[ai][bj][m][n], 0, 0, 0); __builtin_amdgcn_s_setprio(0); } while (0)
; #define PG8_WAIT_V(n) asm volatile("s_waitcnt vmcnt(" #n ")" ::: "memory")
; #define PG8_WAIT_L(n) asm volatile("s_waitcnt lgkmcnt(" #n ")" ::: "memory")
; #define PG8_BAR __builtin_amdgcn_s_barrier()
; #define PG8_SCHED __builtin_amdgcn_sched_barrier(0)
; template <class Epi, class Sched, bool ALIGN_EPI = false, bool SP2 = false>
; __device__ __forceinline__ void gemm_phase(PG8_LAS unsigned char* lds, const Gemm g, const Sched& S, const Epi& E) {
;     ...
;         for (int t = 0; t < nt; t += 2) {
;             const bool last = (t == nt - 2);
;             const char* a1 = cA + (size_t)(t + 1) * kstep;
;             const char* a2 = last ? nA : cA + (size_t)(t + 2) * kstep; const char* b2 = last ? nB : cB + (size_t)(t + 2) * kstep;
;     ...
;             PG8_LDA(At, 1, 1); PG8_STAGE(PG8_SB(1, 0), b3, voffB); PG8_STAGE(PG8_SB(1, 1), b3 + hstep, voffB); PG8_STAGE(PG8_SA(1, 0), a3, voffA);
;             PG8_WAIT_V(8); PG8_WAIT_L(0); PG8_BAR; PG8_MMA(1, 0, At, B0); PG8_MMA(1, 1, At, B1); PG8_BAR; PG8_SCHED;
	s_add_i32 s47, s47, s54
	v_lshl_add_u64 v[158:159], v[158:159], 0, s[68:69]
	s_mov_b32 m0, s47
	ds_read_b128 v[212:215], v161 offset:49152
	ds_read_b128 v[216:219], v161 offset:50176
	ds_read_b128 v[220:223], v161 offset:51200
	ds_read_b128 v[224:227], v161 offset:52224
	ds_read_b128 v[228:231], v161 offset:53248
	ds_read_b128 v[232:235], v161 offset:54272
	ds_read_b128 v[236:239], v161 offset:55296
	ds_read_b128 v[240:243], v161 offset:56320
	global_load_lds_dwordx4 v[158:159], off
	s_add_i32 m0, s47, 0x2000
	s_add_u32 s18, s18, 0x80080
	v_lshl_add_u64 v[158:159], v[186:187], 0, s[68:69]
	s_addc_u32 s19, s19, 0
	s_add_i32 s47, s76, s54
	global_load_lds_dwordx4 v[158:159], off
	v_lshl_add_u64 v[158:159], s[18:19], 0, v[148:149]
	s_mov_b32 m0, s47
	s_nop 0
	global_load_lds_dwordx4 v[158:159], off
	v_lshl_add_u64 v[158:159], s[18:19], 0, v[144:145]
	s_add_i32 m0, s47, 0x2000
	s_nop 0
	global_load_lds_dwordx4 v[158:159], off
	v_lshl_add_u64 v[158:159], v[244:245], 0, s[68:69]
	s_mov_b32 m0, s5
	s_nop 0
	global_load_lds_dwordx4 v[158:159], off
	v_lshl_add_u64 v[158:159], v[246:247], 0, s[68:69]
	s_mov_b32 m0, s57
	s_nop 0
	global_load_lds_dwordx4 v[158:159], off
	s_nop 0
	s_waitcnt vmcnt(8)
	s_waitcnt lgkmcnt(0)
	s_setprio 1
	s_barrier
	v_mfma_f32_16x16x32_bf16 v[62:65], v[162:165], v[212:215], v[62:65]
	v_mfma_f32_16x16x32_bf16 v[58:61], v[170:173], v[212:215], v[58:61]
	v_mfma_f32_16x16x32_bf16 v[46:49], v[162:165], v[220:223], v[46:49]
	v_mfma_f32_16x16x32_bf16 v[42:45], v[170:173], v[220:223], v[42:45]
	v_mfma_f32_16x16x32_bf16 v[30:33], v[162:165], v[228:231], v[30:33]
	v_mfma_f32_16x16x32_bf16 v[26:29], v[170:173], v[228:231], v[26:29]
	v_mfma_f32_16x16x32_bf16 v[14:17], v[162:165], v[236:239], v[14:17]
	v_mfma_f32_16x16x32_bf16 v[10:13], v[170:173], v[236:239], v[10:13]
	v_mfma_f32_16x16x32_bf16 v[62:65], v[166:169], v[216:219], v[62:65]
	v_mfma_f32_16x16x32_bf16 v[58:61], v[174:177], v[216:219], v[58:61]
	v_mfma_f32_16x16x32_bf16 v[46:49], v[166:169], v[224:227], v[46:49]
	v_mfma_f32_16x16x32_bf16 v[42:45], v[174:177], v[224:227], v[42:45]
	v_mfma_f32_16x16x32_bf16 v[30:33], v[166:169], v[232:235], v[30:33]
	v_mfma_f32_16x16x32_bf16 v[26:29], v[174:177], v[232:235], v[26:29]
	v_mfma_f32_16x16x32_bf16 v[14:17], v[166:169], v[240:243], v[14:17]
	v_mfma_f32_16x16x32_bf16 v[10:13], v[174:177], v[240:243], v[10:13]
	v_mfma_f32_16x16x32_bf16 v[54:57], v[178:181], v[212:215], v[54:57]
	v_mfma_f32_16x16x32_bf16 v[50:53], v[204:207], v[212:215], v[50:53]
	v_mfma_f32_16x16x32_bf16 v[38:41], v[178:181], v[220:223], v[38:41]
	v_mfma_f32_16x16x32_bf16 v[34:37], v[204:207], v[220:223], v[34:37]
	v_mfma_f32_16x16x32_bf16 v[22:25], v[178:181], v[228:231], v[22:25]
	v_mfma_f32_16x16x32_bf16 v[18:21], v[204:207], v[228:231], v[18:21]
	v_mfma_f32_16x16x32_bf16 v[6:9], v[178:181], v[236:239], v[6:9]
	v_mfma_f32_16x16x32_bf16 v[2:5], v[204:207], v[236:239], v[2:5]
	v_mfma_f32_16x16x32_bf16 v[54:57], v[182:185], v[216:219], v[54:57]
	v_mfma_f32_16x16x32_bf16 v[50:53], v[208:211], v[216:219], v[50:53]
	v_mfma_f32_16x16x32_bf16 v[38:41], v[182:185], v[224:227], v[38:41]
	v_mfma_f32_16x16x32_bf16 v[34:37], v[208:211], v[224:227], v[34:37]
	v_mfma_f32_16x16x32_bf16 v[22:25], v[182:185], v[232:235], v[22:25]
	v_mfma_f32_16x16x32_bf16 v[18:21], v[208:211], v[232:235], v[18:21]
	v_mfma_f32_16x16x32_bf16 v[6:9], v[182:185], v[240:243], v[6:9]
	v_mfma_f32_16x16x32_bf16 v[2:5], v[208:211], v[240:243], v[2:5]
	s_setprio 0
	s_barrier
	s_add_i32 s46, s46, 2
	s_add_u32 s0, s0, 0x100
	s_addc_u32 s1, s1, 0
	s_add_u32 s78, s78, 0x100
	s_addc_u32 s79, s79, 0
	s_cmp_gt_u32 s46, 29

; #define PG8_STAGE(bufoff, gbase, voff) do { _Pragma("unroll") for (int _i = 0; _i < 2; ++_i) \
;         __builtin_amdgcn_global_load_lds((const unsigned*)((const char*)(gbase) + (voff)[_i]), (PG8_LAS unsigned*)(lds + (bufoff) + ldsw + _i * 8192), 16, 0, 0); } while (0)
; #define PG8_LDA(dst, b, h) do { _Pragma("unroll") for (int m = 0; m < 4; ++m) _Pragma("unroll") for (int k = 0; k < 2; ++k) dst[m][k] = *(const PG8_LAS bf16x8*)(lds + PG8_SA(b, h) + aoff + m * 2048 + k * 1024); } while (0)
; #define PG8_LDB(dst, b, h) do { _Pragma("unroll") for (int n = 0; n < 2; ++n) _Pragma("unroll") for (int k = 0; k < 2; ++k) dst[n][k] = *(const PG8_LAS bf16x8*)(lds + PG8_SB(b, h) + boff + n * 2048 + k * 1024); } while (0)
; #define PG8_WAIT_V(n) asm volatile("s_waitcnt vmcnt(" #n ")" ::: "memory")
; #define PG8_WAIT_L(n) asm volatile("s_waitcnt lgkmcnt(" #n ")" ::: "memory")
; #define PG8_BAR __builtin_amdgcn_s_barrier()
; #define PG8_SCHED __builtin_amdgcn_sched_barrier(0)
; template <class Epi, class Sched, bool ALIGN_EPI = false, bool SP2 = false>
; __device__ __forceinline__ void gemm_phase(PG8_LAS unsigned char* lds, const Gemm g, const Sched& S, const Epi& E) {
;     ...
;         const bool has_next = S.next(ui + 1, nxt);
;         const char* nA = has_next ? (const char*)g.A + (size_t)nxt.pm * tstep : cA; const char* nB = has_next ? (const char*)g.Bt + (size_t)nxt.pn * tstep : cB;
;         for (int t = 0; t < nt; t += 2) {
;             const bool last = (t == nt - 2);
;             const char* a1 = cA + (size_t)(t + 1) * kstep;
;             const char* a2 = last ? nA : cA + (size_t)(t + 2) * kstep; const char* b2 = last ? nB : cB + (size_t)(t + 2) * kstep;
;             const char* a3 = a2 + kstep; const char* b3 = b2 + kstep;
;             if (last && has_next) S.a_ready(nxt);
;             if constexpr (SP2) {
;             PG8_LDB(B0, 0, 0); PG8_LDB(B1, 0, 1); PG8_SCHED; PG8_LDA(At, 0, 0); PG8_STAGE(PG8_SA(1, 1), a1 + hstep, voffA);
;             PG8_WAIT_V(8); PG8_WAIT_L(0); PG8_BAR; PG8_MMA(0, 0, At, B0); PG8_MMA(0, 1, At, B1); PG8_BAR; PG8_SCHED;
;             PG8_LDA(At, 0, 1); PG8_STAGE(PG8_SB(0, 0), b2, voffB); PG8_STAGE(PG8_SB(0, 1), b2 + hstep, voffB); PG8_STAGE(PG8_SA(0, 0), a2, voffA);
;             PG8_WAIT_V(8); PG8_WAIT_L(0); PG8_BAR; PG8_MMA(1, 0, At, B0); PG8_MMA(1, 1, At, B1); PG8_BAR; PG8_SCHED;
.LBB0_97:
	s_ashr_i32 s97, s96, 31
	s_lshl_b64 s[18:19], s[96:97], 20
	s_add_u32 s18, s12, s18
	s_addc_u32 s19, s13, s19
	s_and_b64 s[46:47], s[44:45], exec
	s_cselect_b32 s97, s19, s41
	s_cselect_b32 s84, s18, s40
	s_ashr_i32 s95, s94, 31
	s_lshl_b64 s[46:47], s[94:95], 20
	v_readlane_b32 s62, v254, 45
	v_readlane_b32 s63, v254, 46
	s_add_u32 s62, s62, s46
	s_addc_u32 s63, s63, s47
	s_and_b64 s[46:47], s[44:45], exec
	s_cselect_b32 s85, s63, s59
	s_cselect_b32 s95, s62, s58
	s_add_u32 vcc_lo, s40, 0x80080
	s_addc_u32 vcc_hi, s41, 0
	s_add_u32 s78, s58, 0x100
	s_addc_u32 s79, s59, 0
	s_mov_b32 s46, -2
	s_waitcnt lgkmcnt(0)
	s_waitcnt vmcnt(0)
	s_add_u32 s40, vcc_lo, 0xfff80080
	s_addc_u32 s41, vcc_hi, -1
	s_add_i32 s47, 0, 0x10000
	s_cmp_eq_u32 s46, 28
	s_cselect_b32 s59, s97, s41
	s_cselect_b32 s58, s84, s40
	s_cselect_b32 s41, s85, s79
	s_cselect_b32 s40, s95, s78
	s_add_i32 s80, 0, 0x14000
	v_add_u32_e32 v170, s47, v143
	v_add_u32_e32 v186, s80, v143
	ds_read_b128 v[156:159], v170
	ds_read_b128 v[162:165], v170 offset:1024
	ds_read_b128 v[166:169], v170 offset:2048
	ds_read_b128 v[170:173], v170 offset:3072
	ds_read_b128 v[174:177], v186
	ds_read_b128 v[178:181], v186 offset:1024
	ds_read_b128 v[182:185], v186 offset:2048
	ds_read_b128 v[204:207], v186 offset:3072
	v_lshl_add_u64 v[186:187], vcc, 0, v[152:153]
	s_add_i32 m0, s5, 0xc000
	ds_read_b128 v[208:211], v161
	ds_read_b128 v[212:215], v161 offset:1024
	ds_read_b128 v[216:219], v161 offset:2048
	ds_read_b128 v[220:223], v161 offset:3072
	ds_read_b128 v[224:227], v161 offset:4096
	ds_read_b128 v[228:231], v161 offset:5120
	ds_read_b128 v[232:235], v161 offset:6144
	ds_read_b128 v[236:239], v161 offset:7168
	global_load_lds_dwordx4 v[186:187], off
	v_lshl_add_u64 v[186:187], vcc, 0, v[154:155]
	s_add_i32 m0, s5, 0xe000
	s_nop 0
	global_load_lds_dwordx4 v[186:187], off
	s_waitcnt vmcnt(8)
	s_waitcnt lgkmcnt(0)
	s_setprio 1
	s_barrier
	v_mfma_f32_16x16x32_bf16 v[126:129], v[156:159], v[208:211], 0
	v_mfma_f32_16x16x32_bf16 v[122:125], v[166:169], v[208:211], 0
	v_mfma_f32_16x16x32_bf16 v[110:113], v[156:159], v[216:219], 0
	v_mfma_f32_16x16x32_bf16 v[106:109], v[166:169], v[216:219], 0
	v_mfma_f32_16x16x32_bf16 v[94:97], v[156:159], v[224:227], 0
	v_mfma_f32_16x16x32_bf16 v[90:93], v[166:169], v[224:227], 0
	v_mfma_f32_16x16x32_bf16 v[78:81], v[156:159], v[232:235], 0
	v_mfma_f32_16x16x32_bf16 v[74:77], v[166:169], v[232:235], 0
	s_setprio 0
	s_setprio 1
	v_mfma_f32_16x16x32_bf16 v[126:129], v[162:165], v[212:215], v[126:129]
	v_mfma_f32_16x16x32_bf16 v[122:125], v[170:173], v[212:215], v[122:125]
	v_mfma_f32_16x16x32_bf16 v[110:113], v[162:165], v[220:223], v[110:113]
	v_mfma_f32_16x16x32_bf16 v[106:109], v[170:173], v[220:223], v[106:109]
	v_mfma_f32_16x16x32_bf16 v[94:97], v[162:165], v[228:231], v[94:97]
	v_mfma_f32_16x16x32_bf16 v[90:93], v[170:173], v[228:231], v[90:93]
	v_mfma_f32_16x16x32_bf16 v[78:81], v[162:165], v[236:239], v[78:81]
	v_mfma_f32_16x16x32_bf16 v[74:77], v[170:173], v[236:239], v[74:77]
	s_setprio 0
	s_setprio 1
	v_mfma_f32_16x16x32_bf16 v[118:121], v[174:177], v[208:211], 0
	v_mfma_f32_16x16x32_bf16 v[114:117], v[182:185], v[208:211], 0
	v_mfma_f32_16x16x32_bf16 v[102:105], v[174:177], v[216:219], 0
	v_mfma_f32_16x16x32_bf16 v[98:101], v[182:185], v[216:219], 0
	v_mfma_f32_16x16x32_bf16 v[86:89], v[174:177], v[224:227], 0
	v_mfma_f32_16x16x32_bf16 v[82:85], v[182:185], v[224:227], 0
	v_mfma_f32_16x16x32_bf16 v[70:73], v[174:177], v[232:235], 0
	v_mfma_f32_16x16x32_bf16 v[66:69], v[182:185], v[232:235], 0
	s_setprio 0
	s_setprio 1
	v_mfma_f32_16x16x32_bf16 v[118:121], v[178:181], v[212:215], v[118:121]
	v_mfma_f32_16x16x32_bf16 v[114:117], v[204:207], v[212:215], v[114:117]
	v_mfma_f32_16x16x32_bf16 v[102:105], v[178:181], v[220:223], v[102:105]
	v_mfma_f32_16x16x32_bf16 v[98:101], v[204:207], v[220:223], v[98:101]
	v_mfma_f32_16x16x32_bf16 v[86:89], v[178:181], v[228:231], v[86:89]
	v_mfma_f32_16x16x32_bf16 v[82:85], v[204:207], v[228:231], v[82:85]
	v_mfma_f32_16x16x32_bf16 v[70:73], v[178:181], v[236:239], v[70:73]
	v_mfma_f32_16x16x32_bf16 v[66:69], v[204:207], v[236:239], v[66:69]
	s_setprio 0
	s_barrier
	s_add_i32 s47, s47, s4
	v_lshl_add_u64 v[186:187], s[40:41], 0, v[148:149]
	s_mov_b32 m0, s47
	ds_read_b128 v[208:211], v161 offset:16384
	ds_read_b128 v[212:215], v161 offset:17408
	ds_read_b128 v[216:219], v161 offset:18432
	ds_read_b128 v[220:223], v161 offset:19456
	ds_read_b128 v[224:227], v161 offset:20480
	ds_read_b128 v[228:231], v161 offset:21504
	ds_read_b128 v[232:235], v161 offset:22528
	ds_read_b128 v[236:239], v161 offset:23552
	global_load_lds_dwordx4 v[186:187], off
	s_add_i32 m0, s47, 0x2000
	s_add_u32 s76, s40, 0x80000
	v_lshl_add_u64 v[240:241], s[40:41], 0, v[144:145]
	s_addc_u32 s77, s41, 0
	s_add_i32 s47, s80, s4
	global_load_lds_dwordx4 v[240:241], off
	v_lshl_add_u64 v[242:243], s[76:77], 0, v[148:149]
	s_mov_b32 m0, s47
	v_lshl_add_u64 v[244:245], s[58:59], 0, v[146:147]
	global_load_lds_dwordx4 v[242:243], off
	v_lshl_add_u64 v[242:243], s[76:77], 0, v[144:145]
	s_add_i32 m0, s47, 0x2000
	s_nop 0
	global_load_lds_dwordx4 v[242:243], off
	v_lshl_add_u64 v[242:243], s[58:59], 0, v[150:151]
	s_mov_b32 m0, s5
	s_nop 0
	global_load_lds_dwordx4 v[242:243], off
	s_mov_b32 m0, s30
	s_nop 0
	global_load_lds_dwordx4 v[244:245], off
	s_waitcnt vmcnt(8)
	s_waitcnt lgkmcnt(0)
	s_setprio 1
	s_barrier
; #define PG8_STAGE(bufoff, gbase, voff) do { _Pragma("unroll") for (int _i = 0; _i < 2; ++_i) \
;         __builtin_amdgcn_global_load_lds((const unsigned*)((const char*)(gbase) + (voff)[_i]), (PG8_LAS unsigned*)(lds + (bufoff) + ldsw + _i * 8192), 16, 0, 0); } while (0)
; #define PG8_LDA(dst, b, h) do { _Pragma("unroll") for (int m = 0; m < 4; ++m) _Pragma("unroll") for (int k = 0; k < 2; ++k) dst[m][k] = *(const PG8_LAS bf16x8*)(lds + PG8_SA(b, h) + aoff + m * 2048 + k * 1024); } while (0)
; #define PG8_LDB(dst, b, h) do { _Pragma("unroll") for (int n = 0; n < 2; ++n) _Pragma("unroll") for (int k = 0; k < 2; ++k) dst[n][k] = *(const PG8_LAS bf16x8*)(lds + PG8_SB(b, h) + boff + n * 2048 + k * 1024); } while (0)
; #define PG8_MMA(ai, bj, At, Bt) do { __builtin_amdgcn_s_setprio(1); _Pragma("unroll") for (int m = 0; m < 4; ++m) _Pragma("unroll") for (int n = 0; n < 2; ++n) _Pragma("unroll") for (int k = 0; k < 2; ++k) \
;         acc[ai][bj][m][n] = __builtin_amdgcn_mfma_f32_16x16x32_bf16(Bt[n][k], At[m][k], acc[ai][bj][m][n], 0, 0, 0); __builtin_amdgcn_s_setprio(0); } while (0)
; #define PG8_WAIT_V(n) asm volatile("s_waitcnt vmcnt(" #n ")" ::: "memory")
; #define PG8_WAIT_L(n) asm volatile("s_waitcnt lgkmcnt(" #n ")" ::: "memory")
; #define PG8_BAR __builtin_amdgcn_s_barrier()
; #define PG8_SCHED __builtin_amdgcn_sched_barrier(0)
; template <class Epi, class Sched, bool ALIGN_EPI = false, bool SP2 = false>
; __device__ __forceinline__ void gemm_phase(PG8_LAS unsigned char* lds, const Gemm g, const Sched& S, const Epi& E) {
;     ...
;             PG8_WAIT_V(8); PG8_WAIT_L(0); PG8_BAR; PG8_MMA(1, 0, At, B0); PG8_MMA(1, 1, At, B1); PG8_BAR; PG8_SCHED;
;             PG8_LDB(B0, 1, 0); PG8_LDB(B1, 1, 1); PG8_SCHED; PG8_LDA(At, 1, 0); PG8_STAGE(PG8_SA(0, 1), a2 + hstep, voffA);
;             PG8_WAIT_V(8); PG8_WAIT_L(0); PG8_BAR; PG8_MMA(0, 0, At, B0); PG8_MMA(0, 1, At, B1); PG8_BAR; PG8_SCHED;
;             PG8_LDA(At, 1, 1); PG8_STAGE(PG8_SB(1, 0), b3, voffB); PG8_STAGE(PG8_SB(1, 1), b3 + hstep, voffB); PG8_STAGE(PG8_SA(1, 0), a3, voffA);
	v_mfma_f32_16x16x32_bf16 v[62:65], v[156:159], v[208:211], 0
	v_mfma_f32_16x16x32_bf16 v[58:61], v[166:169], v[208:211], 0
	v_mfma_f32_16x16x32_bf16 v[46:49], v[156:159], v[216:219], 0
	v_mfma_f32_16x16x32_bf16 v[42:45], v[166:169], v[216:219], 0
	v_mfma_f32_16x16x32_bf16 v[30:33], v[156:159], v[224:227], 0
	v_mfma_f32_16x16x32_bf16 v[26:29], v[166:169], v[224:227], 0
	v_mfma_f32_16x16x32_bf16 v[14:17], v[156:159], v[232:235], 0
	v_mfma_f32_16x16x32_bf16 v[10:13], v[166:169], v[232:235], 0
	v_mfma_f32_16x16x32_bf16 v[62:65], v[162:165], v[212:215], v[62:65]
	v_mfma_f32_16x16x32_bf16 v[58:61], v[170:173], v[212:215], v[58:61]
	v_mfma_f32_16x16x32_bf16 v[46:49], v[162:165], v[220:223], v[46:49]
	v_mfma_f32_16x16x32_bf16 v[42:45], v[170:173], v[220:223], v[42:45]
	v_mfma_f32_16x16x32_bf16 v[30:33], v[162:165], v[228:231], v[30:33]
	v_mfma_f32_16x16x32_bf16 v[26:29], v[170:173], v[228:231], v[26:29]
	v_mfma_f32_16x16x32_bf16 v[14:17], v[162:165], v[236:239], v[14:17]
	v_mfma_f32_16x16x32_bf16 v[10:13], v[170:173], v[236:239], v[10:13]
	v_mfma_f32_16x16x32_bf16 v[54:57], v[174:177], v[208:211], 0
	v_mfma_f32_16x16x32_bf16 v[50:53], v[182:185], v[208:211], 0
	v_mfma_f32_16x16x32_bf16 v[38:41], v[174:177], v[216:219], 0
	v_mfma_f32_16x16x32_bf16 v[34:37], v[182:185], v[216:219], 0
	v_mfma_f32_16x16x32_bf16 v[22:25], v[174:177], v[224:227], 0
	v_mfma_f32_16x16x32_bf16 v[18:21], v[182:185], v[224:227], 0
	v_mfma_f32_16x16x32_bf16 v[6:9], v[174:177], v[232:235], 0
	v_mfma_f32_16x16x32_bf16 v[2:5], v[182:185], v[232:235], 0
	v_mfma_f32_16x16x32_bf16 v[54:57], v[178:181], v[212:215], v[54:57]
	v_mfma_f32_16x16x32_bf16 v[50:53], v[204:207], v[212:215], v[50:53]
	v_mfma_f32_16x16x32_bf16 v[38:41], v[178:181], v[220:223], v[38:41]
	v_mfma_f32_16x16x32_bf16 v[34:37], v[204:207], v[220:223], v[34:37]
	v_mfma_f32_16x16x32_bf16 v[22:25], v[178:181], v[228:231], v[22:25]
	v_mfma_f32_16x16x32_bf16 v[18:21], v[204:207], v[228:231], v[18:21]
	v_mfma_f32_16x16x32_bf16 v[6:9], v[178:181], v[236:239], v[6:9]
	v_mfma_f32_16x16x32_bf16 v[2:5], v[204:207], v[236:239], v[2:5]
	s_setprio 0
	s_barrier
	s_add_i32 s47, 0, 0x18000
	s_add_i32 s76, 0, 0x1c000
	v_add_u32_e32 v170, s47, v143
	v_add_u32_e32 v203, s76, v143
	ds_read_b128 v[156:159], v170
	ds_read_b128 v[162:165], v170 offset:1024
	ds_read_b128 v[166:169], v170 offset:2048
	ds_read_b128 v[170:173], v170 offset:3072
	ds_read_b128 v[174:177], v203
	ds_read_b128 v[178:181], v203 offset:1024
	ds_read_b128 v[182:185], v203 offset:2048
	ds_read_b128 v[204:207], v203 offset:3072
	s_add_u32 s58, s58, 0x80000
	s_addc_u32 s59, s59, 0
	s_mov_b32 m0, s34
	v_lshl_add_u64 v[246:247], s[58:59], 0, v[150:151]
	ds_read_b128 v[208:211], v161 offset:32768
	ds_read_b128 v[212:215], v161 offset:33792
	ds_read_b128 v[216:219], v161 offset:34816
	ds_read_b128 v[220:223], v161 offset:35840
	ds_read_b128 v[224:227], v161 offset:36864
	ds_read_b128 v[228:231], v161 offset:37888
	ds_read_b128 v[232:235], v161 offset:38912
	ds_read_b128 v[236:239], v161 offset:39936
	global_load_lds_dwordx4 v[246:247], off
	v_lshl_add_u64 v[246:247], s[58:59], 0, v[146:147]
	s_mov_b32 m0, s57
	s_nop 0
	global_load_lds_dwordx4 v[246:247], off
	s_waitcnt vmcnt(8)
	s_waitcnt lgkmcnt(0)
	s_setprio 1
	s_barrier
	v_mfma_f32_16x16x32_bf16 v[126:129], v[156:159], v[208:211], v[126:129]
	v_mfma_f32_16x16x32_bf16 v[122:125], v[166:169], v[208:211], v[122:125]
	v_mfma_f32_16x16x32_bf16 v[110:113], v[156:159], v[216:219], v[110:113]
	v_mfma_f32_16x16x32_bf16 v[106:109], v[166:169], v[216:219], v[106:109]
	v_mfma_f32_16x16x32_bf16 v[94:97], v[156:159], v[224:227], v[94:97]
	v_mfma_f32_16x16x32_bf16 v[90:93], v[166:169], v[224:227], v[90:93]
	v_mfma_f32_16x16x32_bf16 v[78:81], v[156:159], v[232:235], v[78:81]
	v_mfma_f32_16x16x32_bf16 v[74:77], v[166:169], v[232:235], v[74:77]
	s_setprio 0
	s_setprio 1
	v_mfma_f32_16x16x32_bf16 v[126:129], v[162:165], v[212:215], v[126:129]
	v_mfma_f32_16x16x32_bf16 v[122:125], v[170:173], v[212:215], v[122:125]
	v_mfma_f32_16x16x32_bf16 v[110:113], v[162:165], v[220:223], v[110:113]
	v_mfma_f32_16x16x32_bf16 v[106:109], v[170:173], v[220:223], v[106:109]
	v_mfma_f32_16x16x32_bf16 v[94:97], v[162:165], v[228:231], v[94:97]
	v_mfma_f32_16x16x32_bf16 v[90:93], v[170:173], v[228:231], v[90:93]
	v_mfma_f32_16x16x32_bf16 v[78:81], v[162:165], v[236:239], v[78:81]
	v_mfma_f32_16x16x32_bf16 v[74:77], v[170:173], v[236:239], v[74:77]
	s_setprio 0
	s_setprio 1
	v_mfma_f32_16x16x32_bf16 v[118:121], v[174:177], v[208:211], v[118:121]
	v_mfma_f32_16x16x32_bf16 v[114:117], v[182:185], v[208:211], v[114:117]
	v_mfma_f32_16x16x32_bf16 v[102:105], v[174:177], v[216:219], v[102:105]
	v_mfma_f32_16x16x32_bf16 v[98:101], v[182:185], v[216:219], v[98:101]
	v_mfma_f32_16x16x32_bf16 v[86:89], v[174:177], v[224:227], v[86:89]
	v_mfma_f32_16x16x32_bf16 v[82:85], v[182:185], v[224:227], v[82:85]
	v_mfma_f32_16x16x32_bf16 v[70:73], v[174:177], v[232:235], v[70:73]
	v_mfma_f32_16x16x32_bf16 v[66:69], v[182:185], v[232:235], v[66:69]
	s_setprio 0
	s_setprio 1
	v_mfma_f32_16x16x32_bf16 v[118:121], v[178:181], v[212:215], v[118:121]
	v_mfma_f32_16x16x32_bf16 v[114:117], v[204:207], v[212:215], v[114:117]
	v_mfma_f32_16x16x32_bf16 v[102:105], v[178:181], v[220:223], v[102:105]
	v_mfma_f32_16x16x32_bf16 v[98:101], v[204:207], v[220:223], v[98:101]
	v_mfma_f32_16x16x32_bf16 v[86:89], v[178:181], v[228:231], v[86:89]
	v_mfma_f32_16x16x32_bf16 v[82:85], v[204:207], v[228:231], v[82:85]
	v_mfma_f32_16x16x32_bf16 v[70:73], v[178:181], v[236:239], v[70:73]
	v_mfma_f32_16x16x32_bf16 v[66:69], v[204:207], v[236:239], v[66:69]
	s_setprio 0
	s_barrier
; #define PG8_STAGE(bufoff, gbase, voff) do { _Pragma("unroll") for (int _i = 0; _i < 2; ++_i) \
;         __builtin_amdgcn_global_load_lds((const unsigned*)((const char*)(gbase) + (voff)[_i]), (PG8_LAS unsigned*)(lds + (bufoff) + ldsw + _i * 8192), 16, 0, 0); } while (0)
; #define PG8_LDA(dst, b, h) do { _Pragma("unroll") for (int m = 0; m < 4; ++m) _Pragma("unroll") for (int k = 0; k < 2; ++k) dst[m][k] = *(const PG8_LAS bf16x8*)(lds + PG8_SA(b, h) + aoff + m * 2048 + k * 1024); } while (0)
; #define PG8_LDB(dst, b, h) do { _Pragma("unroll") for (int n = 0; n < 2; ++n) _Pragma("unroll") for (int k = 0; k < 2; ++k) dst[n][k] = *(const PG8_LAS bf16x8*)(lds + PG8_SB(b, h) + boff + n * 2048 + k * 1024); } while (0)
; #define PG8_MMA(ai, bj, At, Bt) do { __builtin_amdgcn_s_setprio(1); _Pragma("unroll") for (int m = 0; m < 4; ++m) _Pragma("unroll") for (int n = 0; n < 2; ++n) _Pragma("unroll") for (int k = 0; k < 2; ++k) \
;         acc[ai][bj][m][n] = __builtin_amdgcn_mfma_f32_16x16x32_bf16(Bt[n][k], At[m][k], acc[ai][bj][m][n], 0, 0, 0); __builtin_amdgcn_s_setprio(0); } while (0)
; #define PG8_WAIT_V(n) asm volatile("s_waitcnt vmcnt(" #n ")" ::: "memory")
; #define PG8_WAIT_L(n) asm volatile("s_waitcnt lgkmcnt(" #n ")" ::: "memory")
; #define PG8_BAR __builtin_amdgcn_s_barrier()
; #define PG8_SCHED __builtin_amdgcn_sched_barrier(0)
; template <class Epi, class Sched, bool ALIGN_EPI = false, bool SP2 = false>
; __device__ __forceinline__ void gemm_phase(PG8_LAS unsigned char* lds, const Gemm g, const Sched& S, const Epi& E) {
;     ...
;             PG8_LDB(B0, 0, 0); PG8_LDB(B1, 0, 1); PG8_SCHED; PG8_LDA(At, 0, 0); PG8_STAGE(PG8_SA(1, 1), a1 + hstep, voffA);
;             PG8_WAIT_V(8); PG8_WAIT_L(0); PG8_BAR; PG8_MMA(0, 0, At, B0); PG8_MMA(0, 1, At, B1); PG8_BAR; PG8_SCHED;
;     ...
;             PG8_LDA(At, 1, 1); PG8_STAGE(PG8_SB(1, 0), b3, voffB); PG8_STAGE(PG8_SB(1, 1), b3 + hstep, voffB); PG8_STAGE(PG8_SA(1, 0), a3, voffA);
;             PG8_WAIT_V(8); PG8_WAIT_L(0); PG8_BAR; PG8_MMA(1, 0, At, B0); PG8_MMA(1, 1, At, B1); PG8_BAR; PG8_SCHED;
	s_add_i32 s47, s47, s4
	v_lshl_add_u64 v[186:187], v[186:187], 0, s[68:69]
	s_mov_b32 m0, s47
	ds_read_b128 v[208:211], v161 offset:49152
	ds_read_b128 v[212:215], v161 offset:50176
	ds_read_b128 v[216:219], v161 offset:51200
	ds_read_b128 v[220:223], v161 offset:52224
	ds_read_b128 v[224:227], v161 offset:53248
	ds_read_b128 v[228:231], v161 offset:54272
	ds_read_b128 v[232:235], v161 offset:55296
	ds_read_b128 v[236:239], v161 offset:56320
	global_load_lds_dwordx4 v[186:187], off
	s_add_i32 m0, s47, 0x2000
	s_add_u32 s40, s40, 0x80080
	v_lshl_add_u64 v[186:187], v[240:241], 0, s[68:69]
	s_addc_u32 s41, s41, 0
	s_add_i32 s47, s76, s4
	global_load_lds_dwordx4 v[186:187], off
	v_lshl_add_u64 v[186:187], s[40:41], 0, v[148:149]
	s_mov_b32 m0, s47
	s_nop 0
	global_load_lds_dwordx4 v[186:187], off
	v_lshl_add_u64 v[186:187], s[40:41], 0, v[144:145]
	s_add_i32 m0, s47, 0x2000
	s_nop 0
	global_load_lds_dwordx4 v[186:187], off
	v_lshl_add_u64 v[186:187], v[242:243], 0, s[68:69]
	s_mov_b32 m0, s67
	s_nop 0
	global_load_lds_dwordx4 v[186:187], off
	v_lshl_add_u64 v[186:187], v[244:245], 0, s[68:69]
	s_mov_b32 m0, s28
	s_nop 0
	global_load_lds_dwordx4 v[186:187], off
	s_nop 0
	s_waitcnt vmcnt(8)
	s_waitcnt lgkmcnt(0)
	s_setprio 1
	s_barrier
	v_mfma_f32_16x16x32_bf16 v[62:65], v[156:159], v[208:211], v[62:65]
	v_mfma_f32_16x16x32_bf16 v[58:61], v[166:169], v[208:211], v[58:61]
	v_mfma_f32_16x16x32_bf16 v[46:49], v[156:159], v[216:219], v[46:49]
	v_mfma_f32_16x16x32_bf16 v[42:45], v[166:169], v[216:219], v[42:45]
	v_mfma_f32_16x16x32_bf16 v[30:33], v[156:159], v[224:227], v[30:33]
	v_mfma_f32_16x16x32_bf16 v[26:29], v[166:169], v[224:227], v[26:29]
	v_mfma_f32_16x16x32_bf16 v[14:17], v[156:159], v[232:235], v[14:17]
	v_mfma_f32_16x16x32_bf16 v[10:13], v[166:169], v[232:235], v[10:13]
	v_mfma_f32_16x16x32_bf16 v[62:65], v[162:165], v[212:215], v[62:65]
	v_mfma_f32_16x16x32_bf16 v[58:61], v[170:173], v[212:215], v[58:61]
	v_mfma_f32_16x16x32_bf16 v[46:49], v[162:165], v[220:223], v[46:49]
	v_mfma_f32_16x16x32_bf16 v[42:45], v[170:173], v[220:223], v[42:45]
	v_mfma_f32_16x16x32_bf16 v[30:33], v[162:165], v[228:231], v[30:33]
	v_mfma_f32_16x16x32_bf16 v[26:29], v[170:173], v[228:231], v[26:29]
	v_mfma_f32_16x16x32_bf16 v[14:17], v[162:165], v[236:239], v[14:17]
	v_mfma_f32_16x16x32_bf16 v[10:13], v[170:173], v[236:239], v[10:13]
	v_mfma_f32_16x16x32_bf16 v[54:57], v[174:177], v[208:211], v[54:57]
	v_mfma_f32_16x16x32_bf16 v[50:53], v[182:185], v[208:211], v[50:53]
	v_mfma_f32_16x16x32_bf16 v[38:41], v[174:177], v[216:219], v[38:41]
	v_mfma_f32_16x16x32_bf16 v[34:37], v[182:185], v[216:219], v[34:37]
	v_mfma_f32_16x16x32_bf16 v[22:25], v[174:177], v[224:227], v[22:25]
	v_mfma_f32_16x16x32_bf16 v[18:21], v[182:185], v[224:227], v[18:21]
	v_mfma_f32_16x16x32_bf16 v[6:9], v[174:177], v[232:235], v[6:9]
	v_mfma_f32_16x16x32_bf16 v[2:5], v[182:185], v[232:235], v[2:5]
	v_mfma_f32_16x16x32_bf16 v[54:57], v[178:181], v[212:215], v[54:57]
	v_mfma_f32_16x16x32_bf16 v[50:53], v[204:207], v[212:215], v[50:53]
	v_mfma_f32_16x16x32_bf16 v[38:41], v[178:181], v[220:223], v[38:41]
	v_mfma_f32_16x16x32_bf16 v[34:37], v[204:207], v[220:223], v[34:37]
	v_mfma_f32_16x16x32_bf16 v[22:25], v[178:181], v[228:231], v[22:25]
	v_mfma_f32_16x16x32_bf16 v[18:21], v[204:207], v[228:231], v[18:21]
	v_mfma_f32_16x16x32_bf16 v[6:9], v[178:181], v[236:239], v[6:9]
	v_mfma_f32_16x16x32_bf16 v[2:5], v[204:207], v[236:239], v[2:5]
	s_setprio 0
	s_barrier
	s_add_i32 s46, s46, 2
	s_add_u32 vcc_lo, vcc_lo, 0x100
	s_addc_u32 vcc_hi, vcc_hi, 0
	s_add_u32 s78, s78, 0x100
	s_addc_u32 s79, s79, 0
	s_cmp_gt_u32 s46, 29
.LBB0_98:
	s_add_u32 s40, vcc_lo, 0xfff80080
	s_addc_u32 s41, vcc_hi, -1
	s_add_i32 s47, 0, 0x10000
	s_cmp_eq_u32 s46, 28
	s_cselect_b32 s59, s97, s41
	s_cselect_b32 s58, s84, s40
	s_cselect_b32 s41, s85, s79
	s_cselect_b32 s40, s95, s78
	s_add_i32 s80, 0, 0x14000
	v_add_u32_e32 v170, s47, v143
	v_add_u32_e32 v186, s80, v143
	ds_read_b128 v[156:159], v170
	ds_read_b128 v[162:165], v170 offset:1024
	ds_read_b128 v[166:169], v170 offset:2048
	ds_read_b128 v[170:173], v170 offset:3072
	ds_read_b128 v[174:177], v186
	ds_read_b128 v[178:181], v186 offset:1024
	ds_read_b128 v[182:185], v186 offset:2048
	ds_read_b128 v[204:207], v186 offset:3072
	v_lshl_add_u64 v[186:187], vcc, 0, v[152:153]
	s_add_i32 m0, s5, 0xc000
	ds_read_b128 v[208:211], v161
	ds_read_b128 v[212:215], v161 offset:1024
	ds_read_b128 v[216:219], v161 offset:2048
	ds_read_b128 v[220:223], v161 offset:3072
	ds_read_b128 v[224:227], v161 offset:4096
	ds_read_b128 v[228:231], v161 offset:5120
	ds_read_b128 v[232:235], v161 offset:6144
	ds_read_b128 v[236:239], v161 offset:7168
	global_load_lds_dwordx4 v[186:187], off
	v_lshl_add_u64 v[186:187], vcc, 0, v[154:155]
	s_add_i32 m0, s5, 0xe000
	s_nop 0
	global_load_lds_dwordx4 v[186:187], off
	s_nop 0
	s_waitcnt vmcnt(8)
	s_waitcnt lgkmcnt(0)
	s_setprio 1
	s_barrier
; #define PG8_STAGE(bufoff, gbase, voff) do { _Pragma("unroll") for (int _i = 0; _i < 2; ++_i) \
;         __builtin_amdgcn_global_load_lds((const unsigned*)((const char*)(gbase) + (voff)[_i]), (PG8_LAS unsigned*)(lds + (bufoff) + ldsw + _i * 8192), 16, 0, 0); } while (0)
; #define PG8_LDA(dst, b, h) do { _Pragma("unroll") for (int m = 0; m < 4; ++m) _Pragma("unroll") for (int k = 0; k < 2; ++k) dst[m][k] = *(const PG8_LAS bf16x8*)(lds + PG8_SA(b, h) + aoff + m * 2048 + k * 1024); } while (0)
; #define PG8_MMA(ai, bj, At, Bt) do { __builtin_amdgcn_s_setprio(1); _Pragma("unroll") for (int m = 0; m < 4; ++m) _Pragma("unroll") for (int n = 0; n < 2; ++n) _Pragma("unroll") for (int k = 0; k < 2; ++k) \
;         acc[ai][bj][m][n] = __builtin_amdgcn_mfma_f32_16x16x32_bf16(Bt[n][k], At[m][k], acc[ai][bj][m][n], 0, 0, 0); __builtin_amdgcn_s_setprio(0); } while (0)
; #define PG8_WAIT_V(n) asm volatile("s_waitcnt vmcnt(" #n ")" ::: "memory")
; #define PG8_WAIT_L(n) asm volatile("s_waitcnt lgkmcnt(" #n ")" ::: "memory")
; #define PG8_BAR __builtin_amdgcn_s_barrier()
; #define PG8_SCHED __builtin_amdgcn_sched_barrier(0)
; template <class Epi, class Sched, bool ALIGN_EPI = false, bool SP2 = false>
; __device__ __forceinline__ void gemm_phase(PG8_LAS unsigned char* lds, const Gemm g, const Sched& S, const Epi& E) {
;     ...
;             PG8_WAIT_V(8); PG8_WAIT_L(0); PG8_BAR; PG8_MMA(0, 0, At, B0); PG8_MMA(0, 1, At, B1); PG8_BAR; PG8_SCHED;
;             PG8_LDA(At, 0, 1); PG8_STAGE(PG8_SB(0, 0), b2, voffB); PG8_STAGE(PG8_SB(0, 1), b2 + hstep, voffB); PG8_STAGE(PG8_SA(0, 0), a2, voffA);
;             PG8_WAIT_V(8); PG8_WAIT_L(0); PG8_BAR; PG8_MMA(1, 0, At, B0); PG8_MMA(1, 1, At, B1); PG8_BAR; PG8_SCHED;
	v_mfma_f32_16x16x32_bf16 v[126:129], v[156:159], v[208:211], v[126:129]
	v_mfma_f32_16x16x32_bf16 v[122:125], v[166:169], v[208:211], v[122:125]
	v_mfma_f32_16x16x32_bf16 v[110:113], v[156:159], v[216:219], v[110:113]
	v_mfma_f32_16x16x32_bf16 v[106:109], v[166:169], v[216:219], v[106:109]
	v_mfma_f32_16x16x32_bf16 v[94:97], v[156:159], v[224:227], v[94:97]
	v_mfma_f32_16x16x32_bf16 v[90:93], v[166:169], v[224:227], v[90:93]
	v_mfma_f32_16x16x32_bf16 v[78:81], v[156:159], v[232:235], v[78:81]
	v_mfma_f32_16x16x32_bf16 v[74:77], v[166:169], v[232:235], v[74:77]
	s_setprio 0
	s_setprio 1
	v_mfma_f32_16x16x32_bf16 v[126:129], v[162:165], v[212:215], v[126:129]
	v_mfma_f32_16x16x32_bf16 v[122:125], v[170:173], v[212:215], v[122:125]
	v_mfma_f32_16x16x32_bf16 v[110:113], v[162:165], v[220:223], v[110:113]
	v_mfma_f32_16x16x32_bf16 v[106:109], v[170:173], v[220:223], v[106:109]
	v_mfma_f32_16x16x32_bf16 v[94:97], v[162:165], v[228:231], v[94:97]
	v_mfma_f32_16x16x32_bf16 v[90:93], v[170:173], v[228:231], v[90:93]
	v_mfma_f32_16x16x32_bf16 v[78:81], v[162:165], v[236:239], v[78:81]
	v_mfma_f32_16x16x32_bf16 v[74:77], v[170:173], v[236:239], v[74:77]
	s_setprio 0
	s_setprio 1
	v_mfma_f32_16x16x32_bf16 v[118:121], v[174:177], v[208:211], v[118:121]
	v_mfma_f32_16x16x32_bf16 v[114:117], v[182:185], v[208:211], v[114:117]
	v_mfma_f32_16x16x32_bf16 v[102:105], v[174:177], v[216:219], v[102:105]
	v_mfma_f32_16x16x32_bf16 v[98:101], v[182:185], v[216:219], v[98:101]
	v_mfma_f32_16x16x32_bf16 v[86:89], v[174:177], v[224:227], v[86:89]
	v_mfma_f32_16x16x32_bf16 v[82:85], v[182:185], v[224:227], v[82:85]
	v_mfma_f32_16x16x32_bf16 v[70:73], v[174:177], v[232:235], v[70:73]
	v_mfma_f32_16x16x32_bf16 v[66:69], v[182:185], v[232:235], v[66:69]
	s_setprio 0
	s_setprio 1
	v_mfma_f32_16x16x32_bf16 v[118:121], v[178:181], v[212:215], v[118:121]
	v_mfma_f32_16x16x32_bf16 v[114:117], v[204:207], v[212:215], v[114:117]
	v_mfma_f32_16x16x32_bf16 v[102:105], v[178:181], v[220:223], v[102:105]
	v_mfma_f32_16x16x32_bf16 v[98:101], v[204:207], v[220:223], v[98:101]
	v_mfma_f32_16x16x32_bf16 v[86:89], v[178:181], v[228:231], v[86:89]
	v_mfma_f32_16x16x32_bf16 v[82:85], v[204:207], v[228:231], v[82:85]
	v_mfma_f32_16x16x32_bf16 v[70:73], v[178:181], v[236:239], v[70:73]
	v_mfma_f32_16x16x32_bf16 v[66:69], v[204:207], v[236:239], v[66:69]
	s_setprio 0
	s_barrier
	s_add_i32 s47, s47, s4
	v_lshl_add_u64 v[186:187], s[40:41], 0, v[148:149]
	s_mov_b32 m0, s47
	ds_read_b128 v[208:211], v161 offset:16384
	ds_read_b128 v[212:215], v161 offset:17408
	ds_read_b128 v[216:219], v161 offset:18432
	ds_read_b128 v[220:223], v161 offset:19456
	ds_read_b128 v[224:227], v161 offset:20480
	ds_read_b128 v[228:231], v161 offset:21504
	ds_read_b128 v[232:235], v161 offset:22528
	ds_read_b128 v[236:239], v161 offset:23552
	global_load_lds_dwordx4 v[186:187], off
	s_add_i32 m0, s47, 0x2000
	s_add_u32 s76, s40, 0x80000
	v_lshl_add_u64 v[240:241], s[40:41], 0, v[144:145]
	s_addc_u32 s77, s41, 0
	s_add_i32 s47, s80, s4
	global_load_lds_dwordx4 v[240:241], off
	v_lshl_add_u64 v[242:243], s[76:77], 0, v[148:149]
	s_mov_b32 m0, s47
	v_lshl_add_u64 v[244:245], s[58:59], 0, v[146:147]
	global_load_lds_dwordx4 v[242:243], off
	v_lshl_add_u64 v[242:243], s[76:77], 0, v[144:145]
	s_add_i32 m0, s47, 0x2000
	s_nop 0
	global_load_lds_dwordx4 v[242:243], off
	v_lshl_add_u64 v[242:243], s[58:59], 0, v[150:151]
	s_mov_b32 m0, s5
	s_nop 0
	global_load_lds_dwordx4 v[242:243], off
	s_mov_b32 m0, s30
	s_nop 0
	global_load_lds_dwordx4 v[244:245], off
	s_waitcnt vmcnt(8)
	s_waitcnt lgkmcnt(0)
	s_setprio 1
	s_barrier
	v_mfma_f32_16x16x32_bf16 v[62:65], v[156:159], v[208:211], v[62:65]
	v_mfma_f32_16x16x32_bf16 v[58:61], v[166:169], v[208:211], v[58:61]
	v_mfma_f32_16x16x32_bf16 v[46:49], v[156:159], v[216:219], v[46:49]
	v_mfma_f32_16x16x32_bf16 v[42:45], v[166:169], v[216:219], v[42:45]
	v_mfma_f32_16x16x32_bf16 v[30:33], v[156:159], v[224:227], v[30:33]
	v_mfma_f32_16x16x32_bf16 v[26:29], v[166:169], v[224:227], v[26:29]
	v_mfma_f32_16x16x32_bf16 v[14:17], v[156:159], v[232:235], v[14:17]
	v_mfma_f32_16x16x32_bf16 v[10:13], v[166:169], v[232:235], v[10:13]
	v_mfma_f32_16x16x32_bf16 v[62:65], v[162:165], v[212:215], v[62:65]
	v_mfma_f32_16x16x32_bf16 v[58:61], v[170:173], v[212:215], v[58:61]
	v_mfma_f32_16x16x32_bf16 v[46:49], v[162:165], v[220:223], v[46:49]
	v_mfma_f32_16x16x32_bf16 v[42:45], v[170:173], v[220:223], v[42:45]
	v_mfma_f32_16x16x32_bf16 v[30:33], v[162:165], v[228:231], v[30:33]
	v_mfma_f32_16x16x32_bf16 v[26:29], v[170:173], v[228:231], v[26:29]
	v_mfma_f32_16x16x32_bf16 v[14:17], v[162:165], v[236:239], v[14:17]
	v_mfma_f32_16x16x32_bf16 v[10:13], v[170:173], v[236:239], v[10:13]
	v_mfma_f32_16x16x32_bf16 v[54:57], v[174:177], v[208:211], v[54:57]
	v_mfma_f32_16x16x32_bf16 v[50:53], v[182:185], v[208:211], v[50:53]
	v_mfma_f32_16x16x32_bf16 v[38:41], v[174:177], v[216:219], v[38:41]
	v_mfma_f32_16x16x32_bf16 v[34:37], v[182:185], v[216:219], v[34:37]
	v_mfma_f32_16x16x32_bf16 v[22:25], v[174:177], v[224:227], v[22:25]
	v_mfma_f32_16x16x32_bf16 v[18:21], v[182:185], v[224:227], v[18:21]
	v_mfma_f32_16x16x32_bf16 v[6:9], v[174:177], v[232:235], v[6:9]
	v_mfma_f32_16x16x32_bf16 v[2:5], v[182:185], v[232:235], v[2:5]
	v_mfma_f32_16x16x32_bf16 v[54:57], v[178:181], v[212:215], v[54:57]
	v_mfma_f32_16x16x32_bf16 v[50:53], v[204:207], v[212:215], v[50:53]
	v_mfma_f32_16x16x32_bf16 v[38:41], v[178:181], v[220:223], v[38:41]
	v_mfma_f32_16x16x32_bf16 v[34:37], v[204:207], v[220:223], v[34:37]
	v_mfma_f32_16x16x32_bf16 v[22:25], v[178:181], v[228:231], v[22:25]
	v_mfma_f32_16x16x32_bf16 v[18:21], v[204:207], v[228:231], v[18:21]
	v_mfma_f32_16x16x32_bf16 v[6:9], v[178:181], v[236:239], v[6:9]
	v_mfma_f32_16x16x32_bf16 v[2:5], v[204:207], v[236:239], v[2:5]
	s_setprio 0
	s_barrier
; #define PG8_STAGE(bufoff, gbase, voff) do { _Pragma("unroll") for (int _i = 0; _i < 2; ++_i) \
;         __builtin_amdgcn_global_load_lds((const unsigned*)((const char*)(gbase) + (voff)[_i]), (PG8_LAS unsigned*)(lds + (bufoff) + ldsw + _i * 8192), 16, 0, 0); } while (0)
; #define PG8_LDA(dst, b, h) do { _Pragma("unroll") for (int m = 0; m < 4; ++m) _Pragma("unroll") for (int k = 0; k < 2; ++k) dst[m][k] = *(const PG8_LAS bf16x8*)(lds + PG8_SA(b, h) + aoff + m * 2048 + k * 1024); } while (0)
; #define PG8_LDB(dst, b, h) do { _Pragma("unroll") for (int n = 0; n < 2; ++n) _Pragma("unroll") for (int k = 0; k < 2; ++k) dst[n][k] = *(const PG8_LAS bf16x8*)(lds + PG8_SB(b, h) + boff + n * 2048 + k * 1024); } while (0)
; #define PG8_MMA(ai, bj, At, Bt) do { __builtin_amdgcn_s_setprio(1); _Pragma("unroll") for (int m = 0; m < 4; ++m) _Pragma("unroll") for (int n = 0; n < 2; ++n) _Pragma("unroll") for (int k = 0; k < 2; ++k) \
;         acc[ai][bj][m][n] = __builtin_amdgcn_mfma_f32_16x16x32_bf16(Bt[n][k], At[m][k], acc[ai][bj][m][n], 0, 0, 0); __builtin_amdgcn_s_setprio(0); } while (0)
; #define PG8_WAIT_V(n) asm volatile("s_waitcnt vmcnt(" #n ")" ::: "memory")
; #define PG8_WAIT_L(n) asm volatile("s_waitcnt lgkmcnt(" #n ")" ::: "memory")
; #define PG8_BAR __builtin_amdgcn_s_barrier()
; #define PG8_SCHED __builtin_amdgcn_sched_barrier(0)
; template <class Epi, class Sched, bool ALIGN_EPI = false, bool SP2 = false>
; __device__ __forceinline__ void gemm_phase(PG8_LAS unsigned char* lds, const Gemm g, const Sched& S, const Epi& E) {
;     ...
;             PG8_LDB(B0, 1, 0); PG8_LDB(B1, 1, 1); PG8_SCHED; PG8_LDA(At, 1, 0); PG8_STAGE(PG8_SA(0, 1), a2 + hstep, voffA);
;             PG8_WAIT_V(8); PG8_WAIT_L(0); PG8_BAR; PG8_MMA(0, 0, At, B0); PG8_MMA(0, 1, At, B1); PG8_BAR; PG8_SCHED;
;             PG8_LDA(At, 1, 1); PG8_STAGE(PG8_SB(1, 0), b3, voffB); PG8_STAGE(PG8_SB(1, 1), b3 + hstep, voffB); PG8_STAGE(PG8_SA(1, 0), a3, voffA);
	s_add_i32 s47, 0, 0x18000
	s_add_i32 s76, 0, 0x1c000
	v_add_u32_e32 v170, s47, v143
	v_add_u32_e32 v203, s76, v143
	ds_read_b128 v[156:159], v170
	ds_read_b128 v[162:165], v170 offset:1024
	ds_read_b128 v[166:169], v170 offset:2048
	ds_read_b128 v[170:173], v170 offset:3072
	ds_read_b128 v[174:177], v203
	ds_read_b128 v[178:181], v203 offset:1024
	ds_read_b128 v[182:185], v203 offset:2048
	ds_read_b128 v[204:207], v203 offset:3072
	s_add_u32 s58, s58, 0x80000
	s_addc_u32 s59, s59, 0
	s_mov_b32 m0, s34
	v_lshl_add_u64 v[246:247], s[58:59], 0, v[150:151]
	ds_read_b128 v[208:211], v161 offset:32768
	ds_read_b128 v[212:215], v161 offset:33792
	ds_read_b128 v[216:219], v161 offset:34816
	ds_read_b128 v[220:223], v161 offset:35840
	ds_read_b128 v[224:227], v161 offset:36864
	ds_read_b128 v[228:231], v161 offset:37888
	ds_read_b128 v[232:235], v161 offset:38912
	ds_read_b128 v[236:239], v161 offset:39936
	global_load_lds_dwordx4 v[246:247], off
	v_lshl_add_u64 v[246:247], s[58:59], 0, v[146:147]
	s_mov_b32 m0, s57
	s_nop 0
	global_load_lds_dwordx4 v[246:247], off
	s_waitcnt vmcnt(8)
	s_waitcnt lgkmcnt(0)
	s_setprio 1
	s_barrier
	v_mfma_f32_16x16x32_bf16 v[126:129], v[156:159], v[208:211], v[126:129]
	v_mfma_f32_16x16x32_bf16 v[122:125], v[166:169], v[208:211], v[122:125]
	v_mfma_f32_16x16x32_bf16 v[110:113], v[156:159], v[216:219], v[110:113]
	v_mfma_f32_16x16x32_bf16 v[106:109], v[166:169], v[216:219], v[106:109]
	v_mfma_f32_16x16x32_bf16 v[94:97], v[156:159], v[224:227], v[94:97]
	v_mfma_f32_16x16x32_bf16 v[90:93], v[166:169], v[224:227], v[90:93]
	v_mfma_f32_16x16x32_bf16 v[78:81], v[156:159], v[232:235], v[78:81]
	v_mfma_f32_16x16x32_bf16 v[74:77], v[166:169], v[232:235], v[74:77]
	s_setprio 0
	s_setprio 1
	v_mfma_f32_16x16x32_bf16 v[126:129], v[162:165], v[212:215], v[126:129]
	v_mfma_f32_16x16x32_bf16 v[122:125], v[170:173], v[212:215], v[122:125]
	v_mfma_f32_16x16x32_bf16 v[110:113], v[162:165], v[220:223], v[110:113]
	v_mfma_f32_16x16x32_bf16 v[106:109], v[170:173], v[220:223], v[106:109]
	v_mfma_f32_16x16x32_bf16 v[94:97], v[162:165], v[228:231], v[94:97]
	v_mfma_f32_16x16x32_bf16 v[90:93], v[170:173], v[228:231], v[90:93]
	v_mfma_f32_16x16x32_bf16 v[78:81], v[162:165], v[236:239], v[78:81]
	v_mfma_f32_16x16x32_bf16 v[74:77], v[170:173], v[236:239], v[74:77]
	s_setprio 0
	s_setprio 1
	v_mfma_f32_16x16x32_bf16 v[118:121], v[174:177], v[208:211], v[118:121]
	v_mfma_f32_16x16x32_bf16 v[114:117], v[182:185], v[208:211], v[114:117]
	v_mfma_f32_16x16x32_bf16 v[102:105], v[174:177], v[216:219], v[102:105]
	v_mfma_f32_16x16x32_bf16 v[98:101], v[182:185], v[216:219], v[98:101]
	v_mfma_f32_16x16x32_bf16 v[86:89], v[174:177], v[224:227], v[86:89]
	v_mfma_f32_16x16x32_bf16 v[82:85], v[182:185], v[224:227], v[82:85]
	v_mfma_f32_16x16x32_bf16 v[70:73], v[174:177], v[232:235], v[70:73]
	v_mfma_f32_16x16x32_bf16 v[66:69], v[182:185], v[232:235], v[66:69]
	s_setprio 0
	s_setprio 1
	v_mfma_f32_16x16x32_bf16 v[118:121], v[178:181], v[212:215], v[118:121]
	v_mfma_f32_16x16x32_bf16 v[114:117], v[204:207], v[212:215], v[114:117]
	v_mfma_f32_16x16x32_bf16 v[102:105], v[178:181], v[220:223], v[102:105]
	v_mfma_f32_16x16x32_bf16 v[98:101], v[204:207], v[220:223], v[98:101]
	v_mfma_f32_16x16x32_bf16 v[86:89], v[178:181], v[228:231], v[86:89]
	v_mfma_f32_16x16x32_bf16 v[82:85], v[204:207], v[228:231], v[82:85]
	v_mfma_f32_16x16x32_bf16 v[70:73], v[178:181], v[236:239], v[70:73]
	v_mfma_f32_16x16x32_bf16 v[66:69], v[204:207], v[236:239], v[66:69]
	s_setprio 0
	s_barrier
	s_add_i32 s47, s47, s4
	v_lshl_add_u64 v[186:187], v[186:187], 0, s[68:69]
	s_mov_b32 m0, s47
	ds_read_b128 v[208:211], v161 offset:49152
	ds_read_b128 v[212:215], v161 offset:50176
	ds_read_b128 v[216:219], v161 offset:51200
	ds_read_b128 v[220:223], v161 offset:52224
	ds_read_b128 v[224:227], v161 offset:53248
	ds_read_b128 v[228:231], v161 offset:54272
	ds_read_b128 v[232:235], v161 offset:55296
	ds_read_b128 v[236:239], v161 offset:56320
	global_load_lds_dwordx4 v[186:187], off
	s_add_i32 m0, s47, 0x2000
	s_add_u32 s40, s40, 0x80080
	v_lshl_add_u64 v[186:187], v[240:241], 0, s[68:69]
	s_addc_u32 s41, s41, 0
	s_add_i32 s47, s76, s4
	global_load_lds_dwordx4 v[186:187], off
	v_lshl_add_u64 v[186:187], s[40:41], 0, v[148:149]
	s_mov_b32 m0, s47
	s_nop 0
	global_load_lds_dwordx4 v[186:187], off
	v_lshl_add_u64 v[186:187], s[40:41], 0, v[144:145]
	s_add_i32 m0, s47, 0x2000
	s_nop 0
	global_load_lds_dwordx4 v[186:187], off
	v_lshl_add_u64 v[186:187], v[242:243], 0, s[68:69]
	s_mov_b32 m0, s67
	s_nop 0
	global_load_lds_dwordx4 v[186:187], off
	v_lshl_add_u64 v[186:187], v[244:245], 0, s[68:69]
	s_mov_b32 m0, s28
	s_nop 0
	global_load_lds_dwordx4 v[186:187], off
	s_nop 0
	s_waitcnt vmcnt(8)
	s_waitcnt lgkmcnt(0)
	s_setprio 1
	s_barrier
; #define PG8_STAGE(bufoff, gbase, voff) do { _Pragma("unroll") for (int _i = 0; _i < 2; ++_i) \
;         __builtin_amdgcn_global_load_lds((const unsigned*)((const char*)(gbase) + (voff)[_i]), (PG8_LAS unsigned*)(lds + (bufoff) + ldsw + _i * 8192), 16, 0, 0); } while (0)
; #define PG8_LDA(dst, b, h) do { _Pragma("unroll") for (int m = 0; m < 4; ++m) _Pragma("unroll") for (int k = 0; k < 2; ++k) dst[m][k] = *(const PG8_LAS bf16x8*)(lds + PG8_SA(b, h) + aoff + m * 2048 + k * 1024); } while (0)
; #define PG8_MMA(ai, bj, At, Bt) do { __builtin_amdgcn_s_setprio(1); _Pragma("unroll") for (int m = 0; m < 4; ++m) _Pragma("unroll") for (int n = 0; n < 2; ++n) _Pragma("unroll") for (int k = 0; k < 2; ++k) \
;         acc[ai][bj][m][n] = __builtin_amdgcn_mfma_f32_16x16x32_bf16(Bt[n][k], At[m][k], acc[ai][bj][m][n], 0, 0, 0); __builtin_amdgcn_s_setprio(0); } while (0)
; #define PG8_WAIT_V(n) asm volatile("s_waitcnt vmcnt(" #n ")" ::: "memory")
; #define PG8_WAIT_L(n) asm volatile("s_waitcnt lgkmcnt(" #n ")" ::: "memory")
; #define PG8_BAR __builtin_amdgcn_s_barrier()
; #define PG8_SCHED __builtin_amdgcn_sched_barrier(0)
;     __device__ __forceinline__ void operator()(const f32x4 (&acc)[2][2][4][2], const Unit& u, int wr, int wc, int fr, int fq) const {
;         const int row0 = u.pm * BM + wr * 64 + fr, col0 = u.pn * BM + wc * 32 + 8 * fq;
; #pragma unroll
;         for (int ai = 0; ai < 2; ++ai)
; #pragma unroll
;             for (int m = 0; m < 4; ++m) { const size_t row = (size_t)(row0 + ai * HALF + m * 16); float ss = 0.f;
; #pragma unroll
;                 for (int bj = 0; bj < 2; ++bj) { const size_t off = row * DM + col0 + bj * HALF;
;                     f32x4 v0 = acc[ai][bj][m][0] + *(const f32x4*)(base + off), v1 = acc[ai][bj][m][1] + *(const f32x4*)(base + off + 4);
; template <class Epi, class Sched, bool ALIGN_EPI = false, bool SP2 = false>
; __device__ __forceinline__ void gemm_phase(PG8_LAS unsigned char* lds, const Gemm g, const Sched& S, const Epi& E) {
;     ...
;             PG8_LDA(At, 1, 1); PG8_STAGE(PG8_SB(1, 0), b3, voffB); PG8_STAGE(PG8_SB(1, 1), b3 + hstep, voffB); PG8_STAGE(PG8_SA(1, 0), a3, voffA);
;             PG8_WAIT_V(8); PG8_WAIT_L(0); PG8_BAR; PG8_MMA(1, 0, At, B0); PG8_MMA(1, 1, At, B1); PG8_BAR; PG8_SCHED;
	v_mfma_f32_16x16x32_bf16 v[62:65], v[156:159], v[208:211], v[62:65]
	v_mfma_f32_16x16x32_bf16 v[58:61], v[166:169], v[208:211], v[58:61]
	v_mfma_f32_16x16x32_bf16 v[46:49], v[156:159], v[216:219], v[46:49]
	v_mfma_f32_16x16x32_bf16 v[42:45], v[166:169], v[216:219], v[42:45]
	v_mfma_f32_16x16x32_bf16 v[30:33], v[156:159], v[224:227], v[30:33]
	v_mfma_f32_16x16x32_bf16 v[26:29], v[166:169], v[224:227], v[26:29]
	v_mfma_f32_16x16x32_bf16 v[14:17], v[156:159], v[232:235], v[14:17]
	v_mfma_f32_16x16x32_bf16 v[10:13], v[166:169], v[232:235], v[10:13]
	v_mfma_f32_16x16x32_bf16 v[62:65], v[162:165], v[212:215], v[62:65]
	v_mfma_f32_16x16x32_bf16 v[58:61], v[170:173], v[212:215], v[58:61]
	v_mfma_f32_16x16x32_bf16 v[46:49], v[162:165], v[220:223], v[46:49]
	v_mfma_f32_16x16x32_bf16 v[42:45], v[170:173], v[220:223], v[42:45]
	v_mfma_f32_16x16x32_bf16 v[30:33], v[162:165], v[228:231], v[30:33]
	v_mfma_f32_16x16x32_bf16 v[26:29], v[170:173], v[228:231], v[26:29]
	v_mfma_f32_16x16x32_bf16 v[14:17], v[162:165], v[236:239], v[14:17]
	v_mfma_f32_16x16x32_bf16 v[10:13], v[170:173], v[236:239], v[10:13]
	v_mfma_f32_16x16x32_bf16 v[54:57], v[174:177], v[208:211], v[54:57]
	v_mfma_f32_16x16x32_bf16 v[50:53], v[182:185], v[208:211], v[50:53]
	v_mfma_f32_16x16x32_bf16 v[38:41], v[174:177], v[216:219], v[38:41]
	v_mfma_f32_16x16x32_bf16 v[34:37], v[182:185], v[216:219], v[34:37]
	v_mfma_f32_16x16x32_bf16 v[22:25], v[174:177], v[224:227], v[22:25]
	v_mfma_f32_16x16x32_bf16 v[18:21], v[182:185], v[224:227], v[18:21]
	v_mfma_f32_16x16x32_bf16 v[6:9], v[174:177], v[232:235], v[6:9]
	v_mfma_f32_16x16x32_bf16 v[2:5], v[182:185], v[232:235], v[2:5]
	v_mfma_f32_16x16x32_bf16 v[54:57], v[178:181], v[212:215], v[54:57]
	v_mfma_f32_16x16x32_bf16 v[50:53], v[204:207], v[212:215], v[50:53]
	v_mfma_f32_16x16x32_bf16 v[38:41], v[178:181], v[220:223], v[38:41]
	v_mfma_f32_16x16x32_bf16 v[34:37], v[204:207], v[220:223], v[34:37]
	v_mfma_f32_16x16x32_bf16 v[22:25], v[178:181], v[228:231], v[22:25]
	v_mfma_f32_16x16x32_bf16 v[18:21], v[204:207], v[228:231], v[18:21]
	v_mfma_f32_16x16x32_bf16 v[6:9], v[178:181], v[236:239], v[6:9]
	v_mfma_f32_16x16x32_bf16 v[2:5], v[204:207], v[236:239], v[2:5]
	s_setprio 0
	s_barrier
	s_add_i32 s46, s46, 2
	s_add_u32 vcc_lo, vcc_lo, 0x100
	s_addc_u32 vcc_hi, vcc_hi, 0
	s_add_u32 s78, s78, 0x100
	s_addc_u32 s79, s79, 0
	s_cmp_gt_u32 s46, 29
	s_cbranch_scc0 .LBB0_98
	v_lshl_add_u32 v156, s73, 8, v1
	v_lshl_or_b32 v157, s54, 8, v160
	v_lshl_add_u32 v157, v156, 11, v157
	v_mov_b32_e32 v247, 0
	v_lshlrev_b32_e32 v246, 2, v157
	v_lshl_add_u64 v[162:163], s[8:9], 0, v[246:247]
	v_lshlrev_b32_e32 v246, 1, v157
	v_lshl_add_u64 v[244:245], s[70:71], 0, v[246:247]
	s_mov_b32 s41, 0
	global_load_dwordx4 v[164:167], v[162:163], off
	global_load_dwordx4 v[168:171], v[162:163], off offset:16
	global_load_dwordx4 v[172:175], v[162:163], off offset:512
	global_load_dwordx4 v[176:179], v[162:163], off offset:528
	s_mov_b32 s40, 0x20000
	v_lshl_add_u64 v[246:247], v[162:163], 0, s[40:41]
	global_load_dwordx4 v[180:183], v[246:247], off
	global_load_dwordx4 v[184:187], v[246:247], off offset:16
	global_load_dwordx4 v[204:207], v[246:247], off offset:512
	global_load_dwordx4 v[208:211], v[246:247], off offset:528
	s_mov_b32 s40, 0x40000
	v_lshl_add_u64 v[246:247], v[162:163], 0, s[40:41]
	global_load_dwordx4 v[212:215], v[246:247], off
	global_load_dwordx4 v[216:219], v[246:247], off offset:16
	global_load_dwordx4 v[220:223], v[246:247], off offset:512
	global_load_dwordx4 v[224:227], v[246:247], off offset:528
	s_mov_b32 s40, 0x60000
	v_lshl_add_u64 v[246:247], v[162:163], 0, s[40:41]
	global_load_dwordx4 v[228:231], v[246:247], off
	global_load_dwordx4 v[232:235], v[246:247], off offset:16
	global_load_dwordx4 v[236:239], v[246:247], off offset:512
	global_load_dwordx4 v[240:243], v[246:247], off offset:528
	s_and_b64 vcc, exec, s[36:37]
	s_cbranch_vccz .Lx1_nobar
	s_barrier

; #define PG8_STAGE(bufoff, gbase, voff) do { _Pragma("unroll") for (int _i = 0; _i < 2; ++_i) \
;         __builtin_amdgcn_global_load_lds((const unsigned*)((const char*)(gbase) + (voff)[_i]), (PG8_LAS unsigned*)(lds + (bufoff) + ldsw + _i * 8192), 16, 0, 0); } while (0)
; #define PG8_LDA(dst, b, h) do { _Pragma("unroll") for (int m = 0; m < 4; ++m) _Pragma("unroll") for (int k = 0; k < 2; ++k) dst[m][k] = *(const PG8_LAS bf16x8*)(lds + PG8_SA(b, h) + aoff + m * 2048 + k * 1024); } while (0)
; #define PG8_LDB(dst, b, h) do { _Pragma("unroll") for (int n = 0; n < 2; ++n) _Pragma("unroll") for (int k = 0; k < 2; ++k) dst[n][k] = *(const PG8_LAS bf16x8*)(lds + PG8_SB(b, h) + boff + n * 2048 + k * 1024); } while (0)
; #define PG8_WAIT_V(n) asm volatile("s_waitcnt vmcnt(" #n ")" ::: "memory")
; #define PG8_WAIT_L(n) asm volatile("s_waitcnt lgkmcnt(" #n ")" ::: "memory")
; #define PG8_BAR __builtin_amdgcn_s_barrier()
; #define PG8_SCHED __builtin_amdgcn_sched_barrier(0)
; template <class Epi, class Sched, bool ALIGN_EPI = false, bool SP2 = false>
; __device__ __forceinline__ void gemm_phase(PG8_LAS unsigned char* lds, const Gemm g, const Sched& S, const Epi& E) {
;     ...
;         const bool has_next = S.next(ui + 1, nxt);
;         const char* nA = has_next ? (const char*)g.A + (size_t)nxt.pm * tstep : cA; const char* nB = has_next ? (const char*)g.Bt + (size_t)nxt.pn * tstep : cB;
;         for (int t = 0; t < nt; t += 2) {
;             const bool last = (t == nt - 2);
;             const char* a1 = cA + (size_t)(t + 1) * kstep;
;             const char* a2 = last ? nA : cA + (size_t)(t + 2) * kstep; const char* b2 = last ? nB : cB + (size_t)(t + 2) * kstep;
;             const char* a3 = a2 + kstep; const char* b3 = b2 + kstep;
;             if (last && has_next) S.a_ready(nxt);
;             if constexpr (SP2) {
;             PG8_LDB(B0, 0, 0); PG8_LDB(B1, 0, 1); PG8_SCHED; PG8_LDA(At, 0, 0); PG8_STAGE(PG8_SA(1, 1), a1 + hstep, voffA);
;             PG8_WAIT_V(8); PG8_WAIT_L(0); PG8_BAR; PG8_MMA(0, 0, At, B0); PG8_MMA(0, 1, At, B1); PG8_BAR; PG8_SCHED;
;             PG8_LDA(At, 0, 1); PG8_STAGE(PG8_SB(0, 0), b2, voffB); PG8_STAGE(PG8_SB(0, 1), b2 + hstep, voffB); PG8_STAGE(PG8_SA(0, 0), a2, voffA);
;             PG8_WAIT_V(8); PG8_WAIT_L(0); PG8_BAR; PG8_MMA(1, 0, At, B0); PG8_MMA(1, 1, At, B1); PG8_BAR; PG8_SCHED;
.LBB0_135:
	s_ashr_i32 s37, s36, 31
	s_lshl_b64 s[40:41], s[36:37], 18
	v_readlane_b32 s44, v254, 59
	v_readlane_b32 s45, v254, 60
	s_add_u32 s40, s44, s40
	s_addc_u32 s41, s45, s41
	s_and_b64 s[44:45], s[42:43], exec
	s_cselect_b32 s37, s41, s19
	s_cselect_b32 s73, s40, s18
	s_ashr_i32 s11, s10, 31
	s_lshl_b64 s[44:45], s[10:11], 18
	v_readlane_b32 s46, v254, 41
	v_readlane_b32 s47, v254, 42
	s_add_u32 s44, s46, s44
	s_addc_u32 s45, s47, s45
	s_and_b64 s[46:47], s[42:43], exec
	s_cselect_b32 s11, s45, s63
	s_cselect_b32 s84, s44, s62
	s_add_u32 s58, s18, 0x20080
	s_addc_u32 s59, s19, 0
	s_add_u32 s85, s62, 0x100
	s_addc_u32 s78, s63, 0
	s_mov_b32 s79, -2
	s_waitcnt vmcnt(0)
	s_add_u32 s18, s58, 0xfffe0080
	s_addc_u32 s19, s59, -1
	s_add_i32 s46, 0, 0x10000
	s_cmp_eq_u32 s79, 4
	s_cselect_b32 s63, s37, s19
	s_cselect_b32 s62, s73, s18
	s_cselect_b32 s19, s11, s78
	s_cselect_b32 s18, s84, s85
	s_add_i32 s76, 0, 0x14000
	v_add_u32_e32 v172, s46, v1
	v_add_u32_e32 v203, s76, v1
	ds_read_b128 v[160:163], v172
	ds_read_b128 v[164:167], v172 offset:1024
	ds_read_b128 v[168:171], v172 offset:2048
	ds_read_b128 v[172:175], v172 offset:3072
	ds_read_b128 v[176:179], v203
	ds_read_b128 v[180:183], v203 offset:1024
	ds_read_b128 v[184:187], v203 offset:2048
	ds_read_b128 v[204:207], v203 offset:3072
	v_lshl_add_u64 v[240:241], s[58:59], 0, v[156:157]
	s_add_i32 m0, s5, 0xc000
	ds_read_b128 v[208:211], v143
	ds_read_b128 v[212:215], v143 offset:1024
	ds_read_b128 v[216:219], v143 offset:2048
	ds_read_b128 v[220:223], v143 offset:3072
	ds_read_b128 v[224:227], v143 offset:4096
	ds_read_b128 v[228:231], v143 offset:5120
	ds_read_b128 v[232:235], v143 offset:6144
	ds_read_b128 v[236:239], v143 offset:7168
	global_load_lds_dwordx4 v[240:241], off
	v_lshl_add_u64 v[240:241], s[58:59], 0, v[158:159]
	s_add_i32 m0, s5, 0xe000
	s_nop 0
	global_load_lds_dwordx4 v[240:241], off
	s_nop 0
	s_waitcnt vmcnt(8)
	s_waitcnt lgkmcnt(0)
	s_setprio 1
	s_barrier
	v_mfma_f32_16x16x32_bf16 v[126:129], v[160:163], v[208:211], 0
	v_mfma_f32_16x16x32_bf16 v[122:125], v[168:171], v[208:211], 0
	v_mfma_f32_16x16x32_bf16 v[110:113], v[160:163], v[216:219], 0
	v_mfma_f32_16x16x32_bf16 v[106:109], v[168:171], v[216:219], 0
	v_mfma_f32_16x16x32_bf16 v[94:97], v[160:163], v[224:227], 0
	v_mfma_f32_16x16x32_bf16 v[90:93], v[168:171], v[224:227], 0
	v_mfma_f32_16x16x32_bf16 v[78:81], v[160:163], v[232:235], 0
	v_mfma_f32_16x16x32_bf16 v[74:77], v[168:171], v[232:235], 0
	s_setprio 0
	s_setprio 1
	v_mfma_f32_16x16x32_bf16 v[126:129], v[164:167], v[212:215], v[126:129]
	v_mfma_f32_16x16x32_bf16 v[122:125], v[172:175], v[212:215], v[122:125]
	v_mfma_f32_16x16x32_bf16 v[110:113], v[164:167], v[220:223], v[110:113]
	v_mfma_f32_16x16x32_bf16 v[106:109], v[172:175], v[220:223], v[106:109]
	v_mfma_f32_16x16x32_bf16 v[94:97], v[164:167], v[228:231], v[94:97]
	v_mfma_f32_16x16x32_bf16 v[90:93], v[172:175], v[228:231], v[90:93]
	v_mfma_f32_16x16x32_bf16 v[78:81], v[164:167], v[236:239], v[78:81]
	v_mfma_f32_16x16x32_bf16 v[74:77], v[172:175], v[236:239], v[74:77]
	s_setprio 0
	s_setprio 1
	v_mfma_f32_16x16x32_bf16 v[118:121], v[176:179], v[208:211], 0
	v_mfma_f32_16x16x32_bf16 v[114:117], v[184:187], v[208:211], 0
	v_mfma_f32_16x16x32_bf16 v[102:105], v[176:179], v[216:219], 0
	v_mfma_f32_16x16x32_bf16 v[98:101], v[184:187], v[216:219], 0
	v_mfma_f32_16x16x32_bf16 v[86:89], v[176:179], v[224:227], 0
	v_mfma_f32_16x16x32_bf16 v[82:85], v[184:187], v[224:227], 0
	v_mfma_f32_16x16x32_bf16 v[70:73], v[176:179], v[232:235], 0
	v_mfma_f32_16x16x32_bf16 v[66:69], v[184:187], v[232:235], 0
	s_setprio 0
	s_setprio 1
	v_mfma_f32_16x16x32_bf16 v[118:121], v[180:183], v[212:215], v[118:121]
	v_mfma_f32_16x16x32_bf16 v[114:117], v[204:207], v[212:215], v[114:117]
	v_mfma_f32_16x16x32_bf16 v[102:105], v[180:183], v[220:223], v[102:105]
	v_mfma_f32_16x16x32_bf16 v[98:101], v[204:207], v[220:223], v[98:101]
	v_mfma_f32_16x16x32_bf16 v[86:89], v[180:183], v[228:231], v[86:89]
	v_mfma_f32_16x16x32_bf16 v[82:85], v[204:207], v[228:231], v[82:85]
	v_mfma_f32_16x16x32_bf16 v[70:73], v[180:183], v[236:239], v[70:73]
	v_mfma_f32_16x16x32_bf16 v[66:69], v[204:207], v[236:239], v[66:69]
	s_setprio 0
	s_barrier
	s_add_i32 s46, s46, s4
	v_lshl_add_u64 v[240:241], s[18:19], 0, v[148:149]
	s_mov_b32 m0, s46
	ds_read_b128 v[208:211], v143 offset:16384
	ds_read_b128 v[212:215], v143 offset:17408
	ds_read_b128 v[216:219], v143 offset:18432
	ds_read_b128 v[220:223], v143 offset:19456
	ds_read_b128 v[224:227], v143 offset:20480
	ds_read_b128 v[228:231], v143 offset:21504
	ds_read_b128 v[232:235], v143 offset:22528
	ds_read_b128 v[236:239], v143 offset:23552
	global_load_lds_dwordx4 v[240:241], off
	s_add_i32 m0, s46, 0x2000
	s_add_u32 s46, s18, 0x20000
	v_lshl_add_u64 v[242:243], s[18:19], 0, v[144:145]
	s_addc_u32 s47, s19, 0
	s_add_i32 s76, s76, s4
	global_load_lds_dwordx4 v[242:243], off
	v_lshl_add_u64 v[244:245], s[46:47], 0, v[148:149]
	s_mov_b32 m0, s76
	v_lshl_add_u64 v[246:247], s[62:63], 0, v[146:147]
	global_load_lds_dwordx4 v[244:245], off
	v_lshl_add_u64 v[244:245], s[46:47], 0, v[144:145]
	s_add_i32 m0, s76, 0x2000
	s_nop 0
	global_load_lds_dwordx4 v[244:245], off
	v_lshl_add_u64 v[244:245], s[62:63], 0, v[150:151]
	s_mov_b32 m0, s5
	s_nop 0
	global_load_lds_dwordx4 v[244:245], off
	s_mov_b32 m0, s28
	s_nop 0
	global_load_lds_dwordx4 v[246:247], off
	s_waitcnt vmcnt(8)
	s_waitcnt lgkmcnt(0)
	s_setprio 1
	s_barrier
; #define PG8_STAGE(bufoff, gbase, voff) do { _Pragma("unroll") for (int _i = 0; _i < 2; ++_i) \
;         __builtin_amdgcn_global_load_lds((const unsigned*)((const char*)(gbase) + (voff)[_i]), (PG8_LAS unsigned*)(lds + (bufoff) + ldsw + _i * 8192), 16, 0, 0); } while (0)
; #define PG8_LDA(dst, b, h) do { _Pragma("unroll") for (int m = 0; m < 4; ++m) _Pragma("unroll") for (int k = 0; k < 2; ++k) dst[m][k] = *(const PG8_LAS bf16x8*)(lds + PG8_SA(b, h) + aoff + m * 2048 + k * 1024); } while (0)
; #define PG8_LDB(dst, b, h) do { _Pragma("unroll") for (int n = 0; n < 2; ++n) _Pragma("unroll") for (int k = 0; k < 2; ++k) dst[n][k] = *(const PG8_LAS bf16x8*)(lds + PG8_SB(b, h) + boff + n * 2048 + k * 1024); } while (0)
; #define PG8_MMA(ai, bj, At, Bt) do { __builtin_amdgcn_s_setprio(1); _Pragma("unroll") for (int m = 0; m < 4; ++m) _Pragma("unroll") for (int n = 0; n < 2; ++n) _Pragma("unroll") for (int k = 0; k < 2; ++k) \
;         acc[ai][bj][m][n] = __builtin_amdgcn_mfma_f32_16x16x32_bf16(Bt[n][k], At[m][k], acc[ai][bj][m][n], 0, 0, 0); __builtin_amdgcn_s_setprio(0); } while (0)
; #define PG8_WAIT_V(n) asm volatile("s_waitcnt vmcnt(" #n ")" ::: "memory")
; #define PG8_WAIT_L(n) asm volatile("s_waitcnt lgkmcnt(" #n ")" ::: "memory")
; #define PG8_BAR __builtin_amdgcn_s_barrier()
; #define PG8_SCHED __builtin_amdgcn_sched_barrier(0)
; template <class Epi, class Sched, bool ALIGN_EPI = false, bool SP2 = false>
; __device__ __forceinline__ void gemm_phase(PG8_LAS unsigned char* lds, const Gemm g, const Sched& S, const Epi& E) {
;     ...
;             PG8_WAIT_V(8); PG8_WAIT_L(0); PG8_BAR; PG8_MMA(1, 0, At, B0); PG8_MMA(1, 1, At, B1); PG8_BAR; PG8_SCHED;
;             PG8_LDB(B0, 1, 0); PG8_LDB(B1, 1, 1); PG8_SCHED; PG8_LDA(At, 1, 0); PG8_STAGE(PG8_SA(0, 1), a2 + hstep, voffA);
;             PG8_WAIT_V(8); PG8_WAIT_L(0); PG8_BAR; PG8_MMA(0, 0, At, B0); PG8_MMA(0, 1, At, B1); PG8_BAR; PG8_SCHED;
;             PG8_LDA(At, 1, 1); PG8_STAGE(PG8_SB(1, 0), b3, voffB); PG8_STAGE(PG8_SB(1, 1), b3 + hstep, voffB); PG8_STAGE(PG8_SA(1, 0), a3, voffA);
	v_mfma_f32_16x16x32_bf16 v[62:65], v[160:163], v[208:211], 0
	v_mfma_f32_16x16x32_bf16 v[58:61], v[168:171], v[208:211], 0
	v_mfma_f32_16x16x32_bf16 v[46:49], v[160:163], v[216:219], 0
	v_mfma_f32_16x16x32_bf16 v[42:45], v[168:171], v[216:219], 0
	v_mfma_f32_16x16x32_bf16 v[30:33], v[160:163], v[224:227], 0
	v_mfma_f32_16x16x32_bf16 v[26:29], v[168:171], v[224:227], 0
	v_mfma_f32_16x16x32_bf16 v[14:17], v[160:163], v[232:235], 0
	v_mfma_f32_16x16x32_bf16 v[10:13], v[168:171], v[232:235], 0
	v_mfma_f32_16x16x32_bf16 v[62:65], v[164:167], v[212:215], v[62:65]
	v_mfma_f32_16x16x32_bf16 v[58:61], v[172:175], v[212:215], v[58:61]
	v_mfma_f32_16x16x32_bf16 v[46:49], v[164:167], v[220:223], v[46:49]
	v_mfma_f32_16x16x32_bf16 v[42:45], v[172:175], v[220:223], v[42:45]
	v_mfma_f32_16x16x32_bf16 v[30:33], v[164:167], v[228:231], v[30:33]
	v_mfma_f32_16x16x32_bf16 v[26:29], v[172:175], v[228:231], v[26:29]
	v_mfma_f32_16x16x32_bf16 v[14:17], v[164:167], v[236:239], v[14:17]
	v_mfma_f32_16x16x32_bf16 v[10:13], v[172:175], v[236:239], v[10:13]
	v_mfma_f32_16x16x32_bf16 v[54:57], v[176:179], v[208:211], 0
	v_mfma_f32_16x16x32_bf16 v[50:53], v[184:187], v[208:211], 0
	v_mfma_f32_16x16x32_bf16 v[38:41], v[176:179], v[216:219], 0
	v_mfma_f32_16x16x32_bf16 v[34:37], v[184:187], v[216:219], 0
	v_mfma_f32_16x16x32_bf16 v[22:25], v[176:179], v[224:227], 0
	v_mfma_f32_16x16x32_bf16 v[18:21], v[184:187], v[224:227], 0
	v_mfma_f32_16x16x32_bf16 v[6:9], v[176:179], v[232:235], 0
	v_mfma_f32_16x16x32_bf16 v[2:5], v[184:187], v[232:235], 0
	v_mfma_f32_16x16x32_bf16 v[54:57], v[180:183], v[212:215], v[54:57]
	v_mfma_f32_16x16x32_bf16 v[50:53], v[204:207], v[212:215], v[50:53]
	v_mfma_f32_16x16x32_bf16 v[38:41], v[180:183], v[220:223], v[38:41]
	v_mfma_f32_16x16x32_bf16 v[34:37], v[204:207], v[220:223], v[34:37]
	v_mfma_f32_16x16x32_bf16 v[22:25], v[180:183], v[228:231], v[22:25]
	v_mfma_f32_16x16x32_bf16 v[18:21], v[204:207], v[228:231], v[18:21]
	v_mfma_f32_16x16x32_bf16 v[6:9], v[180:183], v[236:239], v[6:9]
	v_mfma_f32_16x16x32_bf16 v[2:5], v[204:207], v[236:239], v[2:5]
	s_setprio 0
	s_barrier
	s_add_i32 s76, 0, 0x18000
	s_add_i32 s77, 0, 0x1c000
	v_add_u32_e32 v172, s76, v1
	v_add_u32_e32 v203, s77, v1
	ds_read_b128 v[160:163], v172
	ds_read_b128 v[164:167], v172 offset:1024
	ds_read_b128 v[168:171], v172 offset:2048
	ds_read_b128 v[172:175], v172 offset:3072
	ds_read_b128 v[176:179], v203
	ds_read_b128 v[180:183], v203 offset:1024
	ds_read_b128 v[184:187], v203 offset:2048
	ds_read_b128 v[204:207], v203 offset:3072
	s_add_u32 s46, s62, 0x20000
	s_addc_u32 s47, s63, 0
	s_mov_b32 m0, s30
	v_lshl_add_u64 v[248:249], s[46:47], 0, v[150:151]
	ds_read_b128 v[208:211], v143 offset:32768
	ds_read_b128 v[212:215], v143 offset:33792
	ds_read_b128 v[216:219], v143 offset:34816
	ds_read_b128 v[220:223], v143 offset:35840
	ds_read_b128 v[224:227], v143 offset:36864
	ds_read_b128 v[228:231], v143 offset:37888
	ds_read_b128 v[232:235], v143 offset:38912
	ds_read_b128 v[236:239], v143 offset:39936
	global_load_lds_dwordx4 v[248:249], off
	v_lshl_add_u64 v[248:249], s[46:47], 0, v[146:147]
	s_mov_b32 m0, s34
	s_nop 0
	global_load_lds_dwordx4 v[248:249], off
	s_waitcnt vmcnt(8)
	s_waitcnt lgkmcnt(0)
	s_setprio 1
	s_barrier
	v_mfma_f32_16x16x32_bf16 v[126:129], v[160:163], v[208:211], v[126:129]
	v_mfma_f32_16x16x32_bf16 v[122:125], v[168:171], v[208:211], v[122:125]
	v_mfma_f32_16x16x32_bf16 v[110:113], v[160:163], v[216:219], v[110:113]
	v_mfma_f32_16x16x32_bf16 v[106:109], v[168:171], v[216:219], v[106:109]
	v_mfma_f32_16x16x32_bf16 v[94:97], v[160:163], v[224:227], v[94:97]
	v_mfma_f32_16x16x32_bf16 v[90:93], v[168:171], v[224:227], v[90:93]
	v_mfma_f32_16x16x32_bf16 v[78:81], v[160:163], v[232:235], v[78:81]
	v_mfma_f32_16x16x32_bf16 v[74:77], v[168:171], v[232:235], v[74:77]
	s_setprio 0
	s_setprio 1
	v_mfma_f32_16x16x32_bf16 v[126:129], v[164:167], v[212:215], v[126:129]
	v_mfma_f32_16x16x32_bf16 v[122:125], v[172:175], v[212:215], v[122:125]
	v_mfma_f32_16x16x32_bf16 v[110:113], v[164:167], v[220:223], v[110:113]
	v_mfma_f32_16x16x32_bf16 v[106:109], v[172:175], v[220:223], v[106:109]
	v_mfma_f32_16x16x32_bf16 v[94:97], v[164:167], v[228:231], v[94:97]
	v_mfma_f32_16x16x32_bf16 v[90:93], v[172:175], v[228:231], v[90:93]
	v_mfma_f32_16x16x32_bf16 v[78:81], v[164:167], v[236:239], v[78:81]
	v_mfma_f32_16x16x32_bf16 v[74:77], v[172:175], v[236:239], v[74:77]
	s_setprio 0
	s_setprio 1
	v_mfma_f32_16x16x32_bf16 v[118:121], v[176:179], v[208:211], v[118:121]
	v_mfma_f32_16x16x32_bf16 v[114:117], v[184:187], v[208:211], v[114:117]
	v_mfma_f32_16x16x32_bf16 v[102:105], v[176:179], v[216:219], v[102:105]
	v_mfma_f32_16x16x32_bf16 v[98:101], v[184:187], v[216:219], v[98:101]
	v_mfma_f32_16x16x32_bf16 v[86:89], v[176:179], v[224:227], v[86:89]
	v_mfma_f32_16x16x32_bf16 v[82:85], v[184:187], v[224:227], v[82:85]
	v_mfma_f32_16x16x32_bf16 v[70:73], v[176:179], v[232:235], v[70:73]
	v_mfma_f32_16x16x32_bf16 v[66:69], v[184:187], v[232:235], v[66:69]
	s_setprio 0
	s_setprio 1
	v_mfma_f32_16x16x32_bf16 v[118:121], v[180:183], v[212:215], v[118:121]
	v_mfma_f32_16x16x32_bf16 v[114:117], v[204:207], v[212:215], v[114:117]
	v_mfma_f32_16x16x32_bf16 v[102:105], v[180:183], v[220:223], v[102:105]
	v_mfma_f32_16x16x32_bf16 v[98:101], v[204:207], v[220:223], v[98:101]
	v_mfma_f32_16x16x32_bf16 v[86:89], v[180:183], v[228:231], v[86:89]
	v_mfma_f32_16x16x32_bf16 v[82:85], v[204:207], v[228:231], v[82:85]
	v_mfma_f32_16x16x32_bf16 v[70:73], v[180:183], v[236:239], v[70:73]
	v_mfma_f32_16x16x32_bf16 v[66:69], v[204:207], v[236:239], v[66:69]
	s_setprio 0
	s_barrier
; #define PG8_STAGE(bufoff, gbase, voff) do { _Pragma("unroll") for (int _i = 0; _i < 2; ++_i) \
;         __builtin_amdgcn_global_load_lds((const unsigned*)((const char*)(gbase) + (voff)[_i]), (PG8_LAS unsigned*)(lds + (bufoff) + ldsw + _i * 8192), 16, 0, 0); } while (0)
; #define PG8_LDA(dst, b, h) do { _Pragma("unroll") for (int m = 0; m < 4; ++m) _Pragma("unroll") for (int k = 0; k < 2; ++k) dst[m][k] = *(const PG8_LAS bf16x8*)(lds + PG8_SA(b, h) + aoff + m * 2048 + k * 1024); } while (0)
; #define PG8_MMA(ai, bj, At, Bt) do { __builtin_amdgcn_s_setprio(1); _Pragma("unroll") for (int m = 0; m < 4; ++m) _Pragma("unroll") for (int n = 0; n < 2; ++n) _Pragma("unroll") for (int k = 0; k < 2; ++k) \
;         acc[ai][bj][m][n] = __builtin_amdgcn_mfma_f32_16x16x32_bf16(Bt[n][k], At[m][k], acc[ai][bj][m][n], 0, 0, 0); __builtin_amdgcn_s_setprio(0); } while (0)
; #define PG8_WAIT_V(n) asm volatile("s_waitcnt vmcnt(" #n ")" ::: "memory")
; #define PG8_WAIT_L(n) asm volatile("s_waitcnt lgkmcnt(" #n ")" ::: "memory")
; #define PG8_BAR __builtin_amdgcn_s_barrier()
; #define PG8_SCHED __builtin_amdgcn_sched_barrier(0)
; template <class Epi, class Sched, bool ALIGN_EPI = false, bool SP2 = false>
; __device__ __forceinline__ void gemm_phase(PG8_LAS unsigned char* lds, const Gemm g, const Sched& S, const Epi& E) {
;     ...
;         for (int t = 0; t < nt; t += 2) {
;             const bool last = (t == nt - 2);
;             const char* a1 = cA + (size_t)(t + 1) * kstep;
;             const char* a2 = last ? nA : cA + (size_t)(t + 2) * kstep; const char* b2 = last ? nB : cB + (size_t)(t + 2) * kstep;
;     ...
;             PG8_LDA(At, 1, 1); PG8_STAGE(PG8_SB(1, 0), b3, voffB); PG8_STAGE(PG8_SB(1, 1), b3 + hstep, voffB); PG8_STAGE(PG8_SA(1, 0), a3, voffA);
;             PG8_WAIT_V(8); PG8_WAIT_L(0); PG8_BAR; PG8_MMA(1, 0, At, B0); PG8_MMA(1, 1, At, B1); PG8_BAR; PG8_SCHED;
	s_add_i32 s46, s76, s4
	v_lshl_add_u64 v[240:241], v[240:241], 0, s[68:69]
	s_mov_b32 m0, s46
	ds_read_b128 v[208:211], v143 offset:49152
	ds_read_b128 v[212:215], v143 offset:50176
	ds_read_b128 v[216:219], v143 offset:51200
	ds_read_b128 v[220:223], v143 offset:52224
	ds_read_b128 v[224:227], v143 offset:53248
	ds_read_b128 v[228:231], v143 offset:54272
	ds_read_b128 v[232:235], v143 offset:55296
	ds_read_b128 v[236:239], v143 offset:56320
	global_load_lds_dwordx4 v[240:241], off
	s_add_i32 m0, s46, 0x2000
	s_add_u32 s18, s18, 0x20080
	v_lshl_add_u64 v[240:241], v[242:243], 0, s[68:69]
	s_addc_u32 s19, s19, 0
	s_add_i32 s46, s77, s4
	global_load_lds_dwordx4 v[240:241], off
	v_lshl_add_u64 v[240:241], s[18:19], 0, v[148:149]
	s_mov_b32 m0, s46
	s_nop 0
	global_load_lds_dwordx4 v[240:241], off
	v_lshl_add_u64 v[240:241], s[18:19], 0, v[144:145]
	s_add_i32 m0, s46, 0x2000
	s_nop 0
	global_load_lds_dwordx4 v[240:241], off
	v_lshl_add_u64 v[240:241], v[244:245], 0, s[68:69]
	s_mov_b32 m0, s54
	s_nop 0
	global_load_lds_dwordx4 v[240:241], off
	v_lshl_add_u64 v[240:241], v[246:247], 0, s[68:69]
	s_mov_b32 m0, s57
	s_nop 0
	global_load_lds_dwordx4 v[240:241], off
	s_nop 0
	s_waitcnt vmcnt(8)
	s_waitcnt lgkmcnt(0)
	s_setprio 1
	s_barrier
	v_mfma_f32_16x16x32_bf16 v[62:65], v[160:163], v[208:211], v[62:65]
	v_mfma_f32_16x16x32_bf16 v[58:61], v[168:171], v[208:211], v[58:61]
	v_mfma_f32_16x16x32_bf16 v[46:49], v[160:163], v[216:219], v[46:49]
	v_mfma_f32_16x16x32_bf16 v[42:45], v[168:171], v[216:219], v[42:45]
	v_mfma_f32_16x16x32_bf16 v[30:33], v[160:163], v[224:227], v[30:33]
	v_mfma_f32_16x16x32_bf16 v[26:29], v[168:171], v[224:227], v[26:29]
	v_mfma_f32_16x16x32_bf16 v[14:17], v[160:163], v[232:235], v[14:17]
	v_mfma_f32_16x16x32_bf16 v[10:13], v[168:171], v[232:235], v[10:13]
	v_mfma_f32_16x16x32_bf16 v[62:65], v[164:167], v[212:215], v[62:65]
	v_mfma_f32_16x16x32_bf16 v[58:61], v[172:175], v[212:215], v[58:61]
	v_mfma_f32_16x16x32_bf16 v[46:49], v[164:167], v[220:223], v[46:49]
	v_mfma_f32_16x16x32_bf16 v[42:45], v[172:175], v[220:223], v[42:45]
	v_mfma_f32_16x16x32_bf16 v[30:33], v[164:167], v[228:231], v[30:33]
	v_mfma_f32_16x16x32_bf16 v[26:29], v[172:175], v[228:231], v[26:29]
	v_mfma_f32_16x16x32_bf16 v[14:17], v[164:167], v[236:239], v[14:17]
	v_mfma_f32_16x16x32_bf16 v[10:13], v[172:175], v[236:239], v[10:13]
	v_mfma_f32_16x16x32_bf16 v[54:57], v[176:179], v[208:211], v[54:57]
	v_mfma_f32_16x16x32_bf16 v[50:53], v[184:187], v[208:211], v[50:53]
	v_mfma_f32_16x16x32_bf16 v[38:41], v[176:179], v[216:219], v[38:41]
	v_mfma_f32_16x16x32_bf16 v[34:37], v[184:187], v[216:219], v[34:37]
	v_mfma_f32_16x16x32_bf16 v[22:25], v[176:179], v[224:227], v[22:25]
	v_mfma_f32_16x16x32_bf16 v[18:21], v[184:187], v[224:227], v[18:21]
	v_mfma_f32_16x16x32_bf16 v[6:9], v[176:179], v[232:235], v[6:9]
	v_mfma_f32_16x16x32_bf16 v[2:5], v[184:187], v[232:235], v[2:5]
	v_mfma_f32_16x16x32_bf16 v[54:57], v[180:183], v[212:215], v[54:57]
	v_mfma_f32_16x16x32_bf16 v[50:53], v[204:207], v[212:215], v[50:53]
	v_mfma_f32_16x16x32_bf16 v[38:41], v[180:183], v[220:223], v[38:41]
	v_mfma_f32_16x16x32_bf16 v[34:37], v[204:207], v[220:223], v[34:37]
	v_mfma_f32_16x16x32_bf16 v[22:25], v[180:183], v[228:231], v[22:25]
	v_mfma_f32_16x16x32_bf16 v[18:21], v[204:207], v[228:231], v[18:21]
	v_mfma_f32_16x16x32_bf16 v[6:9], v[180:183], v[236:239], v[6:9]
	v_mfma_f32_16x16x32_bf16 v[2:5], v[204:207], v[236:239], v[2:5]
	s_setprio 0
	s_barrier
	s_add_i32 s79, s79, 2
	s_add_u32 s58, s58, 0x100
	s_addc_u32 s59, s59, 0
	s_add_u32 s85, s85, 0x100
	s_addc_u32 s78, s78, 0
	s_cmp_gt_u32 s79, 5

; #define PG8_STAGE(bufoff, gbase, voff) do { _Pragma("unroll") for (int _i = 0; _i < 2; ++_i) \
;         __builtin_amdgcn_global_load_lds((const unsigned*)((const char*)(gbase) + (voff)[_i]), (PG8_LAS unsigned*)(lds + (bufoff) + ldsw + _i * 8192), 16, 0, 0); } while (0)
; #define PG8_LDA(dst, b, h) do { _Pragma("unroll") for (int m = 0; m < 4; ++m) _Pragma("unroll") for (int k = 0; k < 2; ++k) dst[m][k] = *(const PG8_LAS bf16x8*)(lds + PG8_SA(b, h) + aoff + m * 2048 + k * 1024); } while (0)
; #define PG8_LDB(dst, b, h) do { _Pragma("unroll") for (int n = 0; n < 2; ++n) _Pragma("unroll") for (int k = 0; k < 2; ++k) dst[n][k] = *(const PG8_LAS bf16x8*)(lds + PG8_SB(b, h) + boff + n * 2048 + k * 1024); } while (0)
; #define PG8_WAIT_V(n) asm volatile("s_waitcnt vmcnt(" #n ")" ::: "memory")
; #define PG8_WAIT_L(n) asm volatile("s_waitcnt lgkmcnt(" #n ")" ::: "memory")
; #define PG8_BAR __builtin_amdgcn_s_barrier()
; #define PG8_SCHED __builtin_amdgcn_sched_barrier(0)
; template <class Epi, class Sched, bool ALIGN_EPI = false, bool SP2 = false>
; __device__ __forceinline__ void gemm_phase(PG8_LAS unsigned char* lds, const Gemm g, const Sched& S, const Epi& E) {
;     ...
;         const bool has_next = S.next(ui + 1, nxt);
;         const char* nA = has_next ? (const char*)g.A + (size_t)nxt.pm * tstep : cA; const char* nB = has_next ? (const char*)g.Bt + (size_t)nxt.pn * tstep : cB;
;         for (int t = 0; t < nt; t += 2) {
;             const bool last = (t == nt - 2);
;             const char* a1 = cA + (size_t)(t + 1) * kstep;
;             const char* a2 = last ? nA : cA + (size_t)(t + 2) * kstep; const char* b2 = last ? nB : cB + (size_t)(t + 2) * kstep;
;             const char* a3 = a2 + kstep; const char* b3 = b2 + kstep;
;             if (last && has_next) S.a_ready(nxt);
;             if constexpr (SP2) {
;             PG8_LDB(B0, 0, 0); PG8_LDB(B1, 0, 1); PG8_SCHED; PG8_LDA(At, 0, 0); PG8_STAGE(PG8_SA(1, 1), a1 + hstep, voffA);
;             PG8_WAIT_V(8); PG8_WAIT_L(0); PG8_BAR; PG8_MMA(0, 0, At, B0); PG8_MMA(0, 1, At, B1); PG8_BAR; PG8_SCHED;
;             PG8_LDA(At, 0, 1); PG8_STAGE(PG8_SB(0, 0), b2, voffB); PG8_STAGE(PG8_SB(0, 1), b2 + hstep, voffB); PG8_STAGE(PG8_SA(0, 0), a2, voffA);
;             PG8_WAIT_V(8); PG8_WAIT_L(0); PG8_BAR; PG8_MMA(1, 0, At, B0); PG8_MMA(1, 1, At, B1); PG8_BAR; PG8_SCHED;
.LBB0_159:
	s_add_u32 s60, s42, 0x100
	s_addc_u32 s73, s43, 0
	s_mov_b32 s46, -2
	s_waitcnt vmcnt(0)
	s_add_u32 s42, s36, 0x100
	s_addc_u32 s43, s37, 0
	s_add_i32 s47, 0, 0x10000
	s_cmp_eq_u32 s46, 20
	s_cselect_b32 s45, s1, s43
	s_cselect_b32 s44, s0, s42
	s_cselect_b32 s19, s7, s73
	s_cselect_b32 s18, s6, s60
	s_add_i32 s76, 0, 0x14000
	v_add_u32_e32 v174, s47, v143
	v_add_u32_e32 v186, s76, v143
	ds_read_b128 v[160:163], v174
	ds_read_b128 v[164:167], v174 offset:1024
	ds_read_b128 v[170:173], v174 offset:2048
	ds_read_b128 v[174:177], v174 offset:3072
	ds_read_b128 v[178:181], v186
	ds_read_b128 v[182:185], v186 offset:1024
	ds_read_b128 v[204:207], v186 offset:2048
	ds_read_b128 v[208:211], v186 offset:3072
	v_lshl_add_u64 v[186:187], s[36:37], 0, v[156:157]
	s_add_i32 m0, s54, 0xc000
	ds_read_b128 v[212:215], v169
	ds_read_b128 v[216:219], v169 offset:1024
	ds_read_b128 v[220:223], v169 offset:2048
	ds_read_b128 v[224:227], v169 offset:3072
	ds_read_b128 v[228:231], v169 offset:4096
	ds_read_b128 v[232:235], v169 offset:5120
	ds_read_b128 v[236:239], v169 offset:6144
	ds_read_b128 v[240:243], v169 offset:7168
	global_load_lds_dwordx4 v[186:187], off
	v_lshl_add_u64 v[186:187], s[36:37], 0, v[158:159]
	s_add_i32 m0, s54, 0xe000
	s_nop 0
	global_load_lds_dwordx4 v[186:187], off
	s_waitcnt vmcnt(8)
	s_waitcnt lgkmcnt(0)
	s_setprio 1
	s_barrier
	v_mfma_f32_16x16x32_bf16 v[126:129], v[160:163], v[212:215], 0
	v_mfma_f32_16x16x32_bf16 v[122:125], v[170:173], v[212:215], 0
	v_mfma_f32_16x16x32_bf16 v[110:113], v[160:163], v[220:223], 0
	v_mfma_f32_16x16x32_bf16 v[106:109], v[170:173], v[220:223], 0
	v_mfma_f32_16x16x32_bf16 v[94:97], v[160:163], v[228:231], 0
	v_mfma_f32_16x16x32_bf16 v[90:93], v[170:173], v[228:231], 0
	v_mfma_f32_16x16x32_bf16 v[78:81], v[160:163], v[236:239], 0
	v_mfma_f32_16x16x32_bf16 v[74:77], v[170:173], v[236:239], 0
	s_setprio 0
	s_setprio 1
	v_mfma_f32_16x16x32_bf16 v[126:129], v[164:167], v[216:219], v[126:129]
	v_mfma_f32_16x16x32_bf16 v[122:125], v[174:177], v[216:219], v[122:125]
	v_mfma_f32_16x16x32_bf16 v[110:113], v[164:167], v[224:227], v[110:113]
	v_mfma_f32_16x16x32_bf16 v[106:109], v[174:177], v[224:227], v[106:109]
	v_mfma_f32_16x16x32_bf16 v[94:97], v[164:167], v[232:235], v[94:97]
	v_mfma_f32_16x16x32_bf16 v[90:93], v[174:177], v[232:235], v[90:93]
	v_mfma_f32_16x16x32_bf16 v[78:81], v[164:167], v[240:243], v[78:81]
	v_mfma_f32_16x16x32_bf16 v[74:77], v[174:177], v[240:243], v[74:77]
	s_setprio 0
	s_setprio 1
	v_mfma_f32_16x16x32_bf16 v[118:121], v[178:181], v[212:215], 0
	v_mfma_f32_16x16x32_bf16 v[114:117], v[204:207], v[212:215], 0
	v_mfma_f32_16x16x32_bf16 v[102:105], v[178:181], v[220:223], 0
	v_mfma_f32_16x16x32_bf16 v[98:101], v[204:207], v[220:223], 0
	v_mfma_f32_16x16x32_bf16 v[86:89], v[178:181], v[228:231], 0
	v_mfma_f32_16x16x32_bf16 v[82:85], v[204:207], v[228:231], 0
	v_mfma_f32_16x16x32_bf16 v[70:73], v[178:181], v[236:239], 0
	v_mfma_f32_16x16x32_bf16 v[66:69], v[204:207], v[236:239], 0
	s_setprio 0
	s_setprio 1
	v_mfma_f32_16x16x32_bf16 v[118:121], v[182:185], v[216:219], v[118:121]
	v_mfma_f32_16x16x32_bf16 v[114:117], v[208:211], v[216:219], v[114:117]
	v_mfma_f32_16x16x32_bf16 v[102:105], v[182:185], v[224:227], v[102:105]
	v_mfma_f32_16x16x32_bf16 v[98:101], v[208:211], v[224:227], v[98:101]
	v_mfma_f32_16x16x32_bf16 v[86:89], v[182:185], v[232:235], v[86:89]
	v_mfma_f32_16x16x32_bf16 v[82:85], v[208:211], v[232:235], v[82:85]
	v_mfma_f32_16x16x32_bf16 v[70:73], v[182:185], v[240:243], v[70:73]
	v_mfma_f32_16x16x32_bf16 v[66:69], v[208:211], v[240:243], v[66:69]
	s_setprio 0
	s_barrier
	s_add_i32 s36, s47, s4
	v_lshl_add_u64 v[186:187], s[18:19], 0, v[148:149]
	s_mov_b32 m0, s36
	ds_read_b128 v[212:215], v169 offset:16384
	ds_read_b128 v[216:219], v169 offset:17408
	ds_read_b128 v[220:223], v169 offset:18432
	ds_read_b128 v[224:227], v169 offset:19456
	ds_read_b128 v[228:231], v169 offset:20480
	ds_read_b128 v[232:235], v169 offset:21504
	ds_read_b128 v[236:239], v169 offset:22528
	ds_read_b128 v[240:243], v169 offset:23552
	global_load_lds_dwordx4 v[186:187], off
	s_add_i32 m0, s36, 0x2000
	s_add_u32 s36, s18, 0x60000
	v_lshl_add_u64 v[244:245], s[18:19], 0, v[144:145]
	s_addc_u32 s37, s19, 0
	s_add_i32 s47, s76, s4
	global_load_lds_dwordx4 v[244:245], off
	v_lshl_add_u64 v[246:247], s[36:37], 0, v[148:149]
	s_mov_b32 m0, s47
	v_lshl_add_u64 v[248:249], s[44:45], 0, v[146:147]
	global_load_lds_dwordx4 v[246:247], off
	v_lshl_add_u64 v[246:247], s[36:37], 0, v[144:145]
	s_add_i32 m0, s47, 0x2000
	s_nop 0
	global_load_lds_dwordx4 v[246:247], off
	v_lshl_add_u64 v[246:247], s[44:45], 0, v[150:151]
	s_mov_b32 m0, s54
	s_nop 0
	global_load_lds_dwordx4 v[246:247], off
	s_mov_b32 m0, s57
	s_nop 0
	global_load_lds_dwordx4 v[248:249], off
	s_waitcnt vmcnt(8)
	s_waitcnt lgkmcnt(0)
	s_setprio 1
	s_barrier
; #define PG8_STAGE(bufoff, gbase, voff) do { _Pragma("unroll") for (int _i = 0; _i < 2; ++_i) \
;         __builtin_amdgcn_global_load_lds((const unsigned*)((const char*)(gbase) + (voff)[_i]), (PG8_LAS unsigned*)(lds + (bufoff) + ldsw + _i * 8192), 16, 0, 0); } while (0)
; #define PG8_LDA(dst, b, h) do { _Pragma("unroll") for (int m = 0; m < 4; ++m) _Pragma("unroll") for (int k = 0; k < 2; ++k) dst[m][k] = *(const PG8_LAS bf16x8*)(lds + PG8_SA(b, h) + aoff + m * 2048 + k * 1024); } while (0)
; #define PG8_LDB(dst, b, h) do { _Pragma("unroll") for (int n = 0; n < 2; ++n) _Pragma("unroll") for (int k = 0; k < 2; ++k) dst[n][k] = *(const PG8_LAS bf16x8*)(lds + PG8_SB(b, h) + boff + n * 2048 + k * 1024); } while (0)
; #define PG8_MMA(ai, bj, At, Bt) do { __builtin_amdgcn_s_setprio(1); _Pragma("unroll") for (int m = 0; m < 4; ++m) _Pragma("unroll") for (int n = 0; n < 2; ++n) _Pragma("unroll") for (int k = 0; k < 2; ++k) \
;         acc[ai][bj][m][n] = __builtin_amdgcn_mfma_f32_16x16x32_bf16(Bt[n][k], At[m][k], acc[ai][bj][m][n], 0, 0, 0); __builtin_amdgcn_s_setprio(0); } while (0)
; #define PG8_WAIT_V(n) asm volatile("s_waitcnt vmcnt(" #n ")" ::: "memory")
; #define PG8_WAIT_L(n) asm volatile("s_waitcnt lgkmcnt(" #n ")" ::: "memory")
; #define PG8_BAR __builtin_amdgcn_s_barrier()
; #define PG8_SCHED __builtin_amdgcn_sched_barrier(0)
; template <class Epi, class Sched, bool ALIGN_EPI = false, bool SP2 = false>
; __device__ __forceinline__ void gemm_phase(PG8_LAS unsigned char* lds, const Gemm g, const Sched& S, const Epi& E) {
;     ...
;             PG8_WAIT_V(8); PG8_WAIT_L(0); PG8_BAR; PG8_MMA(1, 0, At, B0); PG8_MMA(1, 1, At, B1); PG8_BAR; PG8_SCHED;
;             PG8_LDB(B0, 1, 0); PG8_LDB(B1, 1, 1); PG8_SCHED; PG8_LDA(At, 1, 0); PG8_STAGE(PG8_SA(0, 1), a2 + hstep, voffA);
;             PG8_WAIT_V(8); PG8_WAIT_L(0); PG8_BAR; PG8_MMA(0, 0, At, B0); PG8_MMA(0, 1, At, B1); PG8_BAR; PG8_SCHED;
;             PG8_LDA(At, 1, 1); PG8_STAGE(PG8_SB(1, 0), b3, voffB); PG8_STAGE(PG8_SB(1, 1), b3 + hstep, voffB); PG8_STAGE(PG8_SA(1, 0), a3, voffA);
	v_mfma_f32_16x16x32_bf16 v[62:65], v[160:163], v[212:215], 0
	v_mfma_f32_16x16x32_bf16 v[58:61], v[170:173], v[212:215], 0
	v_mfma_f32_16x16x32_bf16 v[46:49], v[160:163], v[220:223], 0
	v_mfma_f32_16x16x32_bf16 v[42:45], v[170:173], v[220:223], 0
	v_mfma_f32_16x16x32_bf16 v[30:33], v[160:163], v[228:231], 0
	v_mfma_f32_16x16x32_bf16 v[26:29], v[170:173], v[228:231], 0
	v_mfma_f32_16x16x32_bf16 v[14:17], v[160:163], v[236:239], 0
	v_mfma_f32_16x16x32_bf16 v[10:13], v[170:173], v[236:239], 0
	v_mfma_f32_16x16x32_bf16 v[62:65], v[164:167], v[216:219], v[62:65]
	v_mfma_f32_16x16x32_bf16 v[58:61], v[174:177], v[216:219], v[58:61]
	v_mfma_f32_16x16x32_bf16 v[46:49], v[164:167], v[224:227], v[46:49]
	v_mfma_f32_16x16x32_bf16 v[42:45], v[174:177], v[224:227], v[42:45]
	v_mfma_f32_16x16x32_bf16 v[30:33], v[164:167], v[232:235], v[30:33]
	v_mfma_f32_16x16x32_bf16 v[26:29], v[174:177], v[232:235], v[26:29]
	v_mfma_f32_16x16x32_bf16 v[14:17], v[164:167], v[240:243], v[14:17]
	v_mfma_f32_16x16x32_bf16 v[10:13], v[174:177], v[240:243], v[10:13]
	v_mfma_f32_16x16x32_bf16 v[54:57], v[178:181], v[212:215], 0
	v_mfma_f32_16x16x32_bf16 v[50:53], v[204:207], v[212:215], 0
	v_mfma_f32_16x16x32_bf16 v[38:41], v[178:181], v[220:223], 0
	v_mfma_f32_16x16x32_bf16 v[34:37], v[204:207], v[220:223], 0
	v_mfma_f32_16x16x32_bf16 v[22:25], v[178:181], v[228:231], 0
	v_mfma_f32_16x16x32_bf16 v[18:21], v[204:207], v[228:231], 0
	v_mfma_f32_16x16x32_bf16 v[6:9], v[178:181], v[236:239], 0
	v_mfma_f32_16x16x32_bf16 v[2:5], v[204:207], v[236:239], 0
	v_mfma_f32_16x16x32_bf16 v[54:57], v[182:185], v[216:219], v[54:57]
	v_mfma_f32_16x16x32_bf16 v[50:53], v[208:211], v[216:219], v[50:53]
	v_mfma_f32_16x16x32_bf16 v[38:41], v[182:185], v[224:227], v[38:41]
	v_mfma_f32_16x16x32_bf16 v[34:37], v[208:211], v[224:227], v[34:37]
	v_mfma_f32_16x16x32_bf16 v[22:25], v[182:185], v[232:235], v[22:25]
	v_mfma_f32_16x16x32_bf16 v[18:21], v[208:211], v[232:235], v[18:21]
	v_mfma_f32_16x16x32_bf16 v[6:9], v[182:185], v[240:243], v[6:9]
	v_mfma_f32_16x16x32_bf16 v[2:5], v[208:211], v[240:243], v[2:5]
	s_setprio 0
	s_barrier
	s_add_i32 s47, 0, 0x18000
	s_add_i32 s76, 0, 0x1c000
	v_add_u32_e32 v174, s47, v143
	v_add_u32_e32 v203, s76, v143
	ds_read_b128 v[160:163], v174
	ds_read_b128 v[164:167], v174 offset:1024
	ds_read_b128 v[170:173], v174 offset:2048
	ds_read_b128 v[174:177], v174 offset:3072
	ds_read_b128 v[178:181], v203
	ds_read_b128 v[182:185], v203 offset:1024
	ds_read_b128 v[204:207], v203 offset:2048
	ds_read_b128 v[208:211], v203 offset:3072
	s_add_u32 s36, s44, 0x60000
	s_addc_u32 s37, s45, 0
	s_mov_b32 m0, s58
	v_lshl_add_u64 v[250:251], s[36:37], 0, v[150:151]
	ds_read_b128 v[212:215], v169 offset:32768
	ds_read_b128 v[216:219], v169 offset:33792
	ds_read_b128 v[220:223], v169 offset:34816
	ds_read_b128 v[224:227], v169 offset:35840
	ds_read_b128 v[228:231], v169 offset:36864
	ds_read_b128 v[232:235], v169 offset:37888
	ds_read_b128 v[236:239], v169 offset:38912
	ds_read_b128 v[240:243], v169 offset:39936
	global_load_lds_dwordx4 v[250:251], off
	v_lshl_add_u64 v[250:251], s[36:37], 0, v[146:147]
	s_mov_b32 m0, s59
	s_nop 0
	global_load_lds_dwordx4 v[250:251], off
	s_waitcnt vmcnt(8)
	s_waitcnt lgkmcnt(0)
	s_setprio 1
	s_barrier
	v_mfma_f32_16x16x32_bf16 v[126:129], v[160:163], v[212:215], v[126:129]
	v_mfma_f32_16x16x32_bf16 v[122:125], v[170:173], v[212:215], v[122:125]
	v_mfma_f32_16x16x32_bf16 v[110:113], v[160:163], v[220:223], v[110:113]
	v_mfma_f32_16x16x32_bf16 v[106:109], v[170:173], v[220:223], v[106:109]
	v_mfma_f32_16x16x32_bf16 v[94:97], v[160:163], v[228:231], v[94:97]
	v_mfma_f32_16x16x32_bf16 v[90:93], v[170:173], v[228:231], v[90:93]
	v_mfma_f32_16x16x32_bf16 v[78:81], v[160:163], v[236:239], v[78:81]
	v_mfma_f32_16x16x32_bf16 v[74:77], v[170:173], v[236:239], v[74:77]
	s_setprio 0
	s_setprio 1
	v_mfma_f32_16x16x32_bf16 v[126:129], v[164:167], v[216:219], v[126:129]
	v_mfma_f32_16x16x32_bf16 v[122:125], v[174:177], v[216:219], v[122:125]
	v_mfma_f32_16x16x32_bf16 v[110:113], v[164:167], v[224:227], v[110:113]
	v_mfma_f32_16x16x32_bf16 v[106:109], v[174:177], v[224:227], v[106:109]
	v_mfma_f32_16x16x32_bf16 v[94:97], v[164:167], v[232:235], v[94:97]
	v_mfma_f32_16x16x32_bf16 v[90:93], v[174:177], v[232:235], v[90:93]
	v_mfma_f32_16x16x32_bf16 v[78:81], v[164:167], v[240:243], v[78:81]
	v_mfma_f32_16x16x32_bf16 v[74:77], v[174:177], v[240:243], v[74:77]
	s_setprio 0
	s_setprio 1
	v_mfma_f32_16x16x32_bf16 v[118:121], v[178:181], v[212:215], v[118:121]
	v_mfma_f32_16x16x32_bf16 v[114:117], v[204:207], v[212:215], v[114:117]
	v_mfma_f32_16x16x32_bf16 v[102:105], v[178:181], v[220:223], v[102:105]
	v_mfma_f32_16x16x32_bf16 v[98:101], v[204:207], v[220:223], v[98:101]
	v_mfma_f32_16x16x32_bf16 v[86:89], v[178:181], v[228:231], v[86:89]
	v_mfma_f32_16x16x32_bf16 v[82:85], v[204:207], v[228:231], v[82:85]
	v_mfma_f32_16x16x32_bf16 v[70:73], v[178:181], v[236:239], v[70:73]
	v_mfma_f32_16x16x32_bf16 v[66:69], v[204:207], v[236:239], v[66:69]
	s_setprio 0
	s_setprio 1
	v_mfma_f32_16x16x32_bf16 v[118:121], v[182:185], v[216:219], v[118:121]
	v_mfma_f32_16x16x32_bf16 v[114:117], v[208:211], v[216:219], v[114:117]
	v_mfma_f32_16x16x32_bf16 v[102:105], v[182:185], v[224:227], v[102:105]
	v_mfma_f32_16x16x32_bf16 v[98:101], v[208:211], v[224:227], v[98:101]
	v_mfma_f32_16x16x32_bf16 v[86:89], v[182:185], v[232:235], v[86:89]
	v_mfma_f32_16x16x32_bf16 v[82:85], v[208:211], v[232:235], v[82:85]
	v_mfma_f32_16x16x32_bf16 v[70:73], v[182:185], v[240:243], v[70:73]
	v_mfma_f32_16x16x32_bf16 v[66:69], v[208:211], v[240:243], v[66:69]
	s_setprio 0
	s_barrier
; #define PG8_STAGE(bufoff, gbase, voff) do { _Pragma("unroll") for (int _i = 0; _i < 2; ++_i) \
;         __builtin_amdgcn_global_load_lds((const unsigned*)((const char*)(gbase) + (voff)[_i]), (PG8_LAS unsigned*)(lds + (bufoff) + ldsw + _i * 8192), 16, 0, 0); } while (0)
; #define PG8_LDA(dst, b, h) do { _Pragma("unroll") for (int m = 0; m < 4; ++m) _Pragma("unroll") for (int k = 0; k < 2; ++k) dst[m][k] = *(const PG8_LAS bf16x8*)(lds + PG8_SA(b, h) + aoff + m * 2048 + k * 1024); } while (0)
; #define PG8_LDB(dst, b, h) do { _Pragma("unroll") for (int n = 0; n < 2; ++n) _Pragma("unroll") for (int k = 0; k < 2; ++k) dst[n][k] = *(const PG8_LAS bf16x8*)(lds + PG8_SB(b, h) + boff + n * 2048 + k * 1024); } while (0)
; #define PG8_MMA(ai, bj, At, Bt) do { __builtin_amdgcn_s_setprio(1); _Pragma("unroll") for (int m = 0; m < 4; ++m) _Pragma("unroll") for (int n = 0; n < 2; ++n) _Pragma("unroll") for (int k = 0; k < 2; ++k) \
;         acc[ai][bj][m][n] = __builtin_amdgcn_mfma_f32_16x16x32_bf16(Bt[n][k], At[m][k], acc[ai][bj][m][n], 0, 0, 0); __builtin_amdgcn_s_setprio(0); } while (0)
; #define PG8_WAIT_V(n) asm volatile("s_waitcnt vmcnt(" #n ")" ::: "memory")
; #define PG8_WAIT_L(n) asm volatile("s_waitcnt lgkmcnt(" #n ")" ::: "memory")
; #define PG8_BAR __builtin_amdgcn_s_barrier()
; #define PG8_SCHED __builtin_amdgcn_sched_barrier(0)
; template <class Epi, class Sched, bool ALIGN_EPI = false, bool SP2 = false>
; __device__ __forceinline__ void gemm_phase(PG8_LAS unsigned char* lds, const Gemm g, const Sched& S, const Epi& E) {
;     ...
;             PG8_LDB(B0, 0, 0); PG8_LDB(B1, 0, 1); PG8_SCHED; PG8_LDA(At, 0, 0); PG8_STAGE(PG8_SA(1, 1), a1 + hstep, voffA);
;             PG8_WAIT_V(8); PG8_WAIT_L(0); PG8_BAR; PG8_MMA(0, 0, At, B0); PG8_MMA(0, 1, At, B1); PG8_BAR; PG8_SCHED;
;     ...
;             PG8_LDA(At, 1, 1); PG8_STAGE(PG8_SB(1, 0), b3, voffB); PG8_STAGE(PG8_SB(1, 1), b3 + hstep, voffB); PG8_STAGE(PG8_SA(1, 0), a3, voffA);
;             PG8_WAIT_V(8); PG8_WAIT_L(0); PG8_BAR; PG8_MMA(1, 0, At, B0); PG8_MMA(1, 1, At, B1); PG8_BAR; PG8_SCHED;
	s_add_i32 s36, s47, s4
	v_lshl_add_u64 v[186:187], v[186:187], 0, s[68:69]
	s_mov_b32 m0, s36
	ds_read_b128 v[212:215], v169 offset:49152
	ds_read_b128 v[216:219], v169 offset:50176
	ds_read_b128 v[220:223], v169 offset:51200
	ds_read_b128 v[224:227], v169 offset:52224
	ds_read_b128 v[228:231], v169 offset:53248
	ds_read_b128 v[232:235], v169 offset:54272
	ds_read_b128 v[236:239], v169 offset:55296
	ds_read_b128 v[240:243], v169 offset:56320
	global_load_lds_dwordx4 v[186:187], off
	s_add_i32 m0, s36, 0x2000
	s_add_u32 s18, s18, 0x60080
	v_lshl_add_u64 v[186:187], v[244:245], 0, s[68:69]
	s_addc_u32 s19, s19, 0
	s_add_i32 s36, s76, s4
	global_load_lds_dwordx4 v[186:187], off
	v_lshl_add_u64 v[186:187], s[18:19], 0, v[148:149]
	s_mov_b32 m0, s36
	s_nop 0
	global_load_lds_dwordx4 v[186:187], off
	v_lshl_add_u64 v[186:187], s[18:19], 0, v[144:145]
	s_add_i32 m0, s36, 0x2000
	s_nop 0
	global_load_lds_dwordx4 v[186:187], off
	v_lshl_add_u64 v[186:187], v[246:247], 0, s[68:69]
	s_mov_b32 m0, s62
	s_nop 0
	global_load_lds_dwordx4 v[186:187], off
	v_lshl_add_u64 v[186:187], v[248:249], 0, s[68:69]
	s_mov_b32 m0, s63
	s_nop 0
	global_load_lds_dwordx4 v[186:187], off
	s_nop 0
	s_waitcnt vmcnt(8)
	s_waitcnt lgkmcnt(0)
	s_setprio 1
	s_barrier
	v_mfma_f32_16x16x32_bf16 v[62:65], v[160:163], v[212:215], v[62:65]
	v_mfma_f32_16x16x32_bf16 v[58:61], v[170:173], v[212:215], v[58:61]
	v_mfma_f32_16x16x32_bf16 v[46:49], v[160:163], v[220:223], v[46:49]
	v_mfma_f32_16x16x32_bf16 v[42:45], v[170:173], v[220:223], v[42:45]
	v_mfma_f32_16x16x32_bf16 v[30:33], v[160:163], v[228:231], v[30:33]
	v_mfma_f32_16x16x32_bf16 v[26:29], v[170:173], v[228:231], v[26:29]
	v_mfma_f32_16x16x32_bf16 v[14:17], v[160:163], v[236:239], v[14:17]
	v_mfma_f32_16x16x32_bf16 v[10:13], v[170:173], v[236:239], v[10:13]
	v_mfma_f32_16x16x32_bf16 v[62:65], v[164:167], v[216:219], v[62:65]
	v_mfma_f32_16x16x32_bf16 v[58:61], v[174:177], v[216:219], v[58:61]
	v_mfma_f32_16x16x32_bf16 v[46:49], v[164:167], v[224:227], v[46:49]
	v_mfma_f32_16x16x32_bf16 v[42:45], v[174:177], v[224:227], v[42:45]
	v_mfma_f32_16x16x32_bf16 v[30:33], v[164:167], v[232:235], v[30:33]
	v_mfma_f32_16x16x32_bf16 v[26:29], v[174:177], v[232:235], v[26:29]
	v_mfma_f32_16x16x32_bf16 v[14:17], v[164:167], v[240:243], v[14:17]
	v_mfma_f32_16x16x32_bf16 v[10:13], v[174:177], v[240:243], v[10:13]
	v_mfma_f32_16x16x32_bf16 v[54:57], v[178:181], v[212:215], v[54:57]
	v_mfma_f32_16x16x32_bf16 v[50:53], v[204:207], v[212:215], v[50:53]
	v_mfma_f32_16x16x32_bf16 v[38:41], v[178:181], v[220:223], v[38:41]
	v_mfma_f32_16x16x32_bf16 v[34:37], v[204:207], v[220:223], v[34:37]
	v_mfma_f32_16x16x32_bf16 v[22:25], v[178:181], v[228:231], v[22:25]
	v_mfma_f32_16x16x32_bf16 v[18:21], v[204:207], v[228:231], v[18:21]
	v_mfma_f32_16x16x32_bf16 v[6:9], v[178:181], v[236:239], v[6:9]
	v_mfma_f32_16x16x32_bf16 v[2:5], v[204:207], v[236:239], v[2:5]
	v_mfma_f32_16x16x32_bf16 v[54:57], v[182:185], v[216:219], v[54:57]
	v_mfma_f32_16x16x32_bf16 v[50:53], v[208:211], v[216:219], v[50:53]
	v_mfma_f32_16x16x32_bf16 v[38:41], v[182:185], v[224:227], v[38:41]
	v_mfma_f32_16x16x32_bf16 v[34:37], v[208:211], v[224:227], v[34:37]
	v_mfma_f32_16x16x32_bf16 v[22:25], v[182:185], v[232:235], v[22:25]
	v_mfma_f32_16x16x32_bf16 v[18:21], v[208:211], v[232:235], v[18:21]
	v_mfma_f32_16x16x32_bf16 v[6:9], v[182:185], v[240:243], v[6:9]
	v_mfma_f32_16x16x32_bf16 v[2:5], v[208:211], v[240:243], v[2:5]
	s_setprio 0
	s_barrier
	s_add_i32 s46, s46, 2
	s_add_u32 s60, s60, 0x100
	s_addc_u32 s73, s73, 0
	s_cmp_gt_u32 s46, 21
	s_mov_b64 s[36:37], s[42:43]
.LBB0_160:
	s_add_u32 s42, s36, 0x100
	s_addc_u32 s43, s37, 0
	s_add_i32 s47, 0, 0x10000
	s_cmp_eq_u32 s46, 20
	s_cselect_b32 s45, s1, s43
	s_cselect_b32 s44, s0, s42
	s_cselect_b32 s19, s7, s73
	s_cselect_b32 s18, s6, s60
	s_add_i32 s76, 0, 0x14000
	v_add_u32_e32 v174, s47, v143
	v_add_u32_e32 v186, s76, v143
	ds_read_b128 v[160:163], v174
	ds_read_b128 v[164:167], v174 offset:1024
	ds_read_b128 v[170:173], v174 offset:2048
	ds_read_b128 v[174:177], v174 offset:3072
	ds_read_b128 v[178:181], v186
	ds_read_b128 v[182:185], v186 offset:1024
	ds_read_b128 v[204:207], v186 offset:2048
	ds_read_b128 v[208:211], v186 offset:3072
	v_lshl_add_u64 v[186:187], s[36:37], 0, v[156:157]
	s_add_i32 m0, s54, 0xc000
	ds_read_b128 v[212:215], v169
	ds_read_b128 v[216:219], v169 offset:1024
	ds_read_b128 v[220:223], v169 offset:2048
	ds_read_b128 v[224:227], v169 offset:3072
	ds_read_b128 v[228:231], v169 offset:4096
	ds_read_b128 v[232:235], v169 offset:5120
	ds_read_b128 v[236:239], v169 offset:6144
	ds_read_b128 v[240:243], v169 offset:7168
	global_load_lds_dwordx4 v[186:187], off
	v_lshl_add_u64 v[186:187], s[36:37], 0, v[158:159]
	s_add_i32 m0, s54, 0xe000
	s_nop 0
	global_load_lds_dwordx4 v[186:187], off
	s_nop 0
	s_waitcnt vmcnt(8)
	s_waitcnt lgkmcnt(0)
	s_setprio 1
	s_barrier
; #define PG8_STAGE(bufoff, gbase, voff) do { _Pragma("unroll") for (int _i = 0; _i < 2; ++_i) \
;         __builtin_amdgcn_global_load_lds((const unsigned*)((const char*)(gbase) + (voff)[_i]), (PG8_LAS unsigned*)(lds + (bufoff) + ldsw + _i * 8192), 16, 0, 0); } while (0)
; #define PG8_LDA(dst, b, h) do { _Pragma("unroll") for (int m = 0; m < 4; ++m) _Pragma("unroll") for (int k = 0; k < 2; ++k) dst[m][k] = *(const PG8_LAS bf16x8*)(lds + PG8_SA(b, h) + aoff + m * 2048 + k * 1024); } while (0)
; #define PG8_MMA(ai, bj, At, Bt) do { __builtin_amdgcn_s_setprio(1); _Pragma("unroll") for (int m = 0; m < 4; ++m) _Pragma("unroll") for (int n = 0; n < 2; ++n) _Pragma("unroll") for (int k = 0; k < 2; ++k) \
;         acc[ai][bj][m][n] = __builtin_amdgcn_mfma_f32_16x16x32_bf16(Bt[n][k], At[m][k], acc[ai][bj][m][n], 0, 0, 0); __builtin_amdgcn_s_setprio(0); } while (0)
; #define PG8_WAIT_V(n) asm volatile("s_waitcnt vmcnt(" #n ")" ::: "memory")
; #define PG8_WAIT_L(n) asm volatile("s_waitcnt lgkmcnt(" #n ")" ::: "memory")
; #define PG8_BAR __builtin_amdgcn_s_barrier()
; #define PG8_SCHED __builtin_amdgcn_sched_barrier(0)
; template <class Epi, class Sched, bool ALIGN_EPI = false, bool SP2 = false>
; __device__ __forceinline__ void gemm_phase(PG8_LAS unsigned char* lds, const Gemm g, const Sched& S, const Epi& E) {
;     ...
;             PG8_WAIT_V(8); PG8_WAIT_L(0); PG8_BAR; PG8_MMA(0, 0, At, B0); PG8_MMA(0, 1, At, B1); PG8_BAR; PG8_SCHED;
;             PG8_LDA(At, 0, 1); PG8_STAGE(PG8_SB(0, 0), b2, voffB); PG8_STAGE(PG8_SB(0, 1), b2 + hstep, voffB); PG8_STAGE(PG8_SA(0, 0), a2, voffA);
;             PG8_WAIT_V(8); PG8_WAIT_L(0); PG8_BAR; PG8_MMA(1, 0, At, B0); PG8_MMA(1, 1, At, B1); PG8_BAR; PG8_SCHED;
	v_mfma_f32_16x16x32_bf16 v[126:129], v[160:163], v[212:215], v[126:129]
	v_mfma_f32_16x16x32_bf16 v[122:125], v[170:173], v[212:215], v[122:125]
	v_mfma_f32_16x16x32_bf16 v[110:113], v[160:163], v[220:223], v[110:113]
	v_mfma_f32_16x16x32_bf16 v[106:109], v[170:173], v[220:223], v[106:109]
	v_mfma_f32_16x16x32_bf16 v[94:97], v[160:163], v[228:231], v[94:97]
	v_mfma_f32_16x16x32_bf16 v[90:93], v[170:173], v[228:231], v[90:93]
	v_mfma_f32_16x16x32_bf16 v[78:81], v[160:163], v[236:239], v[78:81]
	v_mfma_f32_16x16x32_bf16 v[74:77], v[170:173], v[236:239], v[74:77]
	s_setprio 0
	s_setprio 1
	v_mfma_f32_16x16x32_bf16 v[126:129], v[164:167], v[216:219], v[126:129]
	v_mfma_f32_16x16x32_bf16 v[122:125], v[174:177], v[216:219], v[122:125]
	v_mfma_f32_16x16x32_bf16 v[110:113], v[164:167], v[224:227], v[110:113]
	v_mfma_f32_16x16x32_bf16 v[106:109], v[174:177], v[224:227], v[106:109]
	v_mfma_f32_16x16x32_bf16 v[94:97], v[164:167], v[232:235], v[94:97]
	v_mfma_f32_16x16x32_bf16 v[90:93], v[174:177], v[232:235], v[90:93]
	v_mfma_f32_16x16x32_bf16 v[78:81], v[164:167], v[240:243], v[78:81]
	v_mfma_f32_16x16x32_bf16 v[74:77], v[174:177], v[240:243], v[74:77]
	s_setprio 0
	s_setprio 1
	v_mfma_f32_16x16x32_bf16 v[118:121], v[178:181], v[212:215], v[118:121]
	v_mfma_f32_16x16x32_bf16 v[114:117], v[204:207], v[212:215], v[114:117]
	v_mfma_f32_16x16x32_bf16 v[102:105], v[178:181], v[220:223], v[102:105]
	v_mfma_f32_16x16x32_bf16 v[98:101], v[204:207], v[220:223], v[98:101]
	v_mfma_f32_16x16x32_bf16 v[86:89], v[178:181], v[228:231], v[86:89]
	v_mfma_f32_16x16x32_bf16 v[82:85], v[204:207], v[228:231], v[82:85]
	v_mfma_f32_16x16x32_bf16 v[70:73], v[178:181], v[236:239], v[70:73]
	v_mfma_f32_16x16x32_bf16 v[66:69], v[204:207], v[236:239], v[66:69]
	s_setprio 0
	s_setprio 1
	v_mfma_f32_16x16x32_bf16 v[118:121], v[182:185], v[216:219], v[118:121]
	v_mfma_f32_16x16x32_bf16 v[114:117], v[208:211], v[216:219], v[114:117]
	v_mfma_f32_16x16x32_bf16 v[102:105], v[182:185], v[224:227], v[102:105]
	v_mfma_f32_16x16x32_bf16 v[98:101], v[208:211], v[224:227], v[98:101]
	v_mfma_f32_16x16x32_bf16 v[86:89], v[182:185], v[232:235], v[86:89]
	v_mfma_f32_16x16x32_bf16 v[82:85], v[208:211], v[232:235], v[82:85]
	v_mfma_f32_16x16x32_bf16 v[70:73], v[182:185], v[240:243], v[70:73]
	v_mfma_f32_16x16x32_bf16 v[66:69], v[208:211], v[240:243], v[66:69]
	s_setprio 0
	s_barrier
	s_add_i32 s36, s47, s4
	v_lshl_add_u64 v[186:187], s[18:19], 0, v[148:149]
	s_mov_b32 m0, s36
	ds_read_b128 v[212:215], v169 offset:16384
	ds_read_b128 v[216:219], v169 offset:17408
	ds_read_b128 v[220:223], v169 offset:18432
	ds_read_b128 v[224:227], v169 offset:19456
	ds_read_b128 v[228:231], v169 offset:20480
	ds_read_b128 v[232:235], v169 offset:21504
	ds_read_b128 v[236:239], v169 offset:22528
	ds_read_b128 v[240:243], v169 offset:23552
	global_load_lds_dwordx4 v[186:187], off
	s_add_i32 m0, s36, 0x2000
	s_add_u32 s36, s18, 0x60000
	v_lshl_add_u64 v[244:245], s[18:19], 0, v[144:145]
	s_addc_u32 s37, s19, 0
	s_add_i32 s47, s76, s4
	global_load_lds_dwordx4 v[244:245], off
	v_lshl_add_u64 v[246:247], s[36:37], 0, v[148:149]
	s_mov_b32 m0, s47
	v_lshl_add_u64 v[248:249], s[44:45], 0, v[146:147]
	global_load_lds_dwordx4 v[246:247], off
	v_lshl_add_u64 v[246:247], s[36:37], 0, v[144:145]
	s_add_i32 m0, s47, 0x2000
	s_nop 0
	global_load_lds_dwordx4 v[246:247], off
	v_lshl_add_u64 v[246:247], s[44:45], 0, v[150:151]
	s_mov_b32 m0, s54
	s_nop 0
	global_load_lds_dwordx4 v[246:247], off
	s_mov_b32 m0, s57
	s_nop 0
	global_load_lds_dwordx4 v[248:249], off
	s_waitcnt vmcnt(8)
	s_waitcnt lgkmcnt(0)
	s_setprio 1
	s_barrier
	v_mfma_f32_16x16x32_bf16 v[62:65], v[160:163], v[212:215], v[62:65]
	v_mfma_f32_16x16x32_bf16 v[58:61], v[170:173], v[212:215], v[58:61]
	v_mfma_f32_16x16x32_bf16 v[46:49], v[160:163], v[220:223], v[46:49]
	v_mfma_f32_16x16x32_bf16 v[42:45], v[170:173], v[220:223], v[42:45]
	v_mfma_f32_16x16x32_bf16 v[30:33], v[160:163], v[228:231], v[30:33]
	v_mfma_f32_16x16x32_bf16 v[26:29], v[170:173], v[228:231], v[26:29]
	v_mfma_f32_16x16x32_bf16 v[14:17], v[160:163], v[236:239], v[14:17]
	v_mfma_f32_16x16x32_bf16 v[10:13], v[170:173], v[236:239], v[10:13]
	v_mfma_f32_16x16x32_bf16 v[62:65], v[164:167], v[216:219], v[62:65]
	v_mfma_f32_16x16x32_bf16 v[58:61], v[174:177], v[216:219], v[58:61]
	v_mfma_f32_16x16x32_bf16 v[46:49], v[164:167], v[224:227], v[46:49]
	v_mfma_f32_16x16x32_bf16 v[42:45], v[174:177], v[224:227], v[42:45]
	v_mfma_f32_16x16x32_bf16 v[30:33], v[164:167], v[232:235], v[30:33]
	v_mfma_f32_16x16x32_bf16 v[26:29], v[174:177], v[232:235], v[26:29]
	v_mfma_f32_16x16x32_bf16 v[14:17], v[164:167], v[240:243], v[14:17]
	v_mfma_f32_16x16x32_bf16 v[10:13], v[174:177], v[240:243], v[10:13]
	v_mfma_f32_16x16x32_bf16 v[54:57], v[178:181], v[212:215], v[54:57]
	v_mfma_f32_16x16x32_bf16 v[50:53], v[204:207], v[212:215], v[50:53]
	v_mfma_f32_16x16x32_bf16 v[38:41], v[178:181], v[220:223], v[38:41]
	v_mfma_f32_16x16x32_bf16 v[34:37], v[204:207], v[220:223], v[34:37]
	v_mfma_f32_16x16x32_bf16 v[22:25], v[178:181], v[228:231], v[22:25]
	v_mfma_f32_16x16x32_bf16 v[18:21], v[204:207], v[228:231], v[18:21]
	v_mfma_f32_16x16x32_bf16 v[6:9], v[178:181], v[236:239], v[6:9]
	v_mfma_f32_16x16x32_bf16 v[2:5], v[204:207], v[236:239], v[2:5]
	v_mfma_f32_16x16x32_bf16 v[54:57], v[182:185], v[216:219], v[54:57]
	v_mfma_f32_16x16x32_bf16 v[50:53], v[208:211], v[216:219], v[50:53]
	v_mfma_f32_16x16x32_bf16 v[38:41], v[182:185], v[224:227], v[38:41]
	v_mfma_f32_16x16x32_bf16 v[34:37], v[208:211], v[224:227], v[34:37]
	v_mfma_f32_16x16x32_bf16 v[22:25], v[182:185], v[232:235], v[22:25]
	v_mfma_f32_16x16x32_bf16 v[18:21], v[208:211], v[232:235], v[18:21]
	v_mfma_f32_16x16x32_bf16 v[6:9], v[182:185], v[240:243], v[6:9]
	v_mfma_f32_16x16x32_bf16 v[2:5], v[208:211], v[240:243], v[2:5]
	s_setprio 0
	s_barrier
; #define PG8_STAGE(bufoff, gbase, voff) do { _Pragma("unroll") for (int _i = 0; _i < 2; ++_i) \
;         __builtin_amdgcn_global_load_lds((const unsigned*)((const char*)(gbase) + (voff)[_i]), (PG8_LAS unsigned*)(lds + (bufoff) + ldsw + _i * 8192), 16, 0, 0); } while (0)
; #define PG8_LDA(dst, b, h) do { _Pragma("unroll") for (int m = 0; m < 4; ++m) _Pragma("unroll") for (int k = 0; k < 2; ++k) dst[m][k] = *(const PG8_LAS bf16x8*)(lds + PG8_SA(b, h) + aoff + m * 2048 + k * 1024); } while (0)
; #define PG8_LDB(dst, b, h) do { _Pragma("unroll") for (int n = 0; n < 2; ++n) _Pragma("unroll") for (int k = 0; k < 2; ++k) dst[n][k] = *(const PG8_LAS bf16x8*)(lds + PG8_SB(b, h) + boff + n * 2048 + k * 1024); } while (0)
; #define PG8_MMA(ai, bj, At, Bt) do { __builtin_amdgcn_s_setprio(1); _Pragma("unroll") for (int m = 0; m < 4; ++m) _Pragma("unroll") for (int n = 0; n < 2; ++n) _Pragma("unroll") for (int k = 0; k < 2; ++k) \
;         acc[ai][bj][m][n] = __builtin_amdgcn_mfma_f32_16x16x32_bf16(Bt[n][k], At[m][k], acc[ai][bj][m][n], 0, 0, 0); __builtin_amdgcn_s_setprio(0); } while (0)
; #define PG8_WAIT_V(n) asm volatile("s_waitcnt vmcnt(" #n ")" ::: "memory")
; #define PG8_WAIT_L(n) asm volatile("s_waitcnt lgkmcnt(" #n ")" ::: "memory")
; #define PG8_BAR __builtin_amdgcn_s_barrier()
; #define PG8_SCHED __builtin_amdgcn_sched_barrier(0)
; template <class Epi, class Sched, bool ALIGN_EPI = false, bool SP2 = false>
; __device__ __forceinline__ void gemm_phase(PG8_LAS unsigned char* lds, const Gemm g, const Sched& S, const Epi& E) {
;     ...
;             PG8_LDB(B0, 1, 0); PG8_LDB(B1, 1, 1); PG8_SCHED; PG8_LDA(At, 1, 0); PG8_STAGE(PG8_SA(0, 1), a2 + hstep, voffA);
;             PG8_WAIT_V(8); PG8_WAIT_L(0); PG8_BAR; PG8_MMA(0, 0, At, B0); PG8_MMA(0, 1, At, B1); PG8_BAR; PG8_SCHED;
;             PG8_LDA(At, 1, 1); PG8_STAGE(PG8_SB(1, 0), b3, voffB); PG8_STAGE(PG8_SB(1, 1), b3 + hstep, voffB); PG8_STAGE(PG8_SA(1, 0), a3, voffA);
	s_add_i32 s47, 0, 0x18000
	s_add_i32 s76, 0, 0x1c000
	v_add_u32_e32 v174, s47, v143
	v_add_u32_e32 v203, s76, v143
	ds_read_b128 v[160:163], v174
	ds_read_b128 v[164:167], v174 offset:1024
	ds_read_b128 v[170:173], v174 offset:2048
	ds_read_b128 v[174:177], v174 offset:3072
	ds_read_b128 v[178:181], v203
	ds_read_b128 v[182:185], v203 offset:1024
	ds_read_b128 v[204:207], v203 offset:2048
	ds_read_b128 v[208:211], v203 offset:3072
	s_add_u32 s36, s44, 0x60000
	s_addc_u32 s37, s45, 0
	s_mov_b32 m0, s58
	v_lshl_add_u64 v[250:251], s[36:37], 0, v[150:151]
	ds_read_b128 v[212:215], v169 offset:32768
	ds_read_b128 v[216:219], v169 offset:33792
	ds_read_b128 v[220:223], v169 offset:34816
	ds_read_b128 v[224:227], v169 offset:35840
	ds_read_b128 v[228:231], v169 offset:36864
	ds_read_b128 v[232:235], v169 offset:37888
	ds_read_b128 v[236:239], v169 offset:38912
	ds_read_b128 v[240:243], v169 offset:39936
	global_load_lds_dwordx4 v[250:251], off
	v_lshl_add_u64 v[250:251], s[36:37], 0, v[146:147]
	s_mov_b32 m0, s59
	s_nop 0
	global_load_lds_dwordx4 v[250:251], off
	s_waitcnt vmcnt(8)
	s_waitcnt lgkmcnt(0)
	s_setprio 1
	s_barrier
	v_mfma_f32_16x16x32_bf16 v[126:129], v[160:163], v[212:215], v[126:129]
	v_mfma_f32_16x16x32_bf16 v[122:125], v[170:173], v[212:215], v[122:125]
	v_mfma_f32_16x16x32_bf16 v[110:113], v[160:163], v[220:223], v[110:113]
	v_mfma_f32_16x16x32_bf16 v[106:109], v[170:173], v[220:223], v[106:109]
	v_mfma_f32_16x16x32_bf16 v[94:97], v[160:163], v[228:231], v[94:97]
	v_mfma_f32_16x16x32_bf16 v[90:93], v[170:173], v[228:231], v[90:93]
	v_mfma_f32_16x16x32_bf16 v[78:81], v[160:163], v[236:239], v[78:81]
	v_mfma_f32_16x16x32_bf16 v[74:77], v[170:173], v[236:239], v[74:77]
	s_setprio 0
	s_setprio 1
	v_mfma_f32_16x16x32_bf16 v[126:129], v[164:167], v[216:219], v[126:129]
	v_mfma_f32_16x16x32_bf16 v[122:125], v[174:177], v[216:219], v[122:125]
	v_mfma_f32_16x16x32_bf16 v[110:113], v[164:167], v[224:227], v[110:113]
	v_mfma_f32_16x16x32_bf16 v[106:109], v[174:177], v[224:227], v[106:109]
	v_mfma_f32_16x16x32_bf16 v[94:97], v[164:167], v[232:235], v[94:97]
	v_mfma_f32_16x16x32_bf16 v[90:93], v[174:177], v[232:235], v[90:93]
	v_mfma_f32_16x16x32_bf16 v[78:81], v[164:167], v[240:243], v[78:81]
	v_mfma_f32_16x16x32_bf16 v[74:77], v[174:177], v[240:243], v[74:77]
	s_setprio 0
	s_setprio 1
	v_mfma_f32_16x16x32_bf16 v[118:121], v[178:181], v[212:215], v[118:121]
	v_mfma_f32_16x16x32_bf16 v[114:117], v[204:207], v[212:215], v[114:117]
	v_mfma_f32_16x16x32_bf16 v[102:105], v[178:181], v[220:223], v[102:105]
	v_mfma_f32_16x16x32_bf16 v[98:101], v[204:207], v[220:223], v[98:101]
	v_mfma_f32_16x16x32_bf16 v[86:89], v[178:181], v[228:231], v[86:89]
	v_mfma_f32_16x16x32_bf16 v[82:85], v[204:207], v[228:231], v[82:85]
	v_mfma_f32_16x16x32_bf16 v[70:73], v[178:181], v[236:239], v[70:73]
	v_mfma_f32_16x16x32_bf16 v[66:69], v[204:207], v[236:239], v[66:69]
	s_setprio 0
	s_setprio 1
	v_mfma_f32_16x16x32_bf16 v[118:121], v[182:185], v[216:219], v[118:121]
	v_mfma_f32_16x16x32_bf16 v[114:117], v[208:211], v[216:219], v[114:117]
	v_mfma_f32_16x16x32_bf16 v[102:105], v[182:185], v[224:227], v[102:105]
	v_mfma_f32_16x16x32_bf16 v[98:101], v[208:211], v[224:227], v[98:101]
	v_mfma_f32_16x16x32_bf16 v[86:89], v[182:185], v[232:235], v[86:89]
	v_mfma_f32_16x16x32_bf16 v[82:85], v[208:211], v[232:235], v[82:85]
	v_mfma_f32_16x16x32_bf16 v[70:73], v[182:185], v[240:243], v[70:73]
	v_mfma_f32_16x16x32_bf16 v[66:69], v[208:211], v[240:243], v[66:69]
	s_setprio 0
	s_barrier
; #define PG8_STAGE(bufoff, gbase, voff) do { _Pragma("unroll") for (int _i = 0; _i < 2; ++_i) \
;         __builtin_amdgcn_global_load_lds((const unsigned*)((const char*)(gbase) + (voff)[_i]), (PG8_LAS unsigned*)(lds + (bufoff) + ldsw + _i * 8192), 16, 0, 0); } while (0)
; #define PG8_LDA(dst, b, h) do { _Pragma("unroll") for (int m = 0; m < 4; ++m) _Pragma("unroll") for (int k = 0; k < 2; ++k) dst[m][k] = *(const PG8_LAS bf16x8*)(lds + PG8_SA(b, h) + aoff + m * 2048 + k * 1024); } while (0)
; #define PG8_MMA(ai, bj, At, Bt) do { __builtin_amdgcn_s_setprio(1); _Pragma("unroll") for (int m = 0; m < 4; ++m) _Pragma("unroll") for (int n = 0; n < 2; ++n) _Pragma("unroll") for (int k = 0; k < 2; ++k) \
;         acc[ai][bj][m][n] = __builtin_amdgcn_mfma_f32_16x16x32_bf16(Bt[n][k], At[m][k], acc[ai][bj][m][n], 0, 0, 0); __builtin_amdgcn_s_setprio(0); } while (0)
; #define PG8_WAIT_V(n) asm volatile("s_waitcnt vmcnt(" #n ")" ::: "memory")
; #define PG8_WAIT_L(n) asm volatile("s_waitcnt lgkmcnt(" #n ")" ::: "memory")
; #define PG8_BAR __builtin_amdgcn_s_barrier()
; #define PG8_SCHED __builtin_amdgcn_sched_barrier(0)
; template <class Epi, class Sched, bool ALIGN_EPI = false, bool SP2 = false>
; __device__ __forceinline__ void gemm_phase(PG8_LAS unsigned char* lds, const Gemm g, const Sched& S, const Epi& E) {
;     ...
;             PG8_LDA(At, 1, 1); PG8_STAGE(PG8_SB(1, 0), b3, voffB); PG8_STAGE(PG8_SB(1, 1), b3 + hstep, voffB); PG8_STAGE(PG8_SA(1, 0), a3, voffA);
;             PG8_WAIT_V(8); PG8_WAIT_L(0); PG8_BAR; PG8_MMA(1, 0, At, B0); PG8_MMA(1, 1, At, B1); PG8_BAR; PG8_SCHED;
;     ...
;         if constexpr (ALIGN_EPI) { if (wr == 0) PG8_BAR; }
;         if constexpr (!Epi::AFTER_DRAIN) { E(acc, cur, wr, wc, fr, fq); S.done(cur); }
;         if (!has_next) break;
	s_add_i32 s36, s47, s4
	v_lshl_add_u64 v[186:187], v[186:187], 0, s[68:69]
	s_mov_b32 m0, s36
	ds_read_b128 v[212:215], v169 offset:49152
	ds_read_b128 v[216:219], v169 offset:50176
	ds_read_b128 v[220:223], v169 offset:51200
	ds_read_b128 v[224:227], v169 offset:52224
	ds_read_b128 v[228:231], v169 offset:53248
	ds_read_b128 v[232:235], v169 offset:54272
	ds_read_b128 v[236:239], v169 offset:55296
	ds_read_b128 v[240:243], v169 offset:56320
	global_load_lds_dwordx4 v[186:187], off
	s_add_i32 m0, s36, 0x2000
	s_add_u32 s18, s18, 0x60080
	v_lshl_add_u64 v[186:187], v[244:245], 0, s[68:69]
	s_addc_u32 s19, s19, 0
	s_add_i32 s36, s76, s4
	global_load_lds_dwordx4 v[186:187], off
	v_lshl_add_u64 v[186:187], s[18:19], 0, v[148:149]
	s_mov_b32 m0, s36
	s_nop 0
	global_load_lds_dwordx4 v[186:187], off
	v_lshl_add_u64 v[186:187], s[18:19], 0, v[144:145]
	s_add_i32 m0, s36, 0x2000
	s_nop 0
	global_load_lds_dwordx4 v[186:187], off
	v_lshl_add_u64 v[186:187], v[246:247], 0, s[68:69]
	s_mov_b32 m0, s62
	s_nop 0
	global_load_lds_dwordx4 v[186:187], off
	v_lshl_add_u64 v[186:187], v[248:249], 0, s[68:69]
	s_mov_b32 m0, s63
	s_nop 0
	global_load_lds_dwordx4 v[186:187], off
	s_nop 0
	s_waitcnt vmcnt(8)
	s_waitcnt lgkmcnt(0)
	s_setprio 1
	s_barrier
	v_mfma_f32_16x16x32_bf16 v[62:65], v[160:163], v[212:215], v[62:65]
	v_mfma_f32_16x16x32_bf16 v[58:61], v[170:173], v[212:215], v[58:61]
	v_mfma_f32_16x16x32_bf16 v[46:49], v[160:163], v[220:223], v[46:49]
	v_mfma_f32_16x16x32_bf16 v[42:45], v[170:173], v[220:223], v[42:45]
	v_mfma_f32_16x16x32_bf16 v[30:33], v[160:163], v[228:231], v[30:33]
	v_mfma_f32_16x16x32_bf16 v[26:29], v[170:173], v[228:231], v[26:29]
	v_mfma_f32_16x16x32_bf16 v[14:17], v[160:163], v[236:239], v[14:17]
	v_mfma_f32_16x16x32_bf16 v[10:13], v[170:173], v[236:239], v[10:13]
	v_mfma_f32_16x16x32_bf16 v[62:65], v[164:167], v[216:219], v[62:65]
	v_mfma_f32_16x16x32_bf16 v[58:61], v[174:177], v[216:219], v[58:61]
	v_mfma_f32_16x16x32_bf16 v[46:49], v[164:167], v[224:227], v[46:49]
	v_mfma_f32_16x16x32_bf16 v[42:45], v[174:177], v[224:227], v[42:45]
	v_mfma_f32_16x16x32_bf16 v[30:33], v[164:167], v[232:235], v[30:33]
	v_mfma_f32_16x16x32_bf16 v[26:29], v[174:177], v[232:235], v[26:29]
	v_mfma_f32_16x16x32_bf16 v[14:17], v[164:167], v[240:243], v[14:17]
	v_mfma_f32_16x16x32_bf16 v[10:13], v[174:177], v[240:243], v[10:13]
	v_mfma_f32_16x16x32_bf16 v[54:57], v[178:181], v[212:215], v[54:57]
	v_mfma_f32_16x16x32_bf16 v[50:53], v[204:207], v[212:215], v[50:53]
	v_mfma_f32_16x16x32_bf16 v[38:41], v[178:181], v[220:223], v[38:41]
	v_mfma_f32_16x16x32_bf16 v[34:37], v[204:207], v[220:223], v[34:37]
	v_mfma_f32_16x16x32_bf16 v[22:25], v[178:181], v[228:231], v[22:25]
	v_mfma_f32_16x16x32_bf16 v[18:21], v[204:207], v[228:231], v[18:21]
	v_mfma_f32_16x16x32_bf16 v[6:9], v[178:181], v[236:239], v[6:9]
	v_mfma_f32_16x16x32_bf16 v[2:5], v[204:207], v[236:239], v[2:5]
	v_mfma_f32_16x16x32_bf16 v[54:57], v[182:185], v[216:219], v[54:57]
	v_mfma_f32_16x16x32_bf16 v[50:53], v[208:211], v[216:219], v[50:53]
	v_mfma_f32_16x16x32_bf16 v[38:41], v[182:185], v[224:227], v[38:41]
	v_mfma_f32_16x16x32_bf16 v[34:37], v[208:211], v[224:227], v[34:37]
	v_mfma_f32_16x16x32_bf16 v[22:25], v[182:185], v[232:235], v[22:25]
	v_mfma_f32_16x16x32_bf16 v[18:21], v[208:211], v[232:235], v[18:21]
	v_mfma_f32_16x16x32_bf16 v[6:9], v[182:185], v[240:243], v[6:9]
	v_mfma_f32_16x16x32_bf16 v[2:5], v[208:211], v[240:243], v[2:5]
	s_setprio 0
	s_barrier
	s_add_i32 s46, s46, 2
	s_add_u32 s60, s60, 0x100
	s_addc_u32 s73, s73, 0
	s_cmp_gt_u32 s46, 21
	s_mov_b64 s[36:37], s[42:43]
	s_cbranch_scc0 .LBB0_160
	s_and_b64 vcc, exec, s[10:11]
	s_cbranch_vccz .LBB0_163
	s_barrier

; #define PG8_STAGE(bufoff, gbase, voff) do { _Pragma("unroll") for (int _i = 0; _i < 2; ++_i) \
;         __builtin_amdgcn_global_load_lds((const unsigned*)((const char*)(gbase) + (voff)[_i]), (PG8_LAS unsigned*)(lds + (bufoff) + ldsw + _i * 8192), 16, 0, 0); } while (0)
; #define PG8_LDA(dst, b, h) do { _Pragma("unroll") for (int m = 0; m < 4; ++m) _Pragma("unroll") for (int k = 0; k < 2; ++k) dst[m][k] = *(const PG8_LAS bf16x8*)(lds + PG8_SA(b, h) + aoff + m * 2048 + k * 1024); } while (0)
; #define PG8_LDB(dst, b, h) do { _Pragma("unroll") for (int n = 0; n < 2; ++n) _Pragma("unroll") for (int k = 0; k < 2; ++k) dst[n][k] = *(const PG8_LAS bf16x8*)(lds + PG8_SB(b, h) + boff + n * 2048 + k * 1024); } while (0)
; #define PG8_WAIT_V(n) asm volatile("s_waitcnt vmcnt(" #n ")" ::: "memory")
; #define PG8_WAIT_L(n) asm volatile("s_waitcnt lgkmcnt(" #n ")" ::: "memory")
; #define PG8_BAR __builtin_amdgcn_s_barrier()
; #define PG8_SCHED __builtin_amdgcn_sched_barrier(0)
; template <class Epi, class Sched, bool ALIGN_EPI = false, bool SP2 = false>
; __device__ __forceinline__ void gemm_phase(PG8_LAS unsigned char* lds, const Gemm g, const Sched& S, const Epi& E) {
;     ...
;         const bool has_next = S.next(ui + 1, nxt);
;         const char* nA = has_next ? (const char*)g.A + (size_t)nxt.pm * tstep : cA; const char* nB = has_next ? (const char*)g.Bt + (size_t)nxt.pn * tstep : cB;
;         for (int t = 0; t < nt; t += 2) {
;             const bool last = (t == nt - 2);
;             const char* a1 = cA + (size_t)(t + 1) * kstep;
;             const char* a2 = last ? nA : cA + (size_t)(t + 2) * kstep; const char* b2 = last ? nB : cB + (size_t)(t + 2) * kstep;
;             const char* a3 = a2 + kstep; const char* b3 = b2 + kstep;
;             if (last && has_next) S.a_ready(nxt);
;             if constexpr (SP2) {
;             PG8_LDB(B0, 0, 0); PG8_LDB(B1, 0, 1); PG8_SCHED; PG8_LDA(At, 0, 0); PG8_STAGE(PG8_SA(1, 1), a1 + hstep, voffA);
;             PG8_WAIT_V(8); PG8_WAIT_L(0); PG8_BAR; PG8_MMA(0, 0, At, B0); PG8_MMA(0, 1, At, B1); PG8_BAR; PG8_SCHED;
;             PG8_LDA(At, 0, 1); PG8_STAGE(PG8_SB(0, 0), b2, voffB); PG8_STAGE(PG8_SB(0, 1), b2 + hstep, voffB); PG8_STAGE(PG8_SA(0, 0), a2, voffA);
;             PG8_WAIT_V(8); PG8_WAIT_L(0); PG8_BAR; PG8_MMA(1, 0, At, B0); PG8_MMA(1, 1, At, B1); PG8_BAR; PG8_SCHED;
.LBB0_280:
	s_ashr_i32 s9, s8, 31
	s_lshl_b64 s[10:11], s[8:9], 20
	s_add_u32 s10, s70, s10
	s_addc_u32 s11, s71, s11
	s_and_b64 s[12:13], s[40:41], exec
	s_cselect_b32 s9, s11, s37
	s_cselect_b32 s59, s10, s36
	s_ashr_i32 s7, s6, 31
	s_lshl_b64 s[12:13], s[6:7], 20
	s_add_u32 s12, s74, s12
	s_addc_u32 s13, s75, s13
	s_and_b64 s[42:43], s[40:41], exec
	s_cselect_b32 s7, s13, s19
	s_cselect_b32 s60, s12, s18
	s_add_u32 s36, s36, 0x80080
	s_addc_u32 s37, s37, 0
	s_add_u32 s62, s18, 0x100
	s_addc_u32 s63, s19, 0
	s_mov_b32 s67, -2
	s_add_u32 s18, s36, 0xfff80080
	s_addc_u32 s19, s37, -1
	s_add_i32 s73, 0, 0x10000
	s_cmp_eq_u32 s67, 28
	s_cselect_b32 s43, s9, s19
	s_cselect_b32 s42, s59, s18
	v_add_u32_e32 v163, s73, v160
	s_cselect_b32 s19, s7, s63
	s_cselect_b32 s18, s60, s62
	s_add_i32 s76, 0, 0x14000
	ds_read_b128 v[156:159], v163
	ds_read_b128 v[164:167], v163 offset:1024
	ds_read_b128 v[168:171], v163 offset:2048
	ds_read_b128 v[172:175], v163 offset:3072
	v_add_u32_e32 v163, s76, v160
	ds_read_b128 v[176:179], v163
	ds_read_b128 v[180:183], v163 offset:1024
	ds_read_b128 v[184:187], v163 offset:2048
	ds_read_b128 v[204:207], v163 offset:3072
	v_lshl_add_u64 v[240:241], s[36:37], 0, v[152:153]
	s_add_i32 m0, s30, 0xc000
	ds_read_b128 v[208:211], v162
	ds_read_b128 v[212:215], v162 offset:1024
	ds_read_b128 v[216:219], v162 offset:2048
	ds_read_b128 v[220:223], v162 offset:3072
	ds_read_b128 v[224:227], v162 offset:4096
	ds_read_b128 v[228:231], v162 offset:5120
	ds_read_b128 v[232:235], v162 offset:6144
	ds_read_b128 v[236:239], v162 offset:7168
	global_load_lds_dwordx4 v[240:241], off
	v_lshl_add_u64 v[240:241], s[36:37], 0, v[154:155]
	s_add_i32 m0, s30, 0xe000
	s_nop 0
	global_load_lds_dwordx4 v[240:241], off
	s_nop 0
	s_nop 0
	s_waitcnt vmcnt(8)
	s_waitcnt lgkmcnt(0)
	s_setprio 1
	s_barrier
	v_mfma_f32_16x16x32_bf16 v[126:129], v[156:159], v[208:211], 0
	v_mfma_f32_16x16x32_bf16 v[122:125], v[168:171], v[208:211], 0
	v_mfma_f32_16x16x32_bf16 v[110:113], v[156:159], v[216:219], 0
	v_mfma_f32_16x16x32_bf16 v[106:109], v[168:171], v[216:219], 0
	v_mfma_f32_16x16x32_bf16 v[94:97], v[156:159], v[224:227], 0
	v_mfma_f32_16x16x32_bf16 v[90:93], v[168:171], v[224:227], 0
	v_mfma_f32_16x16x32_bf16 v[78:81], v[156:159], v[232:235], 0
	v_mfma_f32_16x16x32_bf16 v[74:77], v[168:171], v[232:235], 0
	s_setprio 0
	s_setprio 1
	v_mfma_f32_16x16x32_bf16 v[126:129], v[164:167], v[212:215], v[126:129]
	v_mfma_f32_16x16x32_bf16 v[122:125], v[172:175], v[212:215], v[122:125]
	v_mfma_f32_16x16x32_bf16 v[110:113], v[164:167], v[220:223], v[110:113]
	v_mfma_f32_16x16x32_bf16 v[106:109], v[172:175], v[220:223], v[106:109]
	v_mfma_f32_16x16x32_bf16 v[94:97], v[164:167], v[228:231], v[94:97]
	v_mfma_f32_16x16x32_bf16 v[90:93], v[172:175], v[228:231], v[90:93]
	v_mfma_f32_16x16x32_bf16 v[78:81], v[164:167], v[236:239], v[78:81]
	v_mfma_f32_16x16x32_bf16 v[74:77], v[172:175], v[236:239], v[74:77]
	s_setprio 0
	s_setprio 1
	v_mfma_f32_16x16x32_bf16 v[118:121], v[176:179], v[208:211], 0
	v_mfma_f32_16x16x32_bf16 v[114:117], v[184:187], v[208:211], 0
	v_mfma_f32_16x16x32_bf16 v[102:105], v[176:179], v[216:219], 0
	v_mfma_f32_16x16x32_bf16 v[98:101], v[184:187], v[216:219], 0
	v_mfma_f32_16x16x32_bf16 v[86:89], v[176:179], v[224:227], 0
	v_mfma_f32_16x16x32_bf16 v[82:85], v[184:187], v[224:227], 0
	v_mfma_f32_16x16x32_bf16 v[70:73], v[176:179], v[232:235], 0
	v_mfma_f32_16x16x32_bf16 v[66:69], v[184:187], v[232:235], 0
	s_setprio 0
	s_setprio 1
	v_mfma_f32_16x16x32_bf16 v[118:121], v[180:183], v[212:215], v[118:121]
	v_mfma_f32_16x16x32_bf16 v[114:117], v[204:207], v[212:215], v[114:117]
	v_mfma_f32_16x16x32_bf16 v[102:105], v[180:183], v[220:223], v[102:105]
	v_mfma_f32_16x16x32_bf16 v[98:101], v[204:207], v[220:223], v[98:101]
	v_mfma_f32_16x16x32_bf16 v[86:89], v[180:183], v[228:231], v[86:89]
	v_mfma_f32_16x16x32_bf16 v[82:85], v[204:207], v[228:231], v[82:85]
	v_mfma_f32_16x16x32_bf16 v[70:73], v[180:183], v[236:239], v[70:73]
	v_mfma_f32_16x16x32_bf16 v[66:69], v[204:207], v[236:239], v[66:69]
	s_setprio 0
	s_barrier
	s_add_i32 s73, s73, s28
	v_lshl_add_u64 v[240:241], s[18:19], 0, v[146:147]
	s_mov_b32 m0, s73
	ds_read_b128 v[208:211], v162 offset:16384
	ds_read_b128 v[212:215], v162 offset:17408
	ds_read_b128 v[216:219], v162 offset:18432
	ds_read_b128 v[220:223], v162 offset:19456
	ds_read_b128 v[224:227], v162 offset:20480
	ds_read_b128 v[228:231], v162 offset:21504
	ds_read_b128 v[232:235], v162 offset:22528
	ds_read_b128 v[236:239], v162 offset:23552
	global_load_lds_dwordx4 v[240:241], off
	s_add_i32 m0, s73, 0x2000
	s_add_u32 s78, s18, 0x80000
	v_lshl_add_u64 v[242:243], s[18:19], 0, v[142:143]
	s_addc_u32 s79, s19, 0
	s_add_i32 s73, s76, s28
	global_load_lds_dwordx4 v[242:243], off
	v_lshl_add_u64 v[244:245], s[78:79], 0, v[146:147]
	s_mov_b32 m0, s73
	v_lshl_add_u64 v[246:247], s[42:43], 0, v[144:145]
	global_load_lds_dwordx4 v[244:245], off
	v_lshl_add_u64 v[244:245], s[78:79], 0, v[142:143]
	s_add_i32 m0, s73, 0x2000
	s_nop 0
	global_load_lds_dwordx4 v[244:245], off
	v_lshl_add_u64 v[244:245], s[42:43], 0, v[148:149]
	s_mov_b32 m0, s30
	s_nop 0
	global_load_lds_dwordx4 v[244:245], off
	s_mov_b32 m0, s34
	s_nop 0
	global_load_lds_dwordx4 v[246:247], off
	s_waitcnt vmcnt(8)
	s_waitcnt lgkmcnt(0)
	s_setprio 1
	s_barrier
; #define PG8_STAGE(bufoff, gbase, voff) do { _Pragma("unroll") for (int _i = 0; _i < 2; ++_i) \
;         __builtin_amdgcn_global_load_lds((const unsigned*)((const char*)(gbase) + (voff)[_i]), (PG8_LAS unsigned*)(lds + (bufoff) + ldsw + _i * 8192), 16, 0, 0); } while (0)
; #define PG8_LDA(dst, b, h) do { _Pragma("unroll") for (int m = 0; m < 4; ++m) _Pragma("unroll") for (int k = 0; k < 2; ++k) dst[m][k] = *(const PG8_LAS bf16x8*)(lds + PG8_SA(b, h) + aoff + m * 2048 + k * 1024); } while (0)
; #define PG8_LDB(dst, b, h) do { _Pragma("unroll") for (int n = 0; n < 2; ++n) _Pragma("unroll") for (int k = 0; k < 2; ++k) dst[n][k] = *(const PG8_LAS bf16x8*)(lds + PG8_SB(b, h) + boff + n * 2048 + k * 1024); } while (0)
; #define PG8_MMA(ai, bj, At, Bt) do { __builtin_amdgcn_s_setprio(1); _Pragma("unroll") for (int m = 0; m < 4; ++m) _Pragma("unroll") for (int n = 0; n < 2; ++n) _Pragma("unroll") for (int k = 0; k < 2; ++k) \
;         acc[ai][bj][m][n] = __builtin_amdgcn_mfma_f32_16x16x32_bf16(Bt[n][k], At[m][k], acc[ai][bj][m][n], 0, 0, 0); __builtin_amdgcn_s_setprio(0); } while (0)
; #define PG8_WAIT_V(n) asm volatile("s_waitcnt vmcnt(" #n ")" ::: "memory")
; #define PG8_WAIT_L(n) asm volatile("s_waitcnt lgkmcnt(" #n ")" ::: "memory")
; #define PG8_BAR __builtin_amdgcn_s_barrier()
; #define PG8_SCHED __builtin_amdgcn_sched_barrier(0)
; template <class Epi, class Sched, bool ALIGN_EPI = false, bool SP2 = false>
; __device__ __forceinline__ void gemm_phase(PG8_LAS unsigned char* lds, const Gemm g, const Sched& S, const Epi& E) {
;     ...
;             PG8_WAIT_V(8); PG8_WAIT_L(0); PG8_BAR; PG8_MMA(1, 0, At, B0); PG8_MMA(1, 1, At, B1); PG8_BAR; PG8_SCHED;
;             PG8_LDB(B0, 1, 0); PG8_LDB(B1, 1, 1); PG8_SCHED; PG8_LDA(At, 1, 0); PG8_STAGE(PG8_SA(0, 1), a2 + hstep, voffA);
;             PG8_WAIT_V(8); PG8_WAIT_L(0); PG8_BAR; PG8_MMA(0, 0, At, B0); PG8_MMA(0, 1, At, B1); PG8_BAR; PG8_SCHED;
;             PG8_LDA(At, 1, 1); PG8_STAGE(PG8_SB(1, 0), b3, voffB); PG8_STAGE(PG8_SB(1, 1), b3 + hstep, voffB); PG8_STAGE(PG8_SA(1, 0), a3, voffA);
	v_mfma_f32_16x16x32_bf16 v[62:65], v[156:159], v[208:211], 0
	v_mfma_f32_16x16x32_bf16 v[58:61], v[168:171], v[208:211], 0
	v_mfma_f32_16x16x32_bf16 v[46:49], v[156:159], v[216:219], 0
	v_mfma_f32_16x16x32_bf16 v[42:45], v[168:171], v[216:219], 0
	v_mfma_f32_16x16x32_bf16 v[30:33], v[156:159], v[224:227], 0
	v_mfma_f32_16x16x32_bf16 v[26:29], v[168:171], v[224:227], 0
	v_mfma_f32_16x16x32_bf16 v[14:17], v[156:159], v[232:235], 0
	v_mfma_f32_16x16x32_bf16 v[10:13], v[168:171], v[232:235], 0
	v_mfma_f32_16x16x32_bf16 v[62:65], v[164:167], v[212:215], v[62:65]
	v_mfma_f32_16x16x32_bf16 v[58:61], v[172:175], v[212:215], v[58:61]
	v_mfma_f32_16x16x32_bf16 v[46:49], v[164:167], v[220:223], v[46:49]
	v_mfma_f32_16x16x32_bf16 v[42:45], v[172:175], v[220:223], v[42:45]
	v_mfma_f32_16x16x32_bf16 v[30:33], v[164:167], v[228:231], v[30:33]
	v_mfma_f32_16x16x32_bf16 v[26:29], v[172:175], v[228:231], v[26:29]
	v_mfma_f32_16x16x32_bf16 v[14:17], v[164:167], v[236:239], v[14:17]
	v_mfma_f32_16x16x32_bf16 v[10:13], v[172:175], v[236:239], v[10:13]
	v_mfma_f32_16x16x32_bf16 v[54:57], v[176:179], v[208:211], 0
	v_mfma_f32_16x16x32_bf16 v[50:53], v[184:187], v[208:211], 0
	v_mfma_f32_16x16x32_bf16 v[38:41], v[176:179], v[216:219], 0
	v_mfma_f32_16x16x32_bf16 v[34:37], v[184:187], v[216:219], 0
	v_mfma_f32_16x16x32_bf16 v[22:25], v[176:179], v[224:227], 0
	v_mfma_f32_16x16x32_bf16 v[18:21], v[184:187], v[224:227], 0
	v_mfma_f32_16x16x32_bf16 v[6:9], v[176:179], v[232:235], 0
	v_mfma_f32_16x16x32_bf16 v[2:5], v[184:187], v[232:235], 0
	v_mfma_f32_16x16x32_bf16 v[54:57], v[180:183], v[212:215], v[54:57]
	v_mfma_f32_16x16x32_bf16 v[50:53], v[204:207], v[212:215], v[50:53]
	v_mfma_f32_16x16x32_bf16 v[38:41], v[180:183], v[220:223], v[38:41]
	v_mfma_f32_16x16x32_bf16 v[34:37], v[204:207], v[220:223], v[34:37]
	v_mfma_f32_16x16x32_bf16 v[22:25], v[180:183], v[228:231], v[22:25]
	v_mfma_f32_16x16x32_bf16 v[18:21], v[204:207], v[228:231], v[18:21]
	v_mfma_f32_16x16x32_bf16 v[6:9], v[180:183], v[236:239], v[6:9]
	v_mfma_f32_16x16x32_bf16 v[2:5], v[204:207], v[236:239], v[2:5]
	s_setprio 0
	s_barrier
	s_add_i32 s73, 0, 0x18000
	v_add_u32_e32 v163, s73, v160
	s_add_i32 s76, 0, 0x1c000
	ds_read_b128 v[156:159], v163
	ds_read_b128 v[164:167], v163 offset:1024
	ds_read_b128 v[168:171], v163 offset:2048
	ds_read_b128 v[172:175], v163 offset:3072
	v_add_u32_e32 v163, s76, v160
	ds_read_b128 v[176:179], v163
	ds_read_b128 v[180:183], v163 offset:1024
	ds_read_b128 v[184:187], v163 offset:2048
	ds_read_b128 v[204:207], v163 offset:3072
	s_add_u32 s42, s42, 0x80000
	s_addc_u32 s43, s43, 0
	s_mov_b32 m0, s44
	v_lshl_add_u64 v[248:249], s[42:43], 0, v[148:149]
	ds_read_b128 v[208:211], v162 offset:32768
	ds_read_b128 v[212:215], v162 offset:33792
	ds_read_b128 v[216:219], v162 offset:34816
	ds_read_b128 v[220:223], v162 offset:35840
	ds_read_b128 v[224:227], v162 offset:36864
	ds_read_b128 v[228:231], v162 offset:37888
	ds_read_b128 v[232:235], v162 offset:38912
	ds_read_b128 v[236:239], v162 offset:39936
	global_load_lds_dwordx4 v[248:249], off
	v_lshl_add_u64 v[248:249], s[42:43], 0, v[144:145]
	s_mov_b32 m0, s45
	s_nop 0
	global_load_lds_dwordx4 v[248:249], off
	s_waitcnt vmcnt(8)
	s_waitcnt lgkmcnt(0)
	s_setprio 1
	s_barrier
	v_mfma_f32_16x16x32_bf16 v[126:129], v[156:159], v[208:211], v[126:129]
	v_mfma_f32_16x16x32_bf16 v[122:125], v[168:171], v[208:211], v[122:125]
	v_mfma_f32_16x16x32_bf16 v[110:113], v[156:159], v[216:219], v[110:113]
	v_mfma_f32_16x16x32_bf16 v[106:109], v[168:171], v[216:219], v[106:109]
	v_mfma_f32_16x16x32_bf16 v[94:97], v[156:159], v[224:227], v[94:97]
	v_mfma_f32_16x16x32_bf16 v[90:93], v[168:171], v[224:227], v[90:93]
	v_mfma_f32_16x16x32_bf16 v[78:81], v[156:159], v[232:235], v[78:81]
	v_mfma_f32_16x16x32_bf16 v[74:77], v[168:171], v[232:235], v[74:77]
	s_setprio 0
	s_setprio 1
	v_mfma_f32_16x16x32_bf16 v[126:129], v[164:167], v[212:215], v[126:129]
	v_mfma_f32_16x16x32_bf16 v[122:125], v[172:175], v[212:215], v[122:125]
	v_mfma_f32_16x16x32_bf16 v[110:113], v[164:167], v[220:223], v[110:113]
	v_mfma_f32_16x16x32_bf16 v[106:109], v[172:175], v[220:223], v[106:109]
	v_mfma_f32_16x16x32_bf16 v[94:97], v[164:167], v[228:231], v[94:97]
	v_mfma_f32_16x16x32_bf16 v[90:93], v[172:175], v[228:231], v[90:93]
	v_mfma_f32_16x16x32_bf16 v[78:81], v[164:167], v[236:239], v[78:81]
	v_mfma_f32_16x16x32_bf16 v[74:77], v[172:175], v[236:239], v[74:77]
	s_setprio 0
	s_setprio 1
	v_mfma_f32_16x16x32_bf16 v[118:121], v[176:179], v[208:211], v[118:121]
	v_mfma_f32_16x16x32_bf16 v[114:117], v[184:187], v[208:211], v[114:117]
	v_mfma_f32_16x16x32_bf16 v[102:105], v[176:179], v[216:219], v[102:105]
	v_mfma_f32_16x16x32_bf16 v[98:101], v[184:187], v[216:219], v[98:101]
	v_mfma_f32_16x16x32_bf16 v[86:89], v[176:179], v[224:227], v[86:89]
	v_mfma_f32_16x16x32_bf16 v[82:85], v[184:187], v[224:227], v[82:85]
	v_mfma_f32_16x16x32_bf16 v[70:73], v[176:179], v[232:235], v[70:73]
	v_mfma_f32_16x16x32_bf16 v[66:69], v[184:187], v[232:235], v[66:69]
	s_setprio 0
	s_setprio 1
	v_mfma_f32_16x16x32_bf16 v[118:121], v[180:183], v[212:215], v[118:121]
	v_mfma_f32_16x16x32_bf16 v[114:117], v[204:207], v[212:215], v[114:117]
	v_mfma_f32_16x16x32_bf16 v[102:105], v[180:183], v[220:223], v[102:105]
	v_mfma_f32_16x16x32_bf16 v[98:101], v[204:207], v[220:223], v[98:101]
	v_mfma_f32_16x16x32_bf16 v[86:89], v[180:183], v[228:231], v[86:89]
	v_mfma_f32_16x16x32_bf16 v[82:85], v[204:207], v[228:231], v[82:85]
	v_mfma_f32_16x16x32_bf16 v[70:73], v[180:183], v[236:239], v[70:73]
	v_mfma_f32_16x16x32_bf16 v[66:69], v[204:207], v[236:239], v[66:69]
	s_setprio 0
	s_barrier
; #define PG8_STAGE(bufoff, gbase, voff) do { _Pragma("unroll") for (int _i = 0; _i < 2; ++_i) \
;         __builtin_amdgcn_global_load_lds((const unsigned*)((const char*)(gbase) + (voff)[_i]), (PG8_LAS unsigned*)(lds + (bufoff) + ldsw + _i * 8192), 16, 0, 0); } while (0)
; #define PG8_LDA(dst, b, h) do { _Pragma("unroll") for (int m = 0; m < 4; ++m) _Pragma("unroll") for (int k = 0; k < 2; ++k) dst[m][k] = *(const PG8_LAS bf16x8*)(lds + PG8_SA(b, h) + aoff + m * 2048 + k * 1024); } while (0)
; #define PG8_LDB(dst, b, h) do { _Pragma("unroll") for (int n = 0; n < 2; ++n) _Pragma("unroll") for (int k = 0; k < 2; ++k) dst[n][k] = *(const PG8_LAS bf16x8*)(lds + PG8_SB(b, h) + boff + n * 2048 + k * 1024); } while (0)
; #define PG8_MMA(ai, bj, At, Bt) do { __builtin_amdgcn_s_setprio(1); _Pragma("unroll") for (int m = 0; m < 4; ++m) _Pragma("unroll") for (int n = 0; n < 2; ++n) _Pragma("unroll") for (int k = 0; k < 2; ++k) \
;         acc[ai][bj][m][n] = __builtin_amdgcn_mfma_f32_16x16x32_bf16(Bt[n][k], At[m][k], acc[ai][bj][m][n], 0, 0, 0); __builtin_amdgcn_s_setprio(0); } while (0)
; #define PG8_WAIT_V(n) asm volatile("s_waitcnt vmcnt(" #n ")" ::: "memory")
; #define PG8_WAIT_L(n) asm volatile("s_waitcnt lgkmcnt(" #n ")" ::: "memory")
; #define PG8_BAR __builtin_amdgcn_s_barrier()
; #define PG8_SCHED __builtin_amdgcn_sched_barrier(0)
; template <class Epi, class Sched, bool ALIGN_EPI = false, bool SP2 = false>
; __device__ __forceinline__ void gemm_phase(PG8_LAS unsigned char* lds, const Gemm g, const Sched& S, const Epi& E) {
;     ...
;             PG8_LDB(B0, 0, 0); PG8_LDB(B1, 0, 1); PG8_SCHED; PG8_LDA(At, 0, 0); PG8_STAGE(PG8_SA(1, 1), a1 + hstep, voffA);
;             PG8_WAIT_V(8); PG8_WAIT_L(0); PG8_BAR; PG8_MMA(0, 0, At, B0); PG8_MMA(0, 1, At, B1); PG8_BAR; PG8_SCHED;
;     ...
;             PG8_LDA(At, 1, 1); PG8_STAGE(PG8_SB(1, 0), b3, voffB); PG8_STAGE(PG8_SB(1, 1), b3 + hstep, voffB); PG8_STAGE(PG8_SA(1, 0), a3, voffA);
;             PG8_WAIT_V(8); PG8_WAIT_L(0); PG8_BAR; PG8_MMA(1, 0, At, B0); PG8_MMA(1, 1, At, B1); PG8_BAR; PG8_SCHED;
	s_add_i32 s42, s73, s28
	v_lshl_add_u64 v[240:241], v[240:241], 0, s[68:69]
	s_mov_b32 m0, s42
	ds_read_b128 v[208:211], v162 offset:49152
	ds_read_b128 v[212:215], v162 offset:50176
	ds_read_b128 v[216:219], v162 offset:51200
	ds_read_b128 v[220:223], v162 offset:52224
	ds_read_b128 v[224:227], v162 offset:53248
	ds_read_b128 v[228:231], v162 offset:54272
	ds_read_b128 v[232:235], v162 offset:55296
	ds_read_b128 v[236:239], v162 offset:56320
	global_load_lds_dwordx4 v[240:241], off
	s_add_i32 m0, s42, 0x2000
	s_add_u32 s18, s18, 0x80080
	v_lshl_add_u64 v[240:241], v[242:243], 0, s[68:69]
	s_addc_u32 s19, s19, 0
	s_add_i32 s42, s76, s28
	global_load_lds_dwordx4 v[240:241], off
	v_lshl_add_u64 v[240:241], s[18:19], 0, v[146:147]
	s_mov_b32 m0, s42
	s_nop 0
	global_load_lds_dwordx4 v[240:241], off
	v_lshl_add_u64 v[240:241], s[18:19], 0, v[142:143]
	s_add_i32 m0, s42, 0x2000
	s_nop 0
	global_load_lds_dwordx4 v[240:241], off
	v_lshl_add_u64 v[240:241], v[244:245], 0, s[68:69]
	s_mov_b32 m0, s46
	s_nop 0
	global_load_lds_dwordx4 v[240:241], off
	v_lshl_add_u64 v[240:241], v[246:247], 0, s[68:69]
	s_mov_b32 m0, s47
	s_nop 0
	global_load_lds_dwordx4 v[240:241], off
	s_nop 0
	s_waitcnt vmcnt(8)
	s_waitcnt lgkmcnt(0)
	s_setprio 1
	s_barrier
	v_mfma_f32_16x16x32_bf16 v[62:65], v[156:159], v[208:211], v[62:65]
	v_mfma_f32_16x16x32_bf16 v[58:61], v[168:171], v[208:211], v[58:61]
	v_mfma_f32_16x16x32_bf16 v[46:49], v[156:159], v[216:219], v[46:49]
	v_mfma_f32_16x16x32_bf16 v[42:45], v[168:171], v[216:219], v[42:45]
	v_mfma_f32_16x16x32_bf16 v[30:33], v[156:159], v[224:227], v[30:33]
	v_mfma_f32_16x16x32_bf16 v[26:29], v[168:171], v[224:227], v[26:29]
	v_mfma_f32_16x16x32_bf16 v[14:17], v[156:159], v[232:235], v[14:17]
	v_mfma_f32_16x16x32_bf16 v[10:13], v[168:171], v[232:235], v[10:13]
	v_mfma_f32_16x16x32_bf16 v[62:65], v[164:167], v[212:215], v[62:65]
	v_mfma_f32_16x16x32_bf16 v[58:61], v[172:175], v[212:215], v[58:61]
	v_mfma_f32_16x16x32_bf16 v[46:49], v[164:167], v[220:223], v[46:49]
	v_mfma_f32_16x16x32_bf16 v[42:45], v[172:175], v[220:223], v[42:45]
	v_mfma_f32_16x16x32_bf16 v[30:33], v[164:167], v[228:231], v[30:33]
	v_mfma_f32_16x16x32_bf16 v[26:29], v[172:175], v[228:231], v[26:29]
	v_mfma_f32_16x16x32_bf16 v[14:17], v[164:167], v[236:239], v[14:17]
	v_mfma_f32_16x16x32_bf16 v[10:13], v[172:175], v[236:239], v[10:13]
	v_mfma_f32_16x16x32_bf16 v[54:57], v[176:179], v[208:211], v[54:57]
	v_mfma_f32_16x16x32_bf16 v[50:53], v[184:187], v[208:211], v[50:53]
	v_mfma_f32_16x16x32_bf16 v[38:41], v[176:179], v[216:219], v[38:41]
	v_mfma_f32_16x16x32_bf16 v[34:37], v[184:187], v[216:219], v[34:37]
	v_mfma_f32_16x16x32_bf16 v[22:25], v[176:179], v[224:227], v[22:25]
	v_mfma_f32_16x16x32_bf16 v[18:21], v[184:187], v[224:227], v[18:21]
	v_mfma_f32_16x16x32_bf16 v[6:9], v[176:179], v[232:235], v[6:9]
	v_mfma_f32_16x16x32_bf16 v[2:5], v[184:187], v[232:235], v[2:5]
	v_mfma_f32_16x16x32_bf16 v[54:57], v[180:183], v[212:215], v[54:57]
	v_mfma_f32_16x16x32_bf16 v[50:53], v[204:207], v[212:215], v[50:53]
	v_mfma_f32_16x16x32_bf16 v[38:41], v[180:183], v[220:223], v[38:41]
	v_mfma_f32_16x16x32_bf16 v[34:37], v[204:207], v[220:223], v[34:37]
	v_mfma_f32_16x16x32_bf16 v[22:25], v[180:183], v[228:231], v[22:25]
	v_mfma_f32_16x16x32_bf16 v[18:21], v[204:207], v[228:231], v[18:21]
	v_mfma_f32_16x16x32_bf16 v[6:9], v[180:183], v[236:239], v[6:9]
	v_mfma_f32_16x16x32_bf16 v[2:5], v[204:207], v[236:239], v[2:5]
	s_setprio 0
	s_barrier
	s_add_i32 s67, s67, 2
	s_add_u32 s36, s36, 0x100
	s_addc_u32 s37, s37, 0
	s_add_u32 s62, s62, 0x100
	s_addc_u32 s63, s63, 0
	s_cmp_gt_u32 s67, 29
.LBB0_281:
	s_add_u32 s18, s36, 0xfff80080
	s_addc_u32 s19, s37, -1
	s_add_i32 s73, 0, 0x10000
	s_cmp_eq_u32 s67, 28
	s_cselect_b32 s43, s9, s19
	s_cselect_b32 s42, s59, s18
	v_add_u32_e32 v163, s73, v160
	s_cselect_b32 s19, s7, s63
	s_cselect_b32 s18, s60, s62
	s_add_i32 s76, 0, 0x14000
	ds_read_b128 v[156:159], v163
	ds_read_b128 v[164:167], v163 offset:1024
	ds_read_b128 v[168:171], v163 offset:2048
	ds_read_b128 v[172:175], v163 offset:3072
	v_add_u32_e32 v163, s76, v160
	ds_read_b128 v[176:179], v163
	ds_read_b128 v[180:183], v163 offset:1024
	ds_read_b128 v[184:187], v163 offset:2048
	ds_read_b128 v[204:207], v163 offset:3072
	v_lshl_add_u64 v[240:241], s[36:37], 0, v[152:153]
	s_add_i32 m0, s30, 0xc000
	ds_read_b128 v[208:211], v162
	ds_read_b128 v[212:215], v162 offset:1024
	ds_read_b128 v[216:219], v162 offset:2048
	ds_read_b128 v[220:223], v162 offset:3072
	ds_read_b128 v[224:227], v162 offset:4096
	ds_read_b128 v[228:231], v162 offset:5120
	ds_read_b128 v[232:235], v162 offset:6144
	ds_read_b128 v[236:239], v162 offset:7168
	global_load_lds_dwordx4 v[240:241], off
	v_lshl_add_u64 v[240:241], s[36:37], 0, v[154:155]
	s_add_i32 m0, s30, 0xe000
	s_nop 0
	global_load_lds_dwordx4 v[240:241], off
	s_nop 0
	s_nop 0
	s_nop 0
	s_waitcnt vmcnt(8)
	s_waitcnt lgkmcnt(0)
	s_setprio 1
	s_barrier
; #define PG8_STAGE(bufoff, gbase, voff) do { _Pragma("unroll") for (int _i = 0; _i < 2; ++_i) \
;         __builtin_amdgcn_global_load_lds((const unsigned*)((const char*)(gbase) + (voff)[_i]), (PG8_LAS unsigned*)(lds + (bufoff) + ldsw + _i * 8192), 16, 0, 0); } while (0)
; #define PG8_LDA(dst, b, h) do { _Pragma("unroll") for (int m = 0; m < 4; ++m) _Pragma("unroll") for (int k = 0; k < 2; ++k) dst[m][k] = *(const PG8_LAS bf16x8*)(lds + PG8_SA(b, h) + aoff + m * 2048 + k * 1024); } while (0)
; #define PG8_MMA(ai, bj, At, Bt) do { __builtin_amdgcn_s_setprio(1); _Pragma("unroll") for (int m = 0; m < 4; ++m) _Pragma("unroll") for (int n = 0; n < 2; ++n) _Pragma("unroll") for (int k = 0; k < 2; ++k) \
;         acc[ai][bj][m][n] = __builtin_amdgcn_mfma_f32_16x16x32_bf16(Bt[n][k], At[m][k], acc[ai][bj][m][n], 0, 0, 0); __builtin_amdgcn_s_setprio(0); } while (0)
; #define PG8_WAIT_V(n) asm volatile("s_waitcnt vmcnt(" #n ")" ::: "memory")
; #define PG8_WAIT_L(n) asm volatile("s_waitcnt lgkmcnt(" #n ")" ::: "memory")
; #define PG8_BAR __builtin_amdgcn_s_barrier()
; #define PG8_SCHED __builtin_amdgcn_sched_barrier(0)
; template <class Epi, class Sched, bool ALIGN_EPI = false, bool SP2 = false>
; __device__ __forceinline__ void gemm_phase(PG8_LAS unsigned char* lds, const Gemm g, const Sched& S, const Epi& E) {
;     ...
;             PG8_WAIT_V(8); PG8_WAIT_L(0); PG8_BAR; PG8_MMA(0, 0, At, B0); PG8_MMA(0, 1, At, B1); PG8_BAR; PG8_SCHED;
;             PG8_LDA(At, 0, 1); PG8_STAGE(PG8_SB(0, 0), b2, voffB); PG8_STAGE(PG8_SB(0, 1), b2 + hstep, voffB); PG8_STAGE(PG8_SA(0, 0), a2, voffA);
;             PG8_WAIT_V(8); PG8_WAIT_L(0); PG8_BAR; PG8_MMA(1, 0, At, B0); PG8_MMA(1, 1, At, B1); PG8_BAR; PG8_SCHED;
	v_mfma_f32_16x16x32_bf16 v[126:129], v[156:159], v[208:211], v[126:129]
	v_mfma_f32_16x16x32_bf16 v[122:125], v[168:171], v[208:211], v[122:125]
	v_mfma_f32_16x16x32_bf16 v[110:113], v[156:159], v[216:219], v[110:113]
	v_mfma_f32_16x16x32_bf16 v[106:109], v[168:171], v[216:219], v[106:109]
	v_mfma_f32_16x16x32_bf16 v[94:97], v[156:159], v[224:227], v[94:97]
	v_mfma_f32_16x16x32_bf16 v[90:93], v[168:171], v[224:227], v[90:93]
	v_mfma_f32_16x16x32_bf16 v[78:81], v[156:159], v[232:235], v[78:81]
	v_mfma_f32_16x16x32_bf16 v[74:77], v[168:171], v[232:235], v[74:77]
	s_setprio 0
	s_setprio 1
	v_mfma_f32_16x16x32_bf16 v[126:129], v[164:167], v[212:215], v[126:129]
	v_mfma_f32_16x16x32_bf16 v[122:125], v[172:175], v[212:215], v[122:125]
	v_mfma_f32_16x16x32_bf16 v[110:113], v[164:167], v[220:223], v[110:113]
	v_mfma_f32_16x16x32_bf16 v[106:109], v[172:175], v[220:223], v[106:109]
	v_mfma_f32_16x16x32_bf16 v[94:97], v[164:167], v[228:231], v[94:97]
	v_mfma_f32_16x16x32_bf16 v[90:93], v[172:175], v[228:231], v[90:93]
	v_mfma_f32_16x16x32_bf16 v[78:81], v[164:167], v[236:239], v[78:81]
	v_mfma_f32_16x16x32_bf16 v[74:77], v[172:175], v[236:239], v[74:77]
	s_setprio 0
	s_setprio 1
	v_mfma_f32_16x16x32_bf16 v[118:121], v[176:179], v[208:211], v[118:121]
	v_mfma_f32_16x16x32_bf16 v[114:117], v[184:187], v[208:211], v[114:117]
	v_mfma_f32_16x16x32_bf16 v[102:105], v[176:179], v[216:219], v[102:105]
	v_mfma_f32_16x16x32_bf16 v[98:101], v[184:187], v[216:219], v[98:101]
	v_mfma_f32_16x16x32_bf16 v[86:89], v[176:179], v[224:227], v[86:89]
	v_mfma_f32_16x16x32_bf16 v[82:85], v[184:187], v[224:227], v[82:85]
	v_mfma_f32_16x16x32_bf16 v[70:73], v[176:179], v[232:235], v[70:73]
	v_mfma_f32_16x16x32_bf16 v[66:69], v[184:187], v[232:235], v[66:69]
	s_setprio 0
	s_setprio 1
	v_mfma_f32_16x16x32_bf16 v[118:121], v[180:183], v[212:215], v[118:121]
	v_mfma_f32_16x16x32_bf16 v[114:117], v[204:207], v[212:215], v[114:117]
	v_mfma_f32_16x16x32_bf16 v[102:105], v[180:183], v[220:223], v[102:105]
	v_mfma_f32_16x16x32_bf16 v[98:101], v[204:207], v[220:223], v[98:101]
	v_mfma_f32_16x16x32_bf16 v[86:89], v[180:183], v[228:231], v[86:89]
	v_mfma_f32_16x16x32_bf16 v[82:85], v[204:207], v[228:231], v[82:85]
	v_mfma_f32_16x16x32_bf16 v[70:73], v[180:183], v[236:239], v[70:73]
	v_mfma_f32_16x16x32_bf16 v[66:69], v[204:207], v[236:239], v[66:69]
	s_setprio 0
	s_barrier
	s_add_i32 s73, s73, s28
	v_lshl_add_u64 v[240:241], s[18:19], 0, v[146:147]
	s_mov_b32 m0, s73
	ds_read_b128 v[208:211], v162 offset:16384
	ds_read_b128 v[212:215], v162 offset:17408
	ds_read_b128 v[216:219], v162 offset:18432
	ds_read_b128 v[220:223], v162 offset:19456
	ds_read_b128 v[224:227], v162 offset:20480
	ds_read_b128 v[228:231], v162 offset:21504
	ds_read_b128 v[232:235], v162 offset:22528
	ds_read_b128 v[236:239], v162 offset:23552
	global_load_lds_dwordx4 v[240:241], off
	s_add_i32 m0, s73, 0x2000
	s_add_u32 s78, s18, 0x80000
	v_lshl_add_u64 v[242:243], s[18:19], 0, v[142:143]
	s_addc_u32 s79, s19, 0
	s_add_i32 s73, s76, s28
	global_load_lds_dwordx4 v[242:243], off
	v_lshl_add_u64 v[244:245], s[78:79], 0, v[146:147]
	s_mov_b32 m0, s73
	v_lshl_add_u64 v[246:247], s[42:43], 0, v[144:145]
	global_load_lds_dwordx4 v[244:245], off
	v_lshl_add_u64 v[244:245], s[78:79], 0, v[142:143]
	s_add_i32 m0, s73, 0x2000
	s_nop 0
	global_load_lds_dwordx4 v[244:245], off
	v_lshl_add_u64 v[244:245], s[42:43], 0, v[148:149]
	s_mov_b32 m0, s30
	s_nop 0
	global_load_lds_dwordx4 v[244:245], off
	s_mov_b32 m0, s34
	s_nop 0
	global_load_lds_dwordx4 v[246:247], off
	s_waitcnt vmcnt(8)
	s_waitcnt lgkmcnt(0)
	s_setprio 1
	s_barrier
	v_mfma_f32_16x16x32_bf16 v[62:65], v[156:159], v[208:211], v[62:65]
	v_mfma_f32_16x16x32_bf16 v[58:61], v[168:171], v[208:211], v[58:61]
	v_mfma_f32_16x16x32_bf16 v[46:49], v[156:159], v[216:219], v[46:49]
	v_mfma_f32_16x16x32_bf16 v[42:45], v[168:171], v[216:219], v[42:45]
	v_mfma_f32_16x16x32_bf16 v[30:33], v[156:159], v[224:227], v[30:33]
	v_mfma_f32_16x16x32_bf16 v[26:29], v[168:171], v[224:227], v[26:29]
	v_mfma_f32_16x16x32_bf16 v[14:17], v[156:159], v[232:235], v[14:17]
	v_mfma_f32_16x16x32_bf16 v[10:13], v[168:171], v[232:235], v[10:13]
	v_mfma_f32_16x16x32_bf16 v[62:65], v[164:167], v[212:215], v[62:65]
	v_mfma_f32_16x16x32_bf16 v[58:61], v[172:175], v[212:215], v[58:61]
	v_mfma_f32_16x16x32_bf16 v[46:49], v[164:167], v[220:223], v[46:49]
	v_mfma_f32_16x16x32_bf16 v[42:45], v[172:175], v[220:223], v[42:45]
	v_mfma_f32_16x16x32_bf16 v[30:33], v[164:167], v[228:231], v[30:33]
	v_mfma_f32_16x16x32_bf16 v[26:29], v[172:175], v[228:231], v[26:29]
	v_mfma_f32_16x16x32_bf16 v[14:17], v[164:167], v[236:239], v[14:17]
	v_mfma_f32_16x16x32_bf16 v[10:13], v[172:175], v[236:239], v[10:13]
	v_mfma_f32_16x16x32_bf16 v[54:57], v[176:179], v[208:211], v[54:57]
	v_mfma_f32_16x16x32_bf16 v[50:53], v[184:187], v[208:211], v[50:53]
	v_mfma_f32_16x16x32_bf16 v[38:41], v[176:179], v[216:219], v[38:41]
	v_mfma_f32_16x16x32_bf16 v[34:37], v[184:187], v[216:219], v[34:37]
	v_mfma_f32_16x16x32_bf16 v[22:25], v[176:179], v[224:227], v[22:25]
	v_mfma_f32_16x16x32_bf16 v[18:21], v[184:187], v[224:227], v[18:21]
	v_mfma_f32_16x16x32_bf16 v[6:9], v[176:179], v[232:235], v[6:9]
	v_mfma_f32_16x16x32_bf16 v[2:5], v[184:187], v[232:235], v[2:5]
	v_mfma_f32_16x16x32_bf16 v[54:57], v[180:183], v[212:215], v[54:57]
	v_mfma_f32_16x16x32_bf16 v[50:53], v[204:207], v[212:215], v[50:53]
	v_mfma_f32_16x16x32_bf16 v[38:41], v[180:183], v[220:223], v[38:41]
	v_mfma_f32_16x16x32_bf16 v[34:37], v[204:207], v[220:223], v[34:37]
	v_mfma_f32_16x16x32_bf16 v[22:25], v[180:183], v[228:231], v[22:25]
	v_mfma_f32_16x16x32_bf16 v[18:21], v[204:207], v[228:231], v[18:21]
	v_mfma_f32_16x16x32_bf16 v[6:9], v[180:183], v[236:239], v[6:9]
	v_mfma_f32_16x16x32_bf16 v[2:5], v[204:207], v[236:239], v[2:5]
	s_setprio 0
	s_barrier
; #define PG8_STAGE(bufoff, gbase, voff) do { _Pragma("unroll") for (int _i = 0; _i < 2; ++_i) \
;         __builtin_amdgcn_global_load_lds((const unsigned*)((const char*)(gbase) + (voff)[_i]), (PG8_LAS unsigned*)(lds + (bufoff) + ldsw + _i * 8192), 16, 0, 0); } while (0)
; #define PG8_LDA(dst, b, h) do { _Pragma("unroll") for (int m = 0; m < 4; ++m) _Pragma("unroll") for (int k = 0; k < 2; ++k) dst[m][k] = *(const PG8_LAS bf16x8*)(lds + PG8_SA(b, h) + aoff + m * 2048 + k * 1024); } while (0)
; #define PG8_LDB(dst, b, h) do { _Pragma("unroll") for (int n = 0; n < 2; ++n) _Pragma("unroll") for (int k = 0; k < 2; ++k) dst[n][k] = *(const PG8_LAS bf16x8*)(lds + PG8_SB(b, h) + boff + n * 2048 + k * 1024); } while (0)
; #define PG8_MMA(ai, bj, At, Bt) do { __builtin_amdgcn_s_setprio(1); _Pragma("unroll") for (int m = 0; m < 4; ++m) _Pragma("unroll") for (int n = 0; n < 2; ++n) _Pragma("unroll") for (int k = 0; k < 2; ++k) \
;         acc[ai][bj][m][n] = __builtin_amdgcn_mfma_f32_16x16x32_bf16(Bt[n][k], At[m][k], acc[ai][bj][m][n], 0, 0, 0); __builtin_amdgcn_s_setprio(0); } while (0)
; #define PG8_WAIT_V(n) asm volatile("s_waitcnt vmcnt(" #n ")" ::: "memory")
; #define PG8_WAIT_L(n) asm volatile("s_waitcnt lgkmcnt(" #n ")" ::: "memory")
; #define PG8_BAR __builtin_amdgcn_s_barrier()
; #define PG8_SCHED __builtin_amdgcn_sched_barrier(0)
; template <class Epi, class Sched, bool ALIGN_EPI = false, bool SP2 = false>
; __device__ __forceinline__ void gemm_phase(PG8_LAS unsigned char* lds, const Gemm g, const Sched& S, const Epi& E) {
;     ...
;             PG8_LDB(B0, 1, 0); PG8_LDB(B1, 1, 1); PG8_SCHED; PG8_LDA(At, 1, 0); PG8_STAGE(PG8_SA(0, 1), a2 + hstep, voffA);
;             PG8_WAIT_V(8); PG8_WAIT_L(0); PG8_BAR; PG8_MMA(0, 0, At, B0); PG8_MMA(0, 1, At, B1); PG8_BAR; PG8_SCHED;
;             PG8_LDA(At, 1, 1); PG8_STAGE(PG8_SB(1, 0), b3, voffB); PG8_STAGE(PG8_SB(1, 1), b3 + hstep, voffB); PG8_STAGE(PG8_SA(1, 0), a3, voffA);
	s_add_i32 s73, 0, 0x18000
	v_add_u32_e32 v163, s73, v160
	s_add_i32 s76, 0, 0x1c000
	ds_read_b128 v[156:159], v163
	ds_read_b128 v[164:167], v163 offset:1024
	ds_read_b128 v[168:171], v163 offset:2048
	ds_read_b128 v[172:175], v163 offset:3072
	v_add_u32_e32 v163, s76, v160
	ds_read_b128 v[176:179], v163
	ds_read_b128 v[180:183], v163 offset:1024
	ds_read_b128 v[184:187], v163 offset:2048
	ds_read_b128 v[204:207], v163 offset:3072
	s_add_u32 s42, s42, 0x80000
	s_addc_u32 s43, s43, 0
	s_mov_b32 m0, s44
	v_lshl_add_u64 v[248:249], s[42:43], 0, v[148:149]
	ds_read_b128 v[208:211], v162 offset:32768
	ds_read_b128 v[212:215], v162 offset:33792
	ds_read_b128 v[216:219], v162 offset:34816
	ds_read_b128 v[220:223], v162 offset:35840
	ds_read_b128 v[224:227], v162 offset:36864
	ds_read_b128 v[228:231], v162 offset:37888
	ds_read_b128 v[232:235], v162 offset:38912
	ds_read_b128 v[236:239], v162 offset:39936
	global_load_lds_dwordx4 v[248:249], off
	v_lshl_add_u64 v[248:249], s[42:43], 0, v[144:145]
	s_mov_b32 m0, s45
	s_nop 0
	global_load_lds_dwordx4 v[248:249], off
	s_waitcnt vmcnt(8)
	s_waitcnt lgkmcnt(0)
	s_setprio 1
	s_barrier
	v_mfma_f32_16x16x32_bf16 v[126:129], v[156:159], v[208:211], v[126:129]
	v_mfma_f32_16x16x32_bf16 v[122:125], v[168:171], v[208:211], v[122:125]
	v_mfma_f32_16x16x32_bf16 v[110:113], v[156:159], v[216:219], v[110:113]
	v_mfma_f32_16x16x32_bf16 v[106:109], v[168:171], v[216:219], v[106:109]
	v_mfma_f32_16x16x32_bf16 v[94:97], v[156:159], v[224:227], v[94:97]
	v_mfma_f32_16x16x32_bf16 v[90:93], v[168:171], v[224:227], v[90:93]
	v_mfma_f32_16x16x32_bf16 v[78:81], v[156:159], v[232:235], v[78:81]
	v_mfma_f32_16x16x32_bf16 v[74:77], v[168:171], v[232:235], v[74:77]
	s_setprio 0
	s_setprio 1
	v_mfma_f32_16x16x32_bf16 v[126:129], v[164:167], v[212:215], v[126:129]
	v_mfma_f32_16x16x32_bf16 v[122:125], v[172:175], v[212:215], v[122:125]
	v_mfma_f32_16x16x32_bf16 v[110:113], v[164:167], v[220:223], v[110:113]
	v_mfma_f32_16x16x32_bf16 v[106:109], v[172:175], v[220:223], v[106:109]
	v_mfma_f32_16x16x32_bf16 v[94:97], v[164:167], v[228:231], v[94:97]
	v_mfma_f32_16x16x32_bf16 v[90:93], v[172:175], v[228:231], v[90:93]
	v_mfma_f32_16x16x32_bf16 v[78:81], v[164:167], v[236:239], v[78:81]
	v_mfma_f32_16x16x32_bf16 v[74:77], v[172:175], v[236:239], v[74:77]
	s_setprio 0
	s_setprio 1
	v_mfma_f32_16x16x32_bf16 v[118:121], v[176:179], v[208:211], v[118:121]
	v_mfma_f32_16x16x32_bf16 v[114:117], v[184:187], v[208:211], v[114:117]
	v_mfma_f32_16x16x32_bf16 v[102:105], v[176:179], v[216:219], v[102:105]
	v_mfma_f32_16x16x32_bf16 v[98:101], v[184:187], v[216:219], v[98:101]
	v_mfma_f32_16x16x32_bf16 v[86:89], v[176:179], v[224:227], v[86:89]
	v_mfma_f32_16x16x32_bf16 v[82:85], v[184:187], v[224:227], v[82:85]
	v_mfma_f32_16x16x32_bf16 v[70:73], v[176:179], v[232:235], v[70:73]
	v_mfma_f32_16x16x32_bf16 v[66:69], v[184:187], v[232:235], v[66:69]
	s_setprio 0
	s_setprio 1
	v_mfma_f32_16x16x32_bf16 v[118:121], v[180:183], v[212:215], v[118:121]
	v_mfma_f32_16x16x32_bf16 v[114:117], v[204:207], v[212:215], v[114:117]
	v_mfma_f32_16x16x32_bf16 v[102:105], v[180:183], v[220:223], v[102:105]
	v_mfma_f32_16x16x32_bf16 v[98:101], v[204:207], v[220:223], v[98:101]
	v_mfma_f32_16x16x32_bf16 v[86:89], v[180:183], v[228:231], v[86:89]
	v_mfma_f32_16x16x32_bf16 v[82:85], v[204:207], v[228:231], v[82:85]
	v_mfma_f32_16x16x32_bf16 v[70:73], v[180:183], v[236:239], v[70:73]
	v_mfma_f32_16x16x32_bf16 v[66:69], v[204:207], v[236:239], v[66:69]
	s_setprio 0
	s_barrier
; #define PG8_STAGE(bufoff, gbase, voff) do { _Pragma("unroll") for (int _i = 0; _i < 2; ++_i) \
;         __builtin_amdgcn_global_load_lds((const unsigned*)((const char*)(gbase) + (voff)[_i]), (PG8_LAS unsigned*)(lds + (bufoff) + ldsw + _i * 8192), 16, 0, 0); } while (0)
; #define PG8_LDA(dst, b, h) do { _Pragma("unroll") for (int m = 0; m < 4; ++m) _Pragma("unroll") for (int k = 0; k < 2; ++k) dst[m][k] = *(const PG8_LAS bf16x8*)(lds + PG8_SA(b, h) + aoff + m * 2048 + k * 1024); } while (0)
; #define PG8_MMA(ai, bj, At, Bt) do { __builtin_amdgcn_s_setprio(1); _Pragma("unroll") for (int m = 0; m < 4; ++m) _Pragma("unroll") for (int n = 0; n < 2; ++n) _Pragma("unroll") for (int k = 0; k < 2; ++k) \
;         acc[ai][bj][m][n] = __builtin_amdgcn_mfma_f32_16x16x32_bf16(Bt[n][k], At[m][k], acc[ai][bj][m][n], 0, 0, 0); __builtin_amdgcn_s_setprio(0); } while (0)
; #define PG8_WAIT_V(n) asm volatile("s_waitcnt vmcnt(" #n ")" ::: "memory")
; #define PG8_WAIT_L(n) asm volatile("s_waitcnt lgkmcnt(" #n ")" ::: "memory")
; #define PG8_BAR __builtin_amdgcn_s_barrier()
; #define PG8_SCHED __builtin_amdgcn_sched_barrier(0)
;     __device__ __forceinline__ void operator()(const f32x4 (&acc)[2][2][4][2], const Unit& u, int wr, int wc, int fr, int fq) const {
;     ...
;         if (u.pn >= 30) {
; template <class Epi, class Sched, bool ALIGN_EPI = false, bool SP2 = false>
; __device__ __forceinline__ void gemm_phase(PG8_LAS unsigned char* lds, const Gemm g, const Sched& S, const Epi& E) {
;     ...
;             PG8_LDA(At, 1, 1); PG8_STAGE(PG8_SB(1, 0), b3, voffB); PG8_STAGE(PG8_SB(1, 1), b3 + hstep, voffB); PG8_STAGE(PG8_SA(1, 0), a3, voffA);
;             PG8_WAIT_V(8); PG8_WAIT_L(0); PG8_BAR; PG8_MMA(1, 0, At, B0); PG8_MMA(1, 1, At, B1); PG8_BAR; PG8_SCHED;
;     ...
;         if constexpr (ALIGN_EPI) { if (wr == 0) PG8_BAR; }
;         if constexpr (!Epi::AFTER_DRAIN) { E(acc, cur, wr, wc, fr, fq); S.done(cur); }
;         if (!has_next) break;
	s_add_i32 s42, s73, s28
	v_lshl_add_u64 v[240:241], v[240:241], 0, s[68:69]
	s_mov_b32 m0, s42
	ds_read_b128 v[208:211], v162 offset:49152
	ds_read_b128 v[212:215], v162 offset:50176
	ds_read_b128 v[216:219], v162 offset:51200
	ds_read_b128 v[220:223], v162 offset:52224
	ds_read_b128 v[224:227], v162 offset:53248
	ds_read_b128 v[228:231], v162 offset:54272
	ds_read_b128 v[232:235], v162 offset:55296
	ds_read_b128 v[236:239], v162 offset:56320
	global_load_lds_dwordx4 v[240:241], off
	s_add_i32 m0, s42, 0x2000
	s_add_u32 s18, s18, 0x80080
	v_lshl_add_u64 v[240:241], v[242:243], 0, s[68:69]
	s_addc_u32 s19, s19, 0
	s_add_i32 s42, s76, s28
	global_load_lds_dwordx4 v[240:241], off
	v_lshl_add_u64 v[240:241], s[18:19], 0, v[146:147]
	s_mov_b32 m0, s42
	s_nop 0
	global_load_lds_dwordx4 v[240:241], off
	v_lshl_add_u64 v[240:241], s[18:19], 0, v[142:143]
	s_add_i32 m0, s42, 0x2000
	s_nop 0
	global_load_lds_dwordx4 v[240:241], off
	v_lshl_add_u64 v[240:241], v[244:245], 0, s[68:69]
	s_mov_b32 m0, s46
	s_nop 0
	global_load_lds_dwordx4 v[240:241], off
	v_lshl_add_u64 v[240:241], v[246:247], 0, s[68:69]
	s_mov_b32 m0, s47
	s_nop 0
	global_load_lds_dwordx4 v[240:241], off
	s_nop 0
	s_waitcnt vmcnt(8)
	s_waitcnt lgkmcnt(0)
	s_setprio 1
	s_barrier
	v_mfma_f32_16x16x32_bf16 v[62:65], v[156:159], v[208:211], v[62:65]
	v_mfma_f32_16x16x32_bf16 v[58:61], v[168:171], v[208:211], v[58:61]
	v_mfma_f32_16x16x32_bf16 v[46:49], v[156:159], v[216:219], v[46:49]
	v_mfma_f32_16x16x32_bf16 v[42:45], v[168:171], v[216:219], v[42:45]
	v_mfma_f32_16x16x32_bf16 v[30:33], v[156:159], v[224:227], v[30:33]
	v_mfma_f32_16x16x32_bf16 v[26:29], v[168:171], v[224:227], v[26:29]
	v_mfma_f32_16x16x32_bf16 v[14:17], v[156:159], v[232:235], v[14:17]
	v_mfma_f32_16x16x32_bf16 v[10:13], v[168:171], v[232:235], v[10:13]
	v_mfma_f32_16x16x32_bf16 v[62:65], v[164:167], v[212:215], v[62:65]
	v_mfma_f32_16x16x32_bf16 v[58:61], v[172:175], v[212:215], v[58:61]
	v_mfma_f32_16x16x32_bf16 v[46:49], v[164:167], v[220:223], v[46:49]
	v_mfma_f32_16x16x32_bf16 v[42:45], v[172:175], v[220:223], v[42:45]
	v_mfma_f32_16x16x32_bf16 v[30:33], v[164:167], v[228:231], v[30:33]
	v_mfma_f32_16x16x32_bf16 v[26:29], v[172:175], v[228:231], v[26:29]
	v_mfma_f32_16x16x32_bf16 v[14:17], v[164:167], v[236:239], v[14:17]
	v_mfma_f32_16x16x32_bf16 v[10:13], v[172:175], v[236:239], v[10:13]
	v_mfma_f32_16x16x32_bf16 v[54:57], v[176:179], v[208:211], v[54:57]
	v_mfma_f32_16x16x32_bf16 v[50:53], v[184:187], v[208:211], v[50:53]
	v_mfma_f32_16x16x32_bf16 v[38:41], v[176:179], v[216:219], v[38:41]
	v_mfma_f32_16x16x32_bf16 v[34:37], v[184:187], v[216:219], v[34:37]
	v_mfma_f32_16x16x32_bf16 v[22:25], v[176:179], v[224:227], v[22:25]
	v_mfma_f32_16x16x32_bf16 v[18:21], v[184:187], v[224:227], v[18:21]
	v_mfma_f32_16x16x32_bf16 v[6:9], v[176:179], v[232:235], v[6:9]
	v_mfma_f32_16x16x32_bf16 v[2:5], v[184:187], v[232:235], v[2:5]
	v_mfma_f32_16x16x32_bf16 v[54:57], v[180:183], v[212:215], v[54:57]
	v_mfma_f32_16x16x32_bf16 v[50:53], v[204:207], v[212:215], v[50:53]
	v_mfma_f32_16x16x32_bf16 v[38:41], v[180:183], v[220:223], v[38:41]
	v_mfma_f32_16x16x32_bf16 v[34:37], v[204:207], v[220:223], v[34:37]
	v_mfma_f32_16x16x32_bf16 v[22:25], v[180:183], v[228:231], v[22:25]
	v_mfma_f32_16x16x32_bf16 v[18:21], v[204:207], v[228:231], v[18:21]
	v_mfma_f32_16x16x32_bf16 v[6:9], v[180:183], v[236:239], v[6:9]
	v_mfma_f32_16x16x32_bf16 v[2:5], v[204:207], v[236:239], v[2:5]
	s_setprio 0
	s_barrier
	s_add_i32 s67, s67, 2
	s_add_u32 s36, s36, 0x100
	s_addc_u32 s37, s37, 0
	s_add_u32 s62, s62, 0x100
	s_addc_u32 s63, s63, 0
	s_cmp_gt_u32 s67, 29
	s_cbranch_scc0 .LBB0_281
	s_and_b64 vcc, exec, s[4:5]
	s_cbranch_vccnz .LBB0_286
	s_cmp_lt_i32 s57, 30
	s_mov_b64 s[18:19], -1
	s_cbranch_scc1 .LBB0_287
